# lane^16 / lane^32 reduction steps in the P2/P3/P4 epilogues: ds_bpermute (LDS round trip) replaced by v_permlane16/32_swap (bit-identical sums)
# baseline (speedup 1.0000x reference)
; #define LAS __attribute__((address_space(3)))
; #define MFMA16(a, b, c) __builtin_amdgcn_mfma_f32_16x16x32_bf16((a), (b), (c), 0, 0, 0)
; #define ATT_LOAD(KS, VS, c, set) do { const bf16_t* s_ = ((c) < 4) ? (KS) + (size_t)(64 * (c)) * 256 : (VS) + (size_t)(64 * ((c) - 4)) * 256; \
;         _Pragma("unroll") for (int it = 0; it < 4; ++it) stg[set][it] = *(const u32x4*)(s_ + (size_t)(16 * it) * 256); } while (0)
; __device__ __forceinline__ void attn_phase(LAS unsigned char* lds, const bf16_t* PROJ, const bf16_t* KM, const bf16_t* VT, bf16_t* Y, float* SS, int bx, int G, int tid) {
;     ...
;         for (int c = 0; c < 8; ++c) {
;             if (c + 2 < 8) ATT_LOAD(ksrc, vsrc, c + 2, c & 1);
;             else if (has_next) ATT_LOAD(nksrc, nvsrc, c - 6, c & 1);
;             if (c == 4) {
;                 const bf16_t* gp = PJ(PROJ, tok, COL_GC + h * 256 + 8 * fq);
; #pragma unroll
;                 for (int i = 0; i < 16; ++i) ot[i] = (f32x4){0.f, 0.f, 0.f, 0.f};
; #pragma unroll
;                 for (int p = 0; p < 8; ++p) gt[p] = *(const u32x4*)(gp + 512 * p);
;                 if (has_next) { const bf16_t* qp = PJ(PROJ, T0n + wid * 16 + fr, COL_Q + hn * 256 + fq * 8);
; #pragma unroll
;                     for (int ks = 0; ks < 8; ++ks) qf[ks] = *(const bf16x8*)(qp + ks * 512); }
;             }
;             const LAS unsigned char* base = lds + (c & 3) * ATT_BUF;
;             if (c < 4) {
;                 bf16x8 kfb[3][4];
; #pragma unroll
;                 for (int p = 0; p < 2; ++p)
; #pragma unroll
;                     for (int i = 0; i < 4; ++i) kfb[p][i] = *(const LAS bf16x8*)(base + (frd ^ (p << 6)) + i * 16 * ATT_ROWB);
; #pragma unroll
;                 for (int ks = 0; ks < 8; ++ks) {
;                     if (ks + 2 < 8) {
; #pragma unroll
;                         for (int i = 0; i < 4; ++i) kfb[(ks + 2) % 3][i] = *(const LAS bf16x8*)(base + (frd ^ ((ks + 2) << 6)) + i * 16 * ATT_ROWB); }
; #pragma unroll
;                     for (int i = 0; i < 4; ++i) st[4 * c + i] = MFMA16(kfb[ks % 3][i], qf[ks], st[4 * c + i]);
;                 }
;     ...
;             if (c + 1 < 8 || has_next) ATT_WRITE((c + 1) & 1, (c + 1) & 3, (c + 1 >= 4 && c + 1 < 8));
;             __syncthreads();
.LBB0_449:
	v_lshlrev_b32_e32 v178, 1, v254
	v_lshl_add_u64 v[78:79], v[190:191], 0, v[178:179]
	v_add_co_u32_e32 v42, vcc, s71, v78
	v_add_u32_e32 v151, 0, v194
	s_waitcnt lgkmcnt(0)
	v_addc_co_u32_e32 v43, vcc, 0, v79, vcc
	global_load_dwordx4 v[70:73], v[42:43], off
	v_add_co_u32_e32 v42, vcc, s72, v78
	v_add_u32_e32 v150, 0, v198
	s_nop 0
	v_addc_co_u32_e32 v43, vcc, 0, v79, vcc
	global_load_dwordx4 v[74:77], v[42:43], off
	v_add_co_u32_e32 v42, vcc, s73, v78
	v_add_u32_e32 v149, 0, v199
	s_nop 0
	v_addc_co_u32_e32 v43, vcc, 0, v79, vcc
	global_load_dwordx4 v[82:85], v[42:43], off
	v_add_co_u32_e32 v42, vcc, s75, v78
	v_add_u32_e32 v148, 0, v200
	s_nop 0
	v_addc_co_u32_e32 v43, vcc, 0, v79, vcc
	global_load_dwordx4 v[66:69], v[42:43], off
	ds_read_b128 v[42:45], v151
	ds_read_b128 v[54:57], v151 offset:8192
	ds_read_b128 v[58:61], v151 offset:16384
	ds_read_b128 v[62:65], v151 offset:24576
	ds_read_b128 v[86:89], v150
	ds_read_b128 v[90:93], v150 offset:8192
	ds_read_b128 v[94:97], v150 offset:16384
	ds_read_b128 v[98:101], v150 offset:24576
	s_waitcnt lgkmcnt(7)
	v_mfma_f32_16x16x32_bf16 v[42:45], v[42:45], v[30:33], 0
	ds_read_b128 v[102:105], v149
	ds_read_b128 v[106:109], v149 offset:8192
	ds_read_b128 v[110:113], v149 offset:16384
	ds_read_b128 v[114:117], v149 offset:24576
	ds_read_b128 v[118:121], v148
	ds_read_b128 v[122:125], v148 offset:8192
	ds_read_b128 v[126:129], v148 offset:16384
	ds_read_b128 v[134:137], v148 offset:24576
	s_ashr_i32 s5, s4, 31
	s_waitcnt lgkmcnt(14)
	v_mfma_f32_16x16x32_bf16 v[54:57], v[54:57], v[30:33], 0
	s_lshl_b64 s[4:5], s[4:5], 17
	v_lshl_add_u64 v[146:147], v[204:205], 0, s[4:5]
	v_add_u32_e32 v162, s86, v194
	s_waitcnt lgkmcnt(13)
	v_mfma_f32_16x16x32_bf16 v[58:61], v[58:61], v[30:33], 0
	v_add_u32_e32 v165, s86, v198
	v_add_u32_e32 v163, s86, v199
	v_add_u32_e32 v164, s86, v200
	s_waitcnt lgkmcnt(12)
	v_mfma_f32_16x16x32_bf16 v[62:65], v[62:65], v[30:33], 0
	s_add_i32 s91, s91, s3
	s_cmpk_lt_i32 s91, 0x200
	s_cselect_b64 s[18:19], -1, 0
	s_waitcnt lgkmcnt(11)
	v_mfma_f32_16x16x32_bf16 v[42:45], v[86:89], v[2:5], v[42:45]
	s_cmpk_gt_i32 s91, 0x1ff
	s_cselect_b64 s[16:17], -1, 0
	s_and_b32 s92, s82, 0xffffff80
	s_waitcnt lgkmcnt(10)
	v_mfma_f32_16x16x32_bf16 v[54:57], v[90:93], v[2:5], v[54:57]
	s_and_b32 s93, s91, 3
	s_add_i32 s94, s95, s80
	s_lshl_b32 s4, s12, 23
	s_waitcnt lgkmcnt(9)
	v_mfma_f32_16x16x32_bf16 v[58:61], v[94:97], v[2:5], v[58:61]
	s_add_u32 s96, s36, s4
	s_addc_u32 s97, s37, 0
	s_ashr_i32 s4, s94, 4
	s_waitcnt lgkmcnt(8)
	v_mfma_f32_16x16x32_bf16 v[62:65], v[98:101], v[2:5], v[62:65]
	ds_read_b128 v[86:89], v151 offset:256
	ds_read_b128 v[90:93], v151 offset:8448
	ds_read_b128 v[94:97], v151 offset:16640
	ds_read_b128 v[98:101], v151 offset:24832
	s_ashr_i32 s5, s4, 31
	s_lshl_b64 s[4:5], s[4:5], 13
	s_waitcnt lgkmcnt(11)
	v_mfma_f32_16x16x32_bf16 v[42:45], v[102:105], v[6:9], v[42:45]
	s_add_u32 s4, s96, s4
	s_addc_u32 s5, s97, s5
	v_mov_b32_e32 v187, v179
	s_waitcnt lgkmcnt(10)
	v_mfma_f32_16x16x32_bf16 v[54:57], v[106:109], v[6:9], v[54:57]
	v_lshl_add_u64 v[130:131], s[4:5], 0, v[186:187]
	v_add_u32_e32 v187, s87, v194
	v_add_u32_e32 v220, s87, v198
	s_waitcnt lgkmcnt(9)
	v_mfma_f32_16x16x32_bf16 v[58:61], v[110:113], v[6:9], v[58:61]
	v_add_u32_e32 v221, s87, v199
	v_add_u32_e32 v222, s87, v200
	v_add_u32_e32 v219, s87, v201
	s_waitcnt lgkmcnt(8)
	v_mfma_f32_16x16x32_bf16 v[62:65], v[114:117], v[6:9], v[62:65]
	ds_read_b128 v[102:105], v150 offset:256
	ds_read_b128 v[106:109], v150 offset:8448
	ds_read_b128 v[110:113], v150 offset:16640
	ds_read_b128 v[114:117], v150 offset:24832
	v_add_u32_e32 v218, s87, v202
	v_add_u32_e32 v217, s87, v203
	s_waitcnt lgkmcnt(11)
	v_mfma_f32_16x16x32_bf16 v[42:45], v[118:121], v[10:13], v[42:45]
	v_lshl_add_u64 v[132:133], v[130:131], 0, s[14:15]
	s_waitcnt lgkmcnt(10)
	v_mfma_f32_16x16x32_bf16 v[54:57], v[122:125], v[10:13], v[54:57]
	s_waitcnt lgkmcnt(9)
	v_mfma_f32_16x16x32_bf16 v[58:61], v[126:129], v[10:13], v[58:61]
	s_waitcnt lgkmcnt(8)
	v_mfma_f32_16x16x32_bf16 v[62:65], v[134:137], v[10:13], v[62:65]
	ds_read_b128 v[118:121], v149 offset:256
	ds_read_b128 v[122:125], v149 offset:8448
	ds_read_b128 v[126:129], v149 offset:16640
	ds_read_b128 v[134:137], v149 offset:24832
	s_waitcnt lgkmcnt(11)
	v_mfma_f32_16x16x32_bf16 v[42:45], v[86:89], v[14:17], v[42:45]
	s_waitcnt lgkmcnt(10)
	v_mfma_f32_16x16x32_bf16 v[54:57], v[90:93], v[14:17], v[54:57]
	s_waitcnt lgkmcnt(9)
	v_mfma_f32_16x16x32_bf16 v[58:61], v[94:97], v[14:17], v[58:61]
	s_waitcnt lgkmcnt(8)
	v_mfma_f32_16x16x32_bf16 v[62:65], v[98:101], v[14:17], v[62:65]
	ds_read_b128 v[86:89], v148 offset:256
	ds_read_b128 v[90:93], v148 offset:8448
	ds_read_b128 v[94:97], v148 offset:16640
	ds_read_b128 v[98:101], v148 offset:24832
	s_waitcnt vmcnt(15)
	ds_write_b128 v195, v[34:37] offset:32768
	s_waitcnt vmcnt(14)
	ds_write_b128 v195, v[38:41] offset:40960
	s_waitcnt vmcnt(13)
	ds_write_b128 v195, v[46:49] offset:49152
	s_waitcnt vmcnt(12)
	ds_write_b128 v195, v[50:53] offset:57344
	v_add_co_u32_e32 v34, vcc, s76, v78
	s_waitcnt lgkmcnt(0)
	s_nop 0
	v_addc_co_u32_e32 v35, vcc, 0, v79, vcc
	s_barrier
; #define LAS __attribute__((address_space(3)))
; #define MFMA16(a, b, c) __builtin_amdgcn_mfma_f32_16x16x32_bf16((a), (b), (c), 0, 0, 0)
; #define ATT_LOAD(KS, VS, c, set) do { const bf16_t* s_ = ((c) < 4) ? (KS) + (size_t)(64 * (c)) * 256 : (VS) + (size_t)(64 * ((c) - 4)) * 256; \
;         _Pragma("unroll") for (int it = 0; it < 4; ++it) stg[set][it] = *(const u32x4*)(s_ + (size_t)(16 * it) * 256); } while (0)
; __device__ __forceinline__ void attn_phase(LAS unsigned char* lds, const bf16_t* PROJ, const bf16_t* KM, const bf16_t* VT, bf16_t* Y, float* SS, int bx, int G, int tid) {
;     ...
;         for (int c = 0; c < 8; ++c) {
;             if (c + 2 < 8) ATT_LOAD(ksrc, vsrc, c + 2, c & 1);
;             else if (has_next) ATT_LOAD(nksrc, nvsrc, c - 6, c & 1);
;             if (c == 4) {
;                 const bf16_t* gp = PJ(PROJ, tok, COL_GC + h * 256 + 8 * fq);
; #pragma unroll
;                 for (int i = 0; i < 16; ++i) ot[i] = (f32x4){0.f, 0.f, 0.f, 0.f};
; #pragma unroll
;                 for (int p = 0; p < 8; ++p) gt[p] = *(const u32x4*)(gp + 512 * p);
;                 if (has_next) { const bf16_t* qp = PJ(PROJ, T0n + wid * 16 + fr, COL_Q + hn * 256 + fq * 8);
; #pragma unroll
;                     for (int ks = 0; ks < 8; ++ks) qf[ks] = *(const bf16x8*)(qp + ks * 512); }
;             }
;             const LAS unsigned char* base = lds + (c & 3) * ATT_BUF;
;             if (c < 4) {
;                 bf16x8 kfb[3][4];
; #pragma unroll
;                 for (int p = 0; p < 2; ++p)
; #pragma unroll
;                     for (int i = 0; i < 4; ++i) kfb[p][i] = *(const LAS bf16x8*)(base + (frd ^ (p << 6)) + i * 16 * ATT_ROWB);
; #pragma unroll
;                 for (int ks = 0; ks < 8; ++ks) {
;                     if (ks + 2 < 8) {
; #pragma unroll
;                         for (int i = 0; i < 4; ++i) kfb[(ks + 2) % 3][i] = *(const LAS bf16x8*)(base + (frd ^ ((ks + 2) << 6)) + i * 16 * ATT_ROWB); }
; #pragma unroll
;                     for (int i = 0; i < 4; ++i) st[4 * c + i] = MFMA16(kfb[ks % 3][i], qf[ks], st[4 * c + i]);
;                 }
;     ...
;             if (c + 1 < 8 || has_next) ATT_WRITE((c + 1) & 1, (c + 1) & 3, (c + 1 >= 4 && c + 1 < 8));
;             __syncthreads();
	global_load_dwordx4 v[38:41], v[34:35], off
	v_add_co_u32_e32 v34, vcc, s77, v78
	v_mfma_f32_16x16x32_bf16 v[42:45], v[102:105], v[18:21], v[42:45]
	s_nop 0
	v_addc_co_u32_e32 v35, vcc, 0, v79, vcc
	v_add_co_u32_e32 v46, vcc, s78, v78
	v_mfma_f32_16x16x32_bf16 v[54:57], v[106:109], v[18:21], v[54:57]
	s_nop 0
	v_addc_co_u32_e32 v47, vcc, 0, v79, vcc
	v_add_co_u32_e32 v50, vcc, s79, v78
	v_mfma_f32_16x16x32_bf16 v[58:61], v[110:113], v[18:21], v[58:61]
	global_load_dwordx4 v[34:37], v[34:35], off
	v_addc_co_u32_e32 v51, vcc, 0, v79, vcc
	v_mfma_f32_16x16x32_bf16 v[62:65], v[114:117], v[18:21], v[62:65]
	global_load_dwordx4 v[46:49], v[46:47], off
	s_nop 0
	global_load_dwordx4 v[50:53], v[50:51], off
	v_mfma_f32_16x16x32_bf16 v[42:45], v[118:121], v[22:25], v[42:45]
	v_mfma_f32_16x16x32_bf16 v[54:57], v[122:125], v[22:25], v[54:57]
	v_mfma_f32_16x16x32_bf16 v[102:105], v[126:129], v[22:25], v[58:61]
	v_mfma_f32_16x16x32_bf16 v[106:109], v[134:137], v[22:25], v[62:65]
	v_mfma_f32_16x16x32_bf16 v[62:65], v[86:89], v[26:29], v[42:45]
	v_mfma_f32_16x16x32_bf16 v[58:61], v[90:93], v[26:29], v[54:57]
	v_mfma_f32_16x16x32_bf16 v[54:57], v[94:97], v[26:29], v[102:105]
	v_mfma_f32_16x16x32_bf16 v[42:45], v[98:101], v[26:29], v[106:109]
	ds_read_b128 v[78:81], v151 offset:32768
	ds_read_b128 v[86:89], v151 offset:40960
	ds_read_b128 v[90:93], v151 offset:49152
	ds_read_b128 v[94:97], v151 offset:57344
	ds_read_b128 v[98:101], v150 offset:32768
	ds_read_b128 v[102:105], v150 offset:40960
	ds_read_b128 v[106:109], v150 offset:49152
	ds_read_b128 v[110:113], v150 offset:57344
	ds_read_b128 v[114:117], v149 offset:32768
	ds_read_b128 v[118:121], v149 offset:40960
	ds_read_b128 v[122:125], v149 offset:49152
	ds_read_b128 v[126:129], v149 offset:57344
	ds_read_b128 v[134:137], v148 offset:32768
	ds_read_b128 v[138:141], v148 offset:40960
	ds_read_b128 v[142:145], v148 offset:49152
	ds_read_b128 v[152:155], v148 offset:57344
	s_waitcnt lgkmcnt(14)
	v_mfma_f32_16x16x32_bf16 v[78:81], v[78:81], v[30:33], 0
	s_waitcnt lgkmcnt(12)
	v_mfma_f32_16x16x32_bf16 v[94:97], v[94:97], v[30:33], 0
	s_waitcnt lgkmcnt(11)
	v_mfma_f32_16x16x32_bf16 v[78:81], v[98:101], v[2:5], v[78:81]
	v_mfma_f32_16x16x32_bf16 v[86:89], v[86:89], v[30:33], 0
	s_waitcnt lgkmcnt(8)
	v_mfma_f32_16x16x32_bf16 v[94:97], v[110:113], v[2:5], v[94:97]
	s_waitcnt lgkmcnt(7)
	v_mfma_f32_16x16x32_bf16 v[78:81], v[114:117], v[6:9], v[78:81]
	v_mfma_f32_16x16x32_bf16 v[90:93], v[90:93], v[30:33], 0
	v_mfma_f32_16x16x32_bf16 v[86:89], v[102:105], v[2:5], v[86:89]
	s_waitcnt lgkmcnt(4)
	v_mfma_f32_16x16x32_bf16 v[94:97], v[126:129], v[6:9], v[94:97]
	s_waitcnt lgkmcnt(3)
	v_mfma_f32_16x16x32_bf16 v[78:81], v[134:137], v[10:13], v[78:81]
	v_mfma_f32_16x16x32_bf16 v[90:93], v[106:109], v[2:5], v[90:93]
	ds_read_b128 v[98:101], v151 offset:33024
	ds_read_b128 v[102:105], v151 offset:41216
	ds_read_b128 v[106:109], v151 offset:49408
	ds_read_b128 v[110:113], v151 offset:57600
	v_mfma_f32_16x16x32_bf16 v[86:89], v[118:121], v[6:9], v[86:89]
	s_waitcnt lgkmcnt(4)
	v_mfma_f32_16x16x32_bf16 v[94:97], v[152:155], v[10:13], v[94:97]
	s_waitcnt lgkmcnt(3)
	v_mfma_f32_16x16x32_bf16 v[78:81], v[98:101], v[14:17], v[78:81]
	v_mfma_f32_16x16x32_bf16 v[90:93], v[122:125], v[6:9], v[90:93]
	ds_read_b128 v[114:117], v150 offset:33024
	ds_read_b128 v[118:121], v150 offset:41216
	ds_read_b128 v[122:125], v150 offset:49408
	ds_read_b128 v[126:129], v150 offset:57600
	v_mfma_f32_16x16x32_bf16 v[86:89], v[138:141], v[10:13], v[86:89]
	s_waitcnt lgkmcnt(4)
	v_mfma_f32_16x16x32_bf16 v[94:97], v[110:113], v[14:17], v[94:97]
	s_waitcnt lgkmcnt(3)
	v_mfma_f32_16x16x32_bf16 v[78:81], v[114:117], v[18:21], v[78:81]
	v_mfma_f32_16x16x32_bf16 v[90:93], v[142:145], v[10:13], v[90:93]
	ds_read_b128 v[134:137], v149 offset:33024
	ds_read_b128 v[138:141], v149 offset:41216
	ds_read_b128 v[142:145], v149 offset:49408
	ds_read_b128 v[152:155], v149 offset:57600
	v_mfma_f32_16x16x32_bf16 v[86:89], v[102:105], v[14:17], v[86:89]
	s_waitcnt lgkmcnt(4)
	v_mfma_f32_16x16x32_bf16 v[94:97], v[126:129], v[18:21], v[94:97]
	s_waitcnt lgkmcnt(3)
	v_mfma_f32_16x16x32_bf16 v[78:81], v[134:137], v[22:25], v[78:81]
	v_mfma_f32_16x16x32_bf16 v[90:93], v[106:109], v[14:17], v[90:93]
	ds_read_b128 v[98:101], v148 offset:33024
	ds_read_b128 v[102:105], v148 offset:41216
	ds_read_b128 v[106:109], v148 offset:49408
	ds_read_b128 v[110:113], v148 offset:57600
	v_mfma_f32_16x16x32_bf16 v[86:89], v[118:121], v[18:21], v[86:89]
	s_waitcnt lgkmcnt(4)
	v_mfma_f32_16x16x32_bf16 v[118:121], v[152:155], v[22:25], v[94:97]
	s_waitcnt lgkmcnt(3)
	v_mfma_f32_16x16x32_bf16 v[94:97], v[98:101], v[26:29], v[78:81]
	v_add_u32_e32 v98, 0x10000, v195
	s_waitcnt vmcnt(7)
	ds_write_b128 v98, v[70:73]
	v_add_u32_e32 v70, 0x12000, v195
	v_mfma_f32_16x16x32_bf16 v[90:93], v[122:125], v[18:21], v[90:93]
	s_waitcnt vmcnt(6)
	ds_write_b128 v70, v[74:77]
	v_add_u32_e32 v70, 0x14000, v195
	s_waitcnt vmcnt(5)
	ds_write_b128 v70, v[82:85]
	v_add_u32_e32 v70, 0x16000, v195
	s_waitcnt vmcnt(4)
	ds_write_b128 v70, v[66:69]
	v_add_co_u32_e32 v66, vcc, s21, v146
	v_mfma_f32_16x16x32_bf16 v[86:89], v[138:141], v[22:25], v[86:89]
	s_nop 0
	v_addc_co_u32_e32 v67, vcc, 0, v147, vcc
	s_waitcnt lgkmcnt(0)
	v_mfma_f32_16x16x32_bf16 v[114:117], v[142:145], v[22:25], v[90:93]
	s_barrier
; #define LAS __attribute__((address_space(3)))
; #define MFMA16(a, b, c) __builtin_amdgcn_mfma_f32_16x16x32_bf16((a), (b), (c), 0, 0, 0)
; #define ATT_LOAD(KS, VS, c, set) do { const bf16_t* s_ = ((c) < 4) ? (KS) + (size_t)(64 * (c)) * 256 : (VS) + (size_t)(64 * ((c) - 4)) * 256; \
;         _Pragma("unroll") for (int it = 0; it < 4; ++it) stg[set][it] = *(const u32x4*)(s_ + (size_t)(16 * it) * 256); } while (0)
; __device__ __forceinline__ void attn_phase(LAS unsigned char* lds, const bf16_t* PROJ, const bf16_t* KM, const bf16_t* VT, bf16_t* Y, float* SS, int bx, int G, int tid) {
;     ...
;         for (int c = 0; c < 8; ++c) {
;             if (c + 2 < 8) ATT_LOAD(ksrc, vsrc, c + 2, c & 1);
;             else if (has_next) ATT_LOAD(nksrc, nvsrc, c - 6, c & 1);
;             if (c == 4) {
;                 const bf16_t* gp = PJ(PROJ, tok, COL_GC + h * 256 + 8 * fq);
; #pragma unroll
;                 for (int i = 0; i < 16; ++i) ot[i] = (f32x4){0.f, 0.f, 0.f, 0.f};
; #pragma unroll
;                 for (int p = 0; p < 8; ++p) gt[p] = *(const u32x4*)(gp + 512 * p);
;                 if (has_next) { const bf16_t* qp = PJ(PROJ, T0n + wid * 16 + fr, COL_Q + hn * 256 + fq * 8);
; #pragma unroll
;                     for (int ks = 0; ks < 8; ++ks) qf[ks] = *(const bf16x8*)(qp + ks * 512); }
;             }
;             const LAS unsigned char* base = lds + (c & 3) * ATT_BUF;
;             if (c < 4) {
;                 bf16x8 kfb[3][4];
; #pragma unroll
;                 for (int p = 0; p < 2; ++p)
; #pragma unroll
;                     for (int i = 0; i < 4; ++i) kfb[p][i] = *(const LAS bf16x8*)(base + (frd ^ (p << 6)) + i * 16 * ATT_ROWB);
; #pragma unroll
;                 for (int ks = 0; ks < 8; ++ks) {
;                     if (ks + 2 < 8) {
; #pragma unroll
;                         for (int i = 0; i < 4; ++i) kfb[(ks + 2) % 3][i] = *(const LAS bf16x8*)(base + (frd ^ ((ks + 2) << 6)) + i * 16 * ATT_ROWB); }
; #pragma unroll
;                     for (int i = 0; i < 4; ++i) st[4 * c + i] = MFMA16(kfb[ks % 3][i], qf[ks], st[4 * c + i]);
;                 }
;     ...
;             if (c + 1 < 8 || has_next) ATT_WRITE((c + 1) & 1, (c + 1) & 3, (c + 1 >= 4 && c + 1 < 8));
;             __syncthreads();
	global_load_dwordx4 v[82:85], v[146:147], off
	global_load_dwordx4 v[74:77], v[66:67], off
	v_add_co_u32_e32 v66, vcc, s20, v146
	v_mfma_f32_16x16x32_bf16 v[90:93], v[102:105], v[26:29], v[86:89]
	s_nop 0
	v_addc_co_u32_e32 v67, vcc, 0, v147, vcc
	global_load_dwordx4 v[70:73], v[66:67], off
	v_add_co_u32_e32 v66, vcc, s58, v146
	v_mfma_f32_16x16x32_bf16 v[86:89], v[106:109], v[26:29], v[114:117]
	s_nop 0
	v_addc_co_u32_e32 v67, vcc, 0, v147, vcc
	global_load_dwordx4 v[66:69], v[66:67], off
	v_mfma_f32_16x16x32_bf16 v[78:81], v[110:113], v[26:29], v[118:121]
	ds_read_b128 v[98:101], v162
	ds_read_b128 v[102:105], v162 offset:8192
	ds_read_b128 v[106:109], v162 offset:16384
	ds_read_b128 v[110:113], v162 offset:24576
	ds_read_b128 v[118:121], v165
	ds_read_b128 v[122:125], v165 offset:8192
	ds_read_b128 v[126:129], v165 offset:16384
	ds_read_b128 v[134:137], v165 offset:24576
	ds_read_b128 v[138:141], v163
	ds_read_b128 v[142:145], v163 offset:8192
	ds_read_b128 v[152:155], v163 offset:16384
	ds_read_b128 v[114:117], v163 offset:24576
	s_waitcnt lgkmcnt(11)
	v_mfma_f32_16x16x32_bf16 v[156:159], v[98:101], v[30:33], 0
	s_waitcnt lgkmcnt(9)
	v_mfma_f32_16x16x32_bf16 v[170:173], v[106:109], v[30:33], 0
	s_waitcnt lgkmcnt(8)
	v_mfma_f32_16x16x32_bf16 v[174:177], v[110:113], v[30:33], 0
	s_waitcnt lgkmcnt(7)
	v_mfma_f32_16x16x32_bf16 v[156:159], v[118:121], v[2:5], v[156:159]
	s_waitcnt lgkmcnt(5)
	v_mfma_f32_16x16x32_bf16 v[126:129], v[126:129], v[2:5], v[170:173]
	s_waitcnt lgkmcnt(4)
	v_mfma_f32_16x16x32_bf16 v[134:137], v[134:137], v[2:5], v[174:177]
	v_mfma_f32_16x16x32_bf16 v[166:169], v[102:105], v[30:33], 0
	ds_read_b128 v[110:113], v164
	ds_read_b128 v[106:109], v164 offset:8192
	ds_read_b128 v[98:101], v164 offset:16384
	ds_read_b128 v[102:105], v164 offset:24576
	s_waitcnt lgkmcnt(7)
	v_mfma_f32_16x16x32_bf16 v[138:141], v[138:141], v[6:9], v[156:159]
	s_waitcnt lgkmcnt(5)
	v_mfma_f32_16x16x32_bf16 v[126:129], v[152:155], v[6:9], v[126:129]
	s_waitcnt lgkmcnt(4)
	v_mfma_f32_16x16x32_bf16 v[114:117], v[114:117], v[6:9], v[134:137]
	v_mfma_f32_16x16x32_bf16 v[122:125], v[122:125], v[2:5], v[166:169]
	ds_read_b128 v[118:121], v162 offset:256
	s_nop 1
	ds_read_b128 v[168:171], v162 offset:8448
	ds_read_b128 v[172:175], v162 offset:16640
	ds_read_b128 v[190:193], v162 offset:24832
	v_add_u32_e32 v166, s86, v201
	v_add_u32_e32 v167, s86, v202
	s_waitcnt lgkmcnt(7)
	v_mfma_f32_16x16x32_bf16 v[110:113], v[110:113], v[10:13], v[138:141]
	s_waitcnt lgkmcnt(5)
	v_mfma_f32_16x16x32_bf16 v[98:101], v[98:101], v[10:13], v[126:129]
	s_waitcnt lgkmcnt(4)
	v_mfma_f32_16x16x32_bf16 v[102:105], v[102:105], v[10:13], v[114:117]
	v_mfma_f32_16x16x32_bf16 v[122:125], v[142:145], v[6:9], v[122:125]
	ds_read_b128 v[134:137], v166
	ds_read_b128 v[142:145], v166 offset:8192
	ds_read_b128 v[152:155], v166 offset:16384
	ds_read_b128 v[156:159], v166 offset:24576
	s_waitcnt lgkmcnt(7)
	v_mfma_f32_16x16x32_bf16 v[110:113], v[118:121], v[14:17], v[110:113]
	s_waitcnt lgkmcnt(5)
	v_mfma_f32_16x16x32_bf16 v[98:101], v[172:175], v[14:17], v[98:101]
	s_waitcnt lgkmcnt(4)
	v_mfma_f32_16x16x32_bf16 v[102:105], v[190:193], v[14:17], v[102:105]
	v_mfma_f32_16x16x32_bf16 v[106:109], v[106:109], v[10:13], v[122:125]
	ds_read_b128 v[114:117], v167
	s_nop 1
	ds_read_b128 v[122:125], v167 offset:8192
	ds_read_b128 v[126:129], v167 offset:16384
	ds_read_b128 v[138:141], v167 offset:24576
	s_waitcnt lgkmcnt(7)
	v_mfma_f32_16x16x32_bf16 v[110:113], v[134:137], v[18:21], v[110:113]
	s_waitcnt lgkmcnt(5)
	v_mfma_f32_16x16x32_bf16 v[98:101], v[152:155], v[18:21], v[98:101]
	s_waitcnt lgkmcnt(4)
	v_mfma_f32_16x16x32_bf16 v[102:105], v[156:159], v[18:21], v[102:105]
	v_mfma_f32_16x16x32_bf16 v[106:109], v[168:171], v[14:17], v[106:109]
	v_add_u32_e32 v168, s86, v203
	ds_read_b128 v[118:121], v168
	ds_read_b128 v[170:173], v168 offset:8192
	ds_read_b128 v[174:177], v168 offset:16384
	ds_read_b128 v[190:193], v168 offset:24576
	s_waitcnt lgkmcnt(7)
	v_mfma_f32_16x16x32_bf16 v[110:113], v[114:117], v[22:25], v[110:113]
	s_waitcnt lgkmcnt(5)
	v_mfma_f32_16x16x32_bf16 v[98:101], v[126:129], v[22:25], v[98:101]
	s_waitcnt lgkmcnt(4)
	v_mfma_f32_16x16x32_bf16 v[114:117], v[138:141], v[22:25], v[102:105]
	s_waitcnt lgkmcnt(1)
	v_mfma_f32_16x16x32_bf16 v[102:105], v[174:177], v[26:29], v[98:101]
	s_waitcnt lgkmcnt(0)
	v_mfma_f32_16x16x32_bf16 v[98:101], v[190:193], v[26:29], v[114:117]
	s_nop 3
	v_add_u32_e32 v114, 0x18000, v195
	s_waitcnt vmcnt(7)
	ds_write_b128 v114, v[38:41]
	s_waitcnt vmcnt(6)
	ds_write_b128 v189, v[34:37]
	v_add_u32_e32 v34, 0x1c000, v195
	s_waitcnt vmcnt(5)
	ds_write_b128 v34, v[46:49]
	s_waitcnt vmcnt(4)
	ds_write_b128 v206, v[50:53]
	v_add_co_u32_e32 v34, vcc, s59, v146
	v_mfma_f32_16x16x32_bf16 v[106:109], v[142:145], v[18:21], v[106:109]
	s_nop 0
	v_addc_co_u32_e32 v35, vcc, 0, v147, vcc
	v_add_co_u32_e32 v38, vcc, s60, v146
	s_waitcnt lgkmcnt(0)
	s_nop 0
	v_addc_co_u32_e32 v39, vcc, 0, v147, vcc
	s_barrier
; #define LAS __attribute__((address_space(3)))
; #define MFMA16(a, b, c) __builtin_amdgcn_mfma_f32_16x16x32_bf16((a), (b), (c), 0, 0, 0)
; __device__ __forceinline__ void attn_phase(LAS unsigned char* lds, const bf16_t* PROJ, const bf16_t* KM, const bf16_t* VT, bf16_t* Y, float* SS, int bx, int G, int tid) {
;     ...
;             if (c < 4) {
;                 bf16x8 kfb[3][4];
; #pragma unroll
;                 for (int p = 0; p < 2; ++p)
; #pragma unroll
;                     for (int i = 0; i < 4; ++i) kfb[p][i] = *(const LAS bf16x8*)(base + (frd ^ (p << 6)) + i * 16 * ATT_ROWB);
; #pragma unroll
;                 for (int ks = 0; ks < 8; ++ks) {
;                     if (ks + 2 < 8) {
; #pragma unroll
;                         for (int i = 0; i < 4; ++i) kfb[(ks + 2) % 3][i] = *(const LAS bf16x8*)(base + (frd ^ ((ks + 2) << 6)) + i * 16 * ATT_ROWB); }
; #pragma unroll
;                     for (int i = 0; i < 4; ++i) st[4 * c + i] = MFMA16(kfb[ks % 3][i], qf[ks], st[4 * c + i]);
;                 }
;                 if (c == 3) {
;                     float mx = -3.0e38f;
; #pragma unroll
;                     for (int i = 0; i < 16; ++i) mx = fmaxf(fmaxf(mx, fmaxf(st[i][0], st[i][1])), fmaxf(st[i][2], st[i][3]));
;                     mx = fmaxf(mx, __shfl_xor(mx, 16)); mx = fmaxf(mx, __shfl_xor(mx, 32));
	global_load_dwordx4 v[34:37], v[34:35], off
	v_mfma_f32_16x16x32_bf16 v[106:109], v[122:125], v[22:25], v[106:109]
	global_load_dwordx4 v[50:53], v[38:39], off
	v_add_co_u32_e32 v38, vcc, s61, v146
	v_mfma_f32_16x16x32_bf16 v[110:113], v[118:121], v[26:29], v[110:113]
	s_nop 0
	v_addc_co_u32_e32 v39, vcc, 0, v147, vcc
	global_load_dwordx4 v[46:49], v[38:39], off
	v_add_co_u32_e32 v38, vcc, s70, v146
	v_mfma_f32_16x16x32_bf16 v[106:109], v[170:173], v[26:29], v[106:109]
	s_nop 0
	v_addc_co_u32_e32 v39, vcc, 0, v147, vcc
	global_load_dwordx4 v[38:41], v[38:39], off
	ds_read_b128 v[114:117], v187
	ds_read_b128 v[118:121], v187 offset:8192
	ds_read_b128 v[122:125], v187 offset:16384
	ds_read_b128 v[126:129], v187 offset:24576
	s_waitcnt lgkmcnt(3)
	v_mfma_f32_16x16x32_bf16 v[114:117], v[114:117], v[30:33], 0
	ds_read_b128 v[134:137], v220
	ds_read_b128 v[138:141], v220 offset:8192
	ds_read_b128 v[142:145], v220 offset:16384
	ds_read_b128 v[152:155], v220 offset:24576
	ds_read_b128 v[156:159], v221
	ds_read_b128 v[170:173], v221 offset:8192
	ds_read_b128 v[174:177], v221 offset:16384
	ds_read_b128 v[190:193], v221 offset:24576
	ds_read_b128 v[224:227], v222
	ds_read_b128 v[228:231], v222 offset:8192
	ds_read_b128 v[232:235], v222 offset:16384
	ds_read_b128 v[236:239], v222 offset:24576
	s_waitcnt lgkmcnt(12)
	v_mfma_f32_16x16x32_bf16 v[126:129], v[126:129], v[30:33], 0
	s_waitcnt lgkmcnt(11)
	v_mfma_f32_16x16x32_bf16 v[114:117], v[134:137], v[2:5], v[114:117]
	v_mfma_f32_16x16x32_bf16 v[118:121], v[118:121], v[30:33], 0
	s_waitcnt lgkmcnt(8)
	v_mfma_f32_16x16x32_bf16 v[126:129], v[152:155], v[2:5], v[126:129]
	s_waitcnt lgkmcnt(7)
	v_mfma_f32_16x16x32_bf16 v[114:117], v[156:159], v[6:9], v[114:117]
	v_mfma_f32_16x16x32_bf16 v[122:125], v[122:125], v[30:33], 0
	v_mfma_f32_16x16x32_bf16 v[118:121], v[138:141], v[2:5], v[118:121]
	s_waitcnt lgkmcnt(4)
	v_mfma_f32_16x16x32_bf16 v[126:129], v[190:193], v[6:9], v[126:129]
	s_waitcnt lgkmcnt(3)
	v_mfma_f32_16x16x32_bf16 v[114:117], v[224:227], v[10:13], v[114:117]
	v_mfma_f32_16x16x32_bf16 v[122:125], v[142:145], v[2:5], v[122:125]
	ds_read_b128 v[134:137], v187 offset:256
	ds_read_b128 v[138:141], v187 offset:8448
	ds_read_b128 v[142:145], v187 offset:16640
	ds_read_b128 v[152:155], v187 offset:24832
	v_mfma_f32_16x16x32_bf16 v[118:121], v[170:173], v[6:9], v[118:121]
	s_waitcnt lgkmcnt(4)
	v_mfma_f32_16x16x32_bf16 v[126:129], v[236:239], v[10:13], v[126:129]
	s_waitcnt lgkmcnt(3)
	v_mfma_f32_16x16x32_bf16 v[114:117], v[134:137], v[14:17], v[114:117]
	v_mfma_f32_16x16x32_bf16 v[122:125], v[174:177], v[6:9], v[122:125]
	ds_read_b128 v[156:159], v219
	ds_read_b128 v[170:173], v219 offset:8192
	ds_read_b128 v[174:177], v219 offset:16384
	ds_read_b128 v[190:193], v219 offset:24576
	v_mfma_f32_16x16x32_bf16 v[118:121], v[228:231], v[10:13], v[118:121]
	s_waitcnt lgkmcnt(4)
	v_mfma_f32_16x16x32_bf16 v[126:129], v[152:155], v[14:17], v[126:129]
	s_waitcnt lgkmcnt(3)
	v_mfma_f32_16x16x32_bf16 v[114:117], v[156:159], v[18:21], v[114:117]
	v_mfma_f32_16x16x32_bf16 v[122:125], v[232:235], v[10:13], v[122:125]
	ds_read_b128 v[224:227], v218
	ds_read_b128 v[228:231], v218 offset:8192
	ds_read_b128 v[232:235], v218 offset:16384
	ds_read_b128 v[236:239], v218 offset:24576
	v_mfma_f32_16x16x32_bf16 v[118:121], v[138:141], v[14:17], v[118:121]
	s_waitcnt lgkmcnt(4)
	v_mfma_f32_16x16x32_bf16 v[126:129], v[190:193], v[18:21], v[126:129]
	s_waitcnt lgkmcnt(3)
	v_mfma_f32_16x16x32_bf16 v[114:117], v[224:227], v[22:25], v[114:117]
	v_mfma_f32_16x16x32_bf16 v[122:125], v[142:145], v[14:17], v[122:125]
	ds_read_b128 v[134:137], v217
	ds_read_b128 v[138:141], v217 offset:8192
	ds_read_b128 v[142:145], v217 offset:16384
	ds_read_b128 v[152:155], v217 offset:24576
	v_mfma_f32_16x16x32_bf16 v[118:121], v[170:173], v[18:21], v[118:121]
	s_waitcnt lgkmcnt(4)
	v_mfma_f32_16x16x32_bf16 v[170:173], v[236:239], v[22:25], v[126:129]
	s_waitcnt lgkmcnt(3)
	v_mfma_f32_16x16x32_bf16 v[126:129], v[134:137], v[26:29], v[114:117]
	v_max_f32_e32 v134, v63, v63
	v_max_f32_e32 v135, v62, v62
	v_max_f32_e32 v134, v135, v134
	v_max_f32_e32 v135, v65, v65
	v_max_f32_e32 v136, v64, v64
	v_max_f32_e32 v135, v136, v135
	v_max3_f32 v134, v134, s88, v135
	v_max_f32_e32 v135, v59, v59
	v_max_f32_e32 v136, v58, v58
	v_max_f32_e32 v135, v136, v135
	v_max_f32_e32 v136, v61, v61
	v_max_f32_e32 v137, v60, v60
	v_max_f32_e32 v136, v137, v136
	v_max3_f32 v134, v134, v135, v136
	v_max_f32_e32 v135, v55, v55
	v_max_f32_e32 v136, v54, v54
	v_max_f32_e32 v135, v136, v135
	v_max_f32_e32 v136, v57, v57
	v_max_f32_e32 v137, v56, v56
	v_max_f32_e32 v136, v137, v136
	v_max3_f32 v134, v134, v135, v136
	v_max_f32_e32 v135, v43, v43
	v_max_f32_e32 v136, v42, v42
	v_max_f32_e32 v135, v136, v135
	v_max_f32_e32 v136, v45, v45
	v_max_f32_e32 v137, v44, v44
	v_max_f32_e32 v136, v137, v136
	v_max3_f32 v134, v134, v135, v136
	v_max_f32_e32 v135, v95, v95
	v_max_f32_e32 v136, v94, v94
	v_max_f32_e32 v135, v136, v135
	v_max_f32_e32 v136, v97, v97
	v_max_f32_e32 v137, v96, v96
	v_max_f32_e32 v136, v137, v136
	v_max3_f32 v134, v134, v135, v136
	v_max_f32_e32 v135, v91, v91
	v_max_f32_e32 v136, v90, v90
	v_max_f32_e32 v135, v136, v135
	v_max_f32_e32 v136, v93, v93
	v_max_f32_e32 v137, v92, v92
	v_max_f32_e32 v136, v137, v136
	v_max3_f32 v134, v134, v135, v136
	v_max_f32_e32 v135, v87, v87
	v_max_f32_e32 v136, v86, v86
	v_max_f32_e32 v135, v136, v135
	v_max_f32_e32 v136, v89, v89
	v_max_f32_e32 v137, v88, v88
	v_max_f32_e32 v136, v137, v136
	v_max3_f32 v134, v134, v135, v136
	v_max_f32_e32 v135, v79, v79
	v_max_f32_e32 v136, v78, v78
	v_max_f32_e32 v135, v136, v135
	v_max_f32_e32 v136, v81, v81
	v_max_f32_e32 v137, v80, v80
	v_max_f32_e32 v136, v137, v136
	v_max3_f32 v134, v134, v135, v136
	v_max_f32_e32 v135, v111, v111
	v_max_f32_e32 v136, v110, v110
	v_max_f32_e32 v135, v136, v135
	v_max_f32_e32 v136, v113, v113
	v_max_f32_e32 v137, v112, v112
	v_max_f32_e32 v136, v137, v136
	v_max3_f32 v134, v134, v135, v136
	v_max_f32_e32 v135, v107, v107
	v_max_f32_e32 v136, v106, v106
	v_max_f32_e32 v135, v136, v135
	v_max_f32_e32 v136, v109, v109
	v_max_f32_e32 v137, v108, v108
	v_max_f32_e32 v136, v137, v136
	v_mfma_f32_16x16x32_bf16 v[122:125], v[174:177], v[18:21], v[122:125]
	v_max3_f32 v134, v134, v135, v136
	v_max_f32_e32 v135, v103, v103
	v_max_f32_e32 v136, v102, v102
	v_mfma_f32_16x16x32_bf16 v[118:121], v[228:231], v[22:25], v[118:121]
	v_max_f32_e32 v135, v136, v135
	v_max_f32_e32 v136, v105, v105
	v_max_f32_e32 v137, v104, v104
	v_max_f32_e32 v136, v137, v136
	v_max3_f32 v134, v134, v135, v136
	v_max_f32_e32 v135, v99, v99
	v_max_f32_e32 v136, v98, v98
	v_mfma_f32_16x16x32_bf16 v[156:159], v[232:235], v[22:25], v[122:125]
	v_max_f32_e32 v135, v136, v135
	v_max_f32_e32 v136, v101, v101
	v_max_f32_e32 v137, v100, v100
	s_waitcnt lgkmcnt(2)
; #define MFMA16(a, b, c) __builtin_amdgcn_mfma_f32_16x16x32_bf16((a), (b), (c), 0, 0, 0)
; __device__ __forceinline__ void attn_phase(LAS unsigned char* lds, const bf16_t* PROJ, const bf16_t* KM, const bf16_t* VT, bf16_t* Y, float* SS, int bx, int G, int tid) {
;     ...
;                     for (int i = 0; i < 4; ++i) st[4 * c + i] = MFMA16(kfb[ks % 3][i], qf[ks], st[4 * c + i]);
;                 }
;                 if (c == 3) {
;                     float mx = -3.0e38f;
; #pragma unroll
;                     for (int i = 0; i < 16; ++i) mx = fmaxf(fmaxf(mx, fmaxf(st[i][0], st[i][1])), fmaxf(st[i][2], st[i][3]));
;                     mx = fmaxf(mx, __shfl_xor(mx, 16)); mx = fmaxf(mx, __shfl_xor(mx, 32));
;                     float l = 0.f;
; #pragma unroll
;                     for (int i = 0; i < 16; ++i)
; #pragma unroll
;                         for (int e = 0; e < 4; ++e) { const float p = __builtin_amdgcn_exp2f(st[i][e] - mx); st[i][e] = p; l += p; }
	v_mfma_f32_16x16x32_bf16 v[122:125], v[138:141], v[26:29], v[118:121]
	v_max_f32_e32 v136, v137, v136
	v_max3_f32 v134, v134, v135, v136
	v_max_f32_e32 v135, v127, v127
	v_max_f32_e32 v136, v126, v126
	v_max_f32_e32 v135, v136, v135
	v_max_f32_e32 v136, v129, v129
	v_max_f32_e32 v137, v128, v128
	s_waitcnt lgkmcnt(1)
	v_mfma_f32_16x16x32_bf16 v[118:121], v[142:145], v[26:29], v[156:159]
	v_max_f32_e32 v136, v137, v136
	v_max3_f32 v134, v134, v135, v136
	v_max_f32_e32 v135, v123, v123
	v_max_f32_e32 v136, v122, v122
	v_max_f32_e32 v135, v136, v135
	v_max_f32_e32 v136, v125, v125
	v_max_f32_e32 v137, v124, v124
	s_waitcnt lgkmcnt(0)
	v_mfma_f32_16x16x32_bf16 v[114:117], v[152:155], v[26:29], v[170:173]
	v_max_f32_e32 v136, v137, v136
	v_max3_f32 v134, v134, v135, v136
	v_max_f32_e32 v135, v119, v119
	v_max_f32_e32 v136, v118, v118
	v_max_f32_e32 v135, v136, v135
	v_max_f32_e32 v136, v121, v121
	v_max_f32_e32 v137, v120, v120
	v_max_f32_e32 v136, v137, v136
	v_max3_f32 v134, v134, v135, v136
	v_max_f32_e32 v135, v115, v115
	v_max_f32_e32 v136, v114, v114
	v_max_f32_e32 v135, v136, v135
	v_max_f32_e32 v136, v117, v117
	v_max_f32_e32 v137, v116, v116
	v_max_f32_e32 v136, v137, v136
	v_max3_f32 v134, v134, v135, v136
	ds_bpermute_b32 v135, v215, v134
	s_waitcnt lgkmcnt(0)
	v_max_f32_e32 v135, v135, v135
	v_max_f32_e32 v134, v134, v135
	ds_bpermute_b32 v135, v216, v134
	s_waitcnt lgkmcnt(0)
	v_max_f32_e32 v135, v135, v135
	v_max_f32_e32 v134, v134, v135
	v_sub_f32_e32 v62, v62, v134
	v_exp_f32_e32 v62, v62
	v_sub_f32_e32 v63, v63, v134
	v_exp_f32_e32 v63, v63
	v_sub_f32_e32 v64, v64, v134
	v_exp_f32_e32 v64, v64
	v_sub_f32_e32 v65, v65, v134
	v_exp_f32_e32 v65, v65
	v_sub_f32_e32 v58, v58, v134
	v_add_f32_e32 v135, 0, v62
	v_exp_f32_e32 v58, v58
	v_sub_f32_e32 v59, v59, v134
	v_add_f32_e32 v135, v63, v135
	v_exp_f32_e32 v59, v59
	v_sub_f32_e32 v60, v60, v134
	v_add_f32_e32 v135, v64, v135
	v_exp_f32_e32 v60, v60
	v_sub_f32_e32 v61, v61, v134
	v_add_f32_e32 v135, v65, v135
	v_exp_f32_e32 v61, v61
	v_sub_f32_e32 v54, v54, v134
	v_add_f32_e32 v135, v58, v135
	v_exp_f32_e32 v54, v54
	v_sub_f32_e32 v55, v55, v134
	v_add_f32_e32 v135, v59, v135
	v_exp_f32_e32 v55, v55
	v_sub_f32_e32 v56, v56, v134
	v_add_f32_e32 v135, v60, v135
	v_exp_f32_e32 v56, v56
	v_sub_f32_e32 v57, v57, v134
	v_add_f32_e32 v135, v61, v135
	v_exp_f32_e32 v57, v57
	v_sub_f32_e32 v42, v42, v134
	v_add_f32_e32 v135, v54, v135
	v_exp_f32_e32 v42, v42
	v_sub_f32_e32 v43, v43, v134
	v_add_f32_e32 v135, v55, v135
	v_exp_f32_e32 v43, v43
	v_sub_f32_e32 v44, v44, v134
	v_add_f32_e32 v135, v56, v135
	v_exp_f32_e32 v44, v44
	v_sub_f32_e32 v45, v45, v134
	v_add_f32_e32 v135, v57, v135
	v_exp_f32_e32 v45, v45
	v_sub_f32_e32 v94, v94, v134
	v_add_f32_e32 v135, v42, v135
	v_exp_f32_e32 v94, v94
	v_sub_f32_e32 v95, v95, v134
	v_add_f32_e32 v135, v43, v135
	v_exp_f32_e32 v95, v95
	v_sub_f32_e32 v96, v96, v134
	v_add_f32_e32 v135, v44, v135
	v_exp_f32_e32 v96, v96
	v_sub_f32_e32 v97, v97, v134
	v_add_f32_e32 v135, v45, v135
	v_exp_f32_e32 v97, v97
	v_sub_f32_e32 v90, v90, v134
	v_add_f32_e32 v135, v94, v135
	v_exp_f32_e32 v90, v90
	v_sub_f32_e32 v91, v91, v134
	v_add_f32_e32 v135, v95, v135
	v_exp_f32_e32 v91, v91
	v_sub_f32_e32 v92, v92, v134
	v_add_f32_e32 v135, v96, v135
	v_exp_f32_e32 v92, v92
	v_sub_f32_e32 v93, v93, v134
	v_add_f32_e32 v135, v97, v135
	v_exp_f32_e32 v93, v93
	v_sub_f32_e32 v86, v86, v134
	v_add_f32_e32 v135, v90, v135
	v_exp_f32_e32 v86, v86
	v_sub_f32_e32 v87, v87, v134
	v_add_f32_e32 v135, v91, v135
	v_exp_f32_e32 v87, v87
	v_sub_f32_e32 v88, v88, v134
	v_add_f32_e32 v135, v92, v135
	v_exp_f32_e32 v88, v88
	v_sub_f32_e32 v89, v89, v134
	v_add_f32_e32 v135, v93, v135
	v_exp_f32_e32 v89, v89
	v_sub_f32_e32 v78, v78, v134
	v_add_f32_e32 v135, v86, v135
	v_exp_f32_e32 v78, v78
	v_sub_f32_e32 v79, v79, v134
	v_add_f32_e32 v135, v87, v135
	v_exp_f32_e32 v79, v79
	v_sub_f32_e32 v80, v80, v134
	v_add_f32_e32 v135, v88, v135
	v_exp_f32_e32 v80, v80
	v_sub_f32_e32 v81, v81, v134
	v_add_f32_e32 v135, v89, v135
	v_exp_f32_e32 v81, v81
	v_sub_f32_e32 v110, v110, v134
	v_add_f32_e32 v135, v78, v135
	v_exp_f32_e32 v110, v110
	v_sub_f32_e32 v111, v111, v134
	v_add_f32_e32 v135, v79, v135
	v_exp_f32_e32 v111, v111
	v_sub_f32_e32 v112, v112, v134
	v_add_f32_e32 v135, v80, v135
	v_exp_f32_e32 v112, v112
	v_sub_f32_e32 v113, v113, v134
	v_add_f32_e32 v135, v81, v135
	v_exp_f32_e32 v113, v113
	v_sub_f32_e32 v106, v106, v134
	v_add_f32_e32 v135, v110, v135
	v_exp_f32_e32 v106, v106
	v_sub_f32_e32 v107, v107, v134
	v_add_f32_e32 v135, v111, v135
	v_exp_f32_e32 v107, v107
	v_sub_f32_e32 v108, v108, v134
	v_add_f32_e32 v135, v112, v135
	v_exp_f32_e32 v108, v108
	v_sub_f32_e32 v109, v109, v134
	v_add_f32_e32 v135, v113, v135
	v_exp_f32_e32 v109, v109
	v_sub_f32_e32 v102, v102, v134
	v_add_f32_e32 v135, v106, v135
	v_exp_f32_e32 v102, v102
	v_sub_f32_e32 v103, v103, v134
	v_add_f32_e32 v135, v107, v135
	v_exp_f32_e32 v103, v103
	v_sub_f32_e32 v104, v104, v134
	v_add_f32_e32 v135, v108, v135
	v_exp_f32_e32 v104, v104
	v_sub_f32_e32 v105, v105, v134
	v_add_f32_e32 v135, v109, v135
	v_exp_f32_e32 v105, v105
	v_sub_f32_e32 v98, v98, v134
	v_add_f32_e32 v135, v102, v135
	v_exp_f32_e32 v136, v98
	v_add_f32_e32 v135, v103, v135
	v_add_f32_e32 v135, v104, v135
	v_add_f32_e32 v135, v105, v135
	v_sub_f32_e32 v99, v99, v134
	v_add_f32_e32 v98, v136, v135
	v_exp_f32_e32 v135, v99
	v_sub_f32_e32 v99, v100, v134
	v_exp_f32_e32 v137, v99
	v_sub_f32_e32 v99, v101, v134
	v_exp_f32_e32 v101, v99
; __device__ __forceinline__ void attn_phase(LAS unsigned char* lds, const bf16_t* PROJ, const bf16_t* KM, const bf16_t* VT, bf16_t* Y, float* SS, int bx, int G, int tid) {
;     ...
;             if (c + 2 < 8) ATT_LOAD(ksrc, vsrc, c + 2, c & 1);
;             else if (has_next) ATT_LOAD(nksrc, nvsrc, c - 6, c & 1);
;             if (c == 4) {
;                 const bf16_t* gp = PJ(PROJ, tok, COL_GC + h * 256 + 8 * fq);
; #pragma unroll
;                 for (int i = 0; i < 16; ++i) ot[i] = (f32x4){0.f, 0.f, 0.f, 0.f};
; #pragma unroll
;                 for (int p = 0; p < 8; ++p) gt[p] = *(const u32x4*)(gp + 512 * p);
;                 if (has_next) { const bf16_t* qp = PJ(PROJ, T0n + wid * 16 + fr, COL_Q + hn * 256 + fq * 8);
; #pragma unroll
;                     for (int ks = 0; ks < 8; ++ks) qf[ks] = *(const bf16x8*)(qp + ks * 512); }
;     ...
;                     for (int i = 0; i < 16; ++i)
; #pragma unroll
;                         for (int e = 0; e < 4; ++e) { const float p = __builtin_amdgcn_exp2f(st[i][e] - mx); st[i][e] = p; l += p; }
;                     l += __shfl_xor(l, 16); l += __shfl_xor(l, 32); linv = 1.0f / l;
; #pragma unroll
;                     for (int kk = 0; kk < 8; ++kk) { u32x4 w; w.x = cvt_pk_bf16(st[2 * kk][0], st[2 * kk][1]); w.y = cvt_pk_bf16(st[2 * kk][2], st[2 * kk][3]);
;                         w.z = cvt_pk_bf16(st[2 * kk + 1][0], st[2 * kk + 1][1]); w.w = cvt_pk_bf16(st[2 * kk + 1][2], st[2 * kk + 1][3]); pf[kk] = __builtin_bit_cast(bf16x8, w); }
;                 }
;             } else {
;                 bf16x8 vfb[3][4];
; #pragma unroll
;                 for (int p = 0; p < 2; ++p)
; #pragma unroll
;                     for (int i = 0; i < 4; ++i) vfb[p][i] = *(const LAS bf16x8*)(base + (frd ^ (p << 6)) + i * 16 * ATT_ROWB);
; #pragma unroll
;                 for (int kk = 0; kk < 8; ++kk) {
;                     if (kk + 2 < 8) {
; #pragma unroll
;                         for (int i = 0; i < 4; ++i) vfb[(kk + 2) % 3][i] = *(const LAS bf16x8*)(base + (frd ^ ((kk + 2) << 6)) + i * 16 * ATT_ROWB); }
; #pragma unroll
;                     for (int i = 0; i < 4; ++i) ot[4 * (c - 4) + i] = MFMA16(vfb[kk % 3][i], pf[kk], ot[4 * (c - 4) + i]);
;                 }
;             }
;             if (c + 1 < 8 || has_next) ATT_WRITE((c + 1) & 1, (c + 1) & 3, (c + 1 >= 4 && c + 1 < 8));
;             __syncthreads();
	v_sub_f32_e32 v99, v126, v134
	v_exp_f32_e32 v138, v99
	v_sub_f32_e32 v99, v127, v134
	v_add_f32_e32 v98, v135, v98
	v_exp_f32_e32 v139, v99
	v_sub_f32_e32 v99, v128, v134
	v_add_f32_e32 v98, v137, v98
	v_exp_f32_e32 v140, v99
	v_sub_f32_e32 v99, v129, v134
	v_add_f32_e32 v98, v101, v98
	v_exp_f32_e32 v141, v99
	v_sub_f32_e32 v99, v122, v134
	v_add_f32_e32 v98, v138, v98
	v_exp_f32_e32 v142, v99
	v_sub_f32_e32 v99, v123, v134
	v_add_f32_e32 v98, v139, v98
	v_exp_f32_e32 v143, v99
	v_sub_f32_e32 v99, v124, v134
	v_add_f32_e32 v98, v140, v98
	v_exp_f32_e32 v144, v99
	v_sub_f32_e32 v99, v125, v134
	v_add_f32_e32 v98, v141, v98
	v_exp_f32_e32 v145, v99
	v_sub_f32_e32 v99, v118, v134
	v_add_f32_e32 v98, v142, v98
	v_exp_f32_e32 v152, v99
	v_sub_f32_e32 v99, v119, v134
	v_add_f32_e32 v98, v143, v98
	v_exp_f32_e32 v153, v99
	v_sub_f32_e32 v99, v120, v134
	v_add_f32_e32 v98, v144, v98
	v_exp_f32_e32 v154, v99
	v_sub_f32_e32 v99, v121, v134
	v_add_f32_e32 v98, v145, v98
	v_exp_f32_e32 v155, v99
	v_sub_f32_e32 v99, v114, v134
	v_add_f32_e32 v98, v152, v98
	v_exp_f32_e32 v156, v99
	v_sub_f32_e32 v99, v115, v134
	v_add_f32_e32 v98, v153, v98
	v_exp_f32_e32 v157, v99
	v_sub_f32_e32 v99, v116, v134
	v_add_f32_e32 v98, v154, v98
	v_exp_f32_e32 v158, v99
	v_sub_f32_e32 v99, v117, v134
	v_add_f32_e32 v98, v155, v98
	v_exp_f32_e32 v134, v99
	v_add_f32_e32 v98, v156, v98
	v_add_f32_e32 v98, v157, v98
	v_add_f32_e32 v98, v158, v98
	v_add_f32_e32 v98, v134, v98
	v_mov_b32_e32 v99, v98
	s_nop 1
	v_permlane16_swap_b32_e32 v99, v98
	v_cvt_pk_bf16_f32 v126, v62, v63
	v_cvt_pk_bf16_f32 v127, v64, v65
	v_cvt_pk_bf16_f32 v128, v58, v59
	v_cvt_pk_bf16_f32 v129, v60, v61
	v_cvt_pk_bf16_f32 v122, v54, v55
	v_cvt_pk_bf16_f32 v123, v56, v57
	v_cvt_pk_bf16_f32 v124, v42, v43
	v_add_co_u32_e32 v42, vcc, s71, v146
	s_waitcnt lgkmcnt(0)
	v_add_f32_e32 v223, v98, v99
	v_cvt_pk_bf16_f32 v125, v44, v45
	v_cvt_pk_bf16_f32 v118, v94, v95
	v_cvt_pk_bf16_f32 v119, v96, v97
	v_cvt_pk_bf16_f32 v120, v90, v91
	v_cvt_pk_bf16_f32 v121, v92, v93
	v_cvt_pk_bf16_f32 v114, v86, v87
	v_cvt_pk_bf16_f32 v115, v88, v89
	v_cvt_pk_bf16_f32 v116, v78, v79
	v_cvt_pk_bf16_f32 v117, v80, v81
	v_cvt_pk_bf16_f32 v110, v110, v111
	v_cvt_pk_bf16_f32 v111, v112, v113
	v_cvt_pk_bf16_f32 v112, v106, v107
	v_cvt_pk_bf16_f32 v113, v108, v109
	v_cvt_pk_bf16_f32 v98, v102, v103
	v_cvt_pk_bf16_f32 v99, v104, v105
	v_cvt_pk_bf16_f32 v100, v136, v135
	v_cvt_pk_bf16_f32 v101, v137, v101
	v_cvt_pk_bf16_f32 v86, v138, v139
	v_cvt_pk_bf16_f32 v87, v140, v141
	v_cvt_pk_bf16_f32 v88, v142, v143
	v_cvt_pk_bf16_f32 v89, v144, v145
	v_cvt_pk_bf16_f32 v78, v152, v153
	v_add_u32_e32 v142, 0, v196
	v_add_u32_e32 v143, 0, v207
	v_add_u32_e32 v144, 0, v208
	v_add_u32_e32 v145, 0, v210
	v_add_u32_e32 v152, 0, v214
	v_addc_co_u32_e32 v43, vcc, 0, v147, vcc
	v_cvt_pk_bf16_f32 v79, v154, v155
	v_cvt_pk_bf16_f32 v80, v156, v157
	v_cvt_pk_bf16_f32 v81, v158, v134
	s_waitcnt vmcnt(7)
	ds_write_b64 v142, v[82:83]
	ds_write_b64 v143, v[84:85]
	s_waitcnt vmcnt(6)
	ds_write_b64 v144, v[74:75] offset:4096
	ds_write_b64 v145, v[76:77]
	s_waitcnt vmcnt(5)
	ds_write_b64 v142, v[70:71] offset:16384
	ds_write_b64 v143, v[72:73] offset:16384
	s_waitcnt vmcnt(4)
	ds_write_b64 v144, v[66:67] offset:20480
	ds_write_b64 v152, v[68:69]
	s_waitcnt lgkmcnt(0)
	s_barrier
	global_load_dwordx4 v[90:93], v[42:43], off
	v_add_co_u32_e32 v42, vcc, s72, v146
	ds_bpermute_b32 v224, v216, v223
	s_nop 0
	v_addc_co_u32_e32 v43, vcc, 0, v147, vcc
	global_load_dwordx4 v[94:97], v[42:43], off
	v_add_co_u32_e32 v42, vcc, s73, v146
	s_nop 1
	v_addc_co_u32_e32 v43, vcc, 0, v147, vcc
	global_load_dwordx4 v[102:105], v[42:43], off
	v_add_co_u32_e32 v42, vcc, s75, v146
	s_nop 1
	v_addc_co_u32_e32 v43, vcc, 0, v147, vcc
	global_load_dwordx4 v[106:109], v[42:43], off
	v_add_co_u32_e32 v42, vcc, s89, v130
	s_nop 1
	v_addc_co_u32_e32 v43, vcc, 0, v131, vcc
	global_load_dwordx4 v[82:85], v[42:43], off
	global_load_dwordx4 v[74:77], v[132:133], off offset:1024
	global_load_dwordx4 v[70:73], v[132:133], off offset:2048
	global_load_dwordx4 v[66:69], v[132:133], off offset:3072
	v_add_co_u32_e32 v42, vcc, 0xc001000, v130
	s_nop 1
	v_addc_co_u32_e32 v43, vcc, 0, v131, vcc
	global_load_dwordx4 v[62:65], v[42:43], off
	global_load_dwordx4 v[58:61], v[42:43], off offset:1024
	global_load_dwordx4 v[54:57], v[42:43], off offset:2048
	s_nop 0
	global_load_dwordx4 v[42:45], v[42:43], off offset:3072
	s_and_b64 vcc, exec, s[16:17]
	s_cbranch_vccnz .LBB0_451
	s_lshl_b32 s4, s93, 23
	s_add_u32 s96, s36, s4
	s_addc_u32 s97, s37, 0
	s_add_i32 s4, s92, s80
	s_ashr_i32 s4, s4, 4
	s_ashr_i32 s5, s4, 31
	s_lshl_b64 s[4:5], s[4:5], 13
	s_add_u32 s4, s96, s4
	s_addc_u32 s5, s97, s5
	v_mov_b32_e32 v2, v189
	v_mov_b32_e32 v189, v179
	v_lshl_add_u64 v[14:15], s[4:5], 0, v[188:189]
	v_add_co_u32_e32 v12, vcc, 0xa000000, v14
	v_lshl_add_u64 v[10:11], v[14:15], 0, s[10:11]
	s_nop 0
	v_addc_co_u32_e32 v13, vcc, 0, v15, vcc
	v_add_co_u32_e32 v26, vcc, 0xa001000, v14
	v_mov_b32_e32 v189, v2
	s_nop 0
	v_addc_co_u32_e32 v27, vcc, 0, v15, vcc
	global_load_dwordx4 v[2:5], v[10:11], off offset:1024
	global_load_dwordx4 v[6:9], v[10:11], off offset:2048
	global_load_dwordx4 v[30:33], v[12:13], off
	s_nop 0
	global_load_dwordx4 v[10:13], v[10:11], off offset:3072
	s_nop 0
	global_load_dwordx4 v[14:17], v[26:27], off
	global_load_dwordx4 v[18:21], v[26:27], off offset:1024
	global_load_dwordx4 v[22:25], v[26:27], off offset:2048
	s_nop 0
	global_load_dwordx4 v[26:29], v[26:27], off offset:3072

; __host__ __device__ __forceinline__ size_t img_off(int r, int c, int K) { return ((size_t)(r >> 7) * (size_t)(K >> 6) + (size_t)(c >> 6)) * 8192u + (size_t)(lds_byte(r & 127, c & 63) >> 1); }
; __device__ __forceinline__ unsigned cvt_pk_bf16(float lo, float hi) { unsigned r; asm volatile("v_cvt_pk_bf16_f32 %0, %1, %2" : "=v"(r) : "v"(lo), "v"(hi)); return r; }
; __device__ __forceinline__ float bf_lo(unsigned u) { return __uint_as_float(u << 16); }
; __device__ __forceinline__ float bf_hi(unsigned u) { return __uint_as_float(u & 0xffff0000u); }
; __device__ __forceinline__ void attn_phase(LAS unsigned char* lds, const bf16_t* PROJ, const bf16_t* KM, const bf16_t* VT, bf16_t* Y, float* SS, int bx, int G, int tid) {
;     ...
;         float ssq = 0.f;
; #pragma unroll
;         for (int p = 0; p < 8; ++p) {
;             const u32x4 g = gt[p]; const f32x4 oa = ot[2 * p], ob = ot[2 * p + 1];
;             const float v0 = oa[0] * linv * bf_lo(g.x), v1 = oa[1] * linv * bf_hi(g.x), v2 = oa[2] * linv * bf_lo(g.y), v3 = oa[3] * linv * bf_hi(g.y);
;             const float v4 = ob[0] * linv * bf_lo(g.z), v5 = ob[1] * linv * bf_hi(g.z), v6 = ob[2] * linv * bf_lo(g.w), v7 = ob[3] * linv * bf_hi(g.w);
;             ssq += ((v0 * v0 + v1 * v1) + (v2 * v2 + v3 * v3)) + ((v4 * v4 + v5 * v5) + (v6 * v6 + v7 * v7));
;             u32x4 w; w.x = cvt_pk_bf16(v0, v1); w.y = cvt_pk_bf16(v2, v3); w.z = cvt_pk_bf16(v4, v5); w.w = cvt_pk_bf16(v6, v7);
;             *(u32x4*)(Y + pg8::img_off(tok, 2048 + h * 256 + 32 * p + 8 * fq, MIXW)) = w;
;         }
.LBB0_457:
	v_add_f32_e32 v90, v223, v224
	v_div_scale_f32 v91, s[4:5], v90, v90, 1.0
	v_rcp_f32_e32 v92, v91
	v_div_scale_f32 v93, vcc, 1.0, v90, 1.0
	s_ashr_i32 s5, s94, 7
	v_fma_f32 v94, -v91, v92, 1.0
	v_fmac_f32_e32 v92, v94, v92
	v_mul_f32_e32 v94, v93, v92
	v_fma_f32 v95, -v91, v94, v93
	v_fmac_f32_e32 v94, v95, v92
	v_fma_f32 v91, -v91, v94, v93
	v_div_fmas_f32 v91, v91, v92, v94
	v_div_fixup_f32 v91, v91, v90, 1.0
	v_mul_f32_e32 v94, v91, v138
	v_lshlrev_b32_e32 v95, 16, v82
	v_mul_f32_e32 v94, v94, v95
	v_mul_f32_e32 v95, v91, v139
	v_and_b32_e32 v82, 0xffff0000, v82
	v_mul_f32_e32 v82, v95, v82
	v_mul_f32_e32 v95, v91, v140
	v_lshlrev_b32_e32 v96, 16, v83
	s_lshl_b32 s4, s12, 2
	s_mul_i32 s5, s5, 48
	v_mul_f32_e32 v95, v95, v96
	v_mul_f32_e32 v96, v91, v141
	v_and_b32_e32 v83, 0xffff0000, v83
	s_ashr_i32 s18, s5, 31
	v_mul_f32_e32 v83, v96, v83
	v_mul_f32_e32 v96, v91, v134
	v_lshlrev_b32_e32 v97, 16, v84
	s_or_b32 s19, s4, 32
	v_mul_f32_e32 v96, v96, v97
	v_mul_f32_e32 v97, v91, v135
	v_and_b32_e32 v84, 0xffff0000, v84
	s_add_u32 s98, s5, s19
	v_or_b32_e32 v90, s94, v1
	v_mul_f32_e32 v84, v97, v84
	v_mul_f32_e32 v97, v91, v136
	v_lshlrev_b32_e32 v102, 16, v85
	s_addc_u32 s99, s18, 0
	v_lshlrev_b32_e32 v92, 6, v90
	v_lshlrev_b32_e32 v93, 2, v90
	v_mul_f32_e32 v97, v97, v102
	v_mul_f32_e32 v102, v91, v137
	v_and_b32_e32 v85, 0xffff0000, v85
	s_lshl_b64 s[98:99], s[98:99], 14
	v_and_or_b32 v92, v92, s90, v197
	v_and_b32_e32 v93, 32, v93
	v_mul_f32_e32 v85, v102, v85
	v_mul_f32_e32 v102, v82, v82
	v_mul_f32_e32 v103, v83, v83
	s_add_u32 s98, s44, s98
	s_waitcnt lgkmcnt(0)
	s_barrier
	v_fmac_f32_e32 v102, v94, v94
	v_fmac_f32_e32 v103, v95, v95
	v_cvt_pk_bf16_f32 v82, v94, v82
	v_cvt_pk_bf16_f32 v83, v95, v83
	v_bitop3_b32 v92, v92, s81, v93 bitop3:0xde
	s_addc_u32 s99, s45, s99
	v_add_f32_e32 v102, v102, v103
	v_mul_f32_e32 v103, v84, v84
	v_mul_f32_e32 v104, v85, v85
	v_cvt_pk_bf16_f32 v84, v96, v84
	v_cvt_pk_bf16_f32 v85, v97, v85
	global_store_dwordx4 v92, v[82:85], s[98:99]
	v_lshlrev_b32_e32 v93, 16, v77
	v_and_b32_e32 v77, 0xffff0000, v77
	v_mul_f32_e32 v82, v91, v130
	v_lshlrev_b32_e32 v83, 16, v74
	v_mul_f32_e32 v82, v82, v83
	v_mul_f32_e32 v83, v91, v131
	v_and_b32_e32 v74, 0xffff0000, v74
	v_mul_f32_e32 v74, v83, v74
	v_mul_f32_e32 v83, v91, v132
	v_lshlrev_b32_e32 v84, 16, v75
	v_mul_f32_e32 v83, v83, v84
	v_mul_f32_e32 v84, v91, v133
	v_and_b32_e32 v75, 0xffff0000, v75
	v_mul_f32_e32 v75, v84, v75
	v_mul_f32_e32 v84, v91, v142
	v_lshlrev_b32_e32 v85, 16, v76
	v_mul_f32_e32 v84, v84, v85
	v_mul_f32_e32 v85, v91, v143
	v_and_b32_e32 v76, 0xffff0000, v76
	v_mul_f32_e32 v76, v85, v76
	v_mul_f32_e32 v85, v91, v144
	v_mul_f32_e32 v85, v85, v93
	v_mul_f32_e32 v93, v91, v145
	v_mul_f32_e32 v77, v93, v77
	v_mul_f32_e32 v93, v74, v74
	v_mul_f32_e32 v94, v75, v75
	v_fmac_f32_e32 v93, v82, v82
	v_fmac_f32_e32 v94, v83, v83
	v_cvt_pk_bf16_f32 v74, v82, v74
	v_cvt_pk_bf16_f32 v75, v83, v75
	v_or_b32_e32 v82, 0x400, v92
	v_add_f32_e32 v93, v93, v94
	v_mul_f32_e32 v94, v76, v76
	v_mul_f32_e32 v95, v77, v77
	v_cvt_pk_bf16_f32 v76, v84, v76
	v_cvt_pk_bf16_f32 v77, v85, v77
	global_store_dwordx4 v82, v[74:77], s[98:99]
	s_or_b32 s19, s4, 33
	s_add_u32 s98, s5, s19
	v_mul_f32_e32 v74, v91, v158
	v_lshlrev_b32_e32 v75, 16, v70
	v_mul_f32_e32 v74, v74, v75
	v_mul_f32_e32 v75, v91, v159
	v_and_b32_e32 v70, 0xffff0000, v70
	v_mul_f32_e32 v70, v75, v70
	v_mul_f32_e32 v75, v91, v160
	v_lshlrev_b32_e32 v76, 16, v71
	v_mul_f32_e32 v75, v75, v76
	v_mul_f32_e32 v76, v91, v161
	v_and_b32_e32 v71, 0xffff0000, v71
	v_mul_f32_e32 v71, v76, v71
	v_mul_f32_e32 v76, v91, v154
	v_lshlrev_b32_e32 v77, 16, v72
	v_mul_f32_e32 v76, v76, v77
	v_mul_f32_e32 v77, v91, v155
	v_and_b32_e32 v72, 0xffff0000, v72
	v_mul_f32_e32 v72, v77, v72
	v_mul_f32_e32 v77, v91, v156
	v_lshlrev_b32_e32 v83, 16, v73
	s_addc_u32 s99, s18, 0
	v_mul_f32_e32 v77, v77, v83
	v_mul_f32_e32 v83, v91, v157
	v_and_b32_e32 v73, 0xffff0000, v73
	s_lshl_b64 s[98:99], s[98:99], 14
	v_fmac_f32_e32 v94, v84, v84
	v_mul_f32_e32 v73, v83, v73
	v_mul_f32_e32 v83, v70, v70
	v_mul_f32_e32 v84, v71, v71
	s_add_u32 s98, s44, s98
	v_fmac_f32_e32 v83, v74, v74
	v_fmac_f32_e32 v84, v75, v75
	v_cvt_pk_bf16_f32 v70, v74, v70
	v_cvt_pk_bf16_f32 v71, v75, v71
	s_addc_u32 s99, s45, s99
	v_fmac_f32_e32 v95, v85, v85
	v_add_f32_e32 v83, v83, v84
	v_mul_f32_e32 v84, v72, v72
	v_mul_f32_e32 v85, v73, v73
	v_cvt_pk_bf16_f32 v72, v76, v72
	v_cvt_pk_bf16_f32 v73, v77, v73
	global_store_dwordx4 v92, v[70:73], s[98:99]
	v_lshlrev_b32_e32 v74, 16, v69
	v_and_b32_e32 v69, 0xffff0000, v69
	v_mul_f32_e32 v70, v91, v150
	v_lshlrev_b32_e32 v71, 16, v66
	v_mul_f32_e32 v70, v70, v71
	v_mul_f32_e32 v71, v91, v151
	v_and_b32_e32 v66, 0xffff0000, v66
	v_mul_f32_e32 v66, v71, v66
	v_mul_f32_e32 v71, v91, v152
	v_lshlrev_b32_e32 v72, 16, v67
	v_mul_f32_e32 v71, v71, v72
	v_mul_f32_e32 v72, v91, v153
	v_and_b32_e32 v67, 0xffff0000, v67
	v_mul_f32_e32 v67, v72, v67
	v_mul_f32_e32 v72, v91, v146
	v_lshlrev_b32_e32 v73, 16, v68
	v_mul_f32_e32 v72, v72, v73
	v_mul_f32_e32 v73, v91, v147
	v_and_b32_e32 v68, 0xffff0000, v68
	v_mul_f32_e32 v68, v73, v68
	v_mul_f32_e32 v73, v91, v148
	v_mul_f32_e32 v73, v73, v74
	v_mul_f32_e32 v74, v91, v149
	v_mul_f32_e32 v69, v74, v69
	v_mul_f32_e32 v74, v66, v66
	v_mul_f32_e32 v75, v67, v67
	v_fmac_f32_e32 v74, v70, v70
	v_fmac_f32_e32 v75, v71, v71
	v_cvt_pk_bf16_f32 v66, v70, v66
	v_cvt_pk_bf16_f32 v67, v71, v67
	v_fmac_f32_e32 v84, v76, v76
	v_add_f32_e32 v74, v74, v75
	v_mul_f32_e32 v75, v68, v68
	v_mul_f32_e32 v76, v69, v69
	v_cvt_pk_bf16_f32 v68, v72, v68
	v_cvt_pk_bf16_f32 v69, v73, v69
; __host__ __device__ __forceinline__ size_t img_off(int r, int c, int K) { return ((size_t)(r >> 7) * (size_t)(K >> 6) + (size_t)(c >> 6)) * 8192u + (size_t)(lds_byte(r & 127, c & 63) >> 1); }
; __device__ __forceinline__ unsigned cvt_pk_bf16(float lo, float hi) { unsigned r; asm volatile("v_cvt_pk_bf16_f32 %0, %1, %2" : "=v"(r) : "v"(lo), "v"(hi)); return r; }
; __device__ __forceinline__ float bf_lo(unsigned u) { return __uint_as_float(u << 16); }
; __device__ __forceinline__ float bf_hi(unsigned u) { return __uint_as_float(u & 0xffff0000u); }
; __device__ __forceinline__ void attn_phase(LAS unsigned char* lds, const bf16_t* PROJ, const bf16_t* KM, const bf16_t* VT, bf16_t* Y, float* SS, int bx, int G, int tid) {
;     ...
;         for (int p = 0; p < 8; ++p) {
;             const u32x4 g = gt[p]; const f32x4 oa = ot[2 * p], ob = ot[2 * p + 1];
;             const float v0 = oa[0] * linv * bf_lo(g.x), v1 = oa[1] * linv * bf_hi(g.x), v2 = oa[2] * linv * bf_lo(g.y), v3 = oa[3] * linv * bf_hi(g.y);
;             const float v4 = ob[0] * linv * bf_lo(g.z), v5 = ob[1] * linv * bf_hi(g.z), v6 = ob[2] * linv * bf_lo(g.w), v7 = ob[3] * linv * bf_hi(g.w);
;             ssq += ((v0 * v0 + v1 * v1) + (v2 * v2 + v3 * v3)) + ((v4 * v4 + v5 * v5) + (v6 * v6 + v7 * v7));
;             u32x4 w; w.x = cvt_pk_bf16(v0, v1); w.y = cvt_pk_bf16(v2, v3); w.z = cvt_pk_bf16(v4, v5); w.w = cvt_pk_bf16(v6, v7);
;             *(u32x4*)(Y + pg8::img_off(tok, 2048 + h * 256 + 32 * p + 8 * fq, MIXW)) = w;
;         }
;         ssq += __shfl_xor(ssq, 16); ssq += __shfl_xor(ssq, 32);
;         if (fq == 0) SS[(size_t)tok * 16 + 12 + h] = ssq;
	global_store_dwordx4 v82, v[66:69], s[98:99]
	s_or_b32 s19, s4, 34
	s_add_u32 s98, s5, s19
	v_mul_f32_e32 v66, v91, v174
	v_lshlrev_b32_e32 v67, 16, v62
	v_mul_f32_e32 v66, v66, v67
	v_mul_f32_e32 v67, v91, v175
	v_and_b32_e32 v62, 0xffff0000, v62
	v_mul_f32_e32 v62, v67, v62
	v_mul_f32_e32 v67, v91, v176
	v_lshlrev_b32_e32 v68, 16, v63
	v_mul_f32_e32 v67, v67, v68
	v_mul_f32_e32 v68, v91, v177
	v_and_b32_e32 v63, 0xffff0000, v63
	v_mul_f32_e32 v63, v68, v63
	v_mul_f32_e32 v68, v91, v170
	v_lshlrev_b32_e32 v69, 16, v64
	v_mul_f32_e32 v68, v68, v69
	v_mul_f32_e32 v69, v91, v171
	v_and_b32_e32 v64, 0xffff0000, v64
	v_mul_f32_e32 v64, v69, v64
	v_mul_f32_e32 v69, v91, v172
	v_lshlrev_b32_e32 v70, 16, v65
	s_addc_u32 s99, s18, 0
	v_mul_f32_e32 v69, v69, v70
	v_mul_f32_e32 v70, v91, v173
	v_and_b32_e32 v65, 0xffff0000, v65
	s_lshl_b64 s[98:99], s[98:99], 14
	v_mul_f32_e32 v65, v70, v65
	v_mul_f32_e32 v70, v62, v62
	v_mul_f32_e32 v71, v63, v63
	s_add_u32 s98, s44, s98
	v_fmac_f32_e32 v70, v66, v66
	v_fmac_f32_e32 v71, v67, v67
	v_cvt_pk_bf16_f32 v62, v66, v62
	v_cvt_pk_bf16_f32 v63, v67, v63
	s_addc_u32 s99, s45, s99
	v_fmac_f32_e32 v75, v72, v72
	v_add_f32_e32 v70, v70, v71
	v_mul_f32_e32 v71, v64, v64
	v_mul_f32_e32 v72, v65, v65
	v_cvt_pk_bf16_f32 v64, v68, v64
	v_cvt_pk_bf16_f32 v65, v69, v65
	global_store_dwordx4 v92, v[62:65], s[98:99]
	v_lshlrev_b32_e32 v66, 16, v61
	v_and_b32_e32 v61, 0xffff0000, v61
	v_mul_f32_e32 v62, v91, v166
	v_lshlrev_b32_e32 v63, 16, v58
	v_mul_f32_e32 v62, v62, v63
	v_mul_f32_e32 v63, v91, v167
	v_and_b32_e32 v58, 0xffff0000, v58
	v_mul_f32_e32 v58, v63, v58
	v_mul_f32_e32 v63, v91, v168
	v_lshlrev_b32_e32 v64, 16, v59
	v_mul_f32_e32 v63, v63, v64
	v_mul_f32_e32 v64, v91, v169
	v_and_b32_e32 v59, 0xffff0000, v59
	v_mul_f32_e32 v59, v64, v59
	v_mul_f32_e32 v64, v91, v162
	v_lshlrev_b32_e32 v65, 16, v60
	v_mul_f32_e32 v64, v64, v65
	v_mul_f32_e32 v65, v91, v163
	v_and_b32_e32 v60, 0xffff0000, v60
	v_mul_f32_e32 v60, v65, v60
	v_mul_f32_e32 v65, v91, v164
	v_mul_f32_e32 v65, v65, v66
	v_mul_f32_e32 v66, v91, v165
	v_mul_f32_e32 v61, v66, v61
	v_mul_f32_e32 v66, v58, v58
	v_mul_f32_e32 v67, v59, v59
	v_fmac_f32_e32 v66, v62, v62
	v_fmac_f32_e32 v67, v63, v63
	v_cvt_pk_bf16_f32 v58, v62, v58
	v_cvt_pk_bf16_f32 v59, v63, v59
	v_fmac_f32_e32 v71, v68, v68
	v_add_f32_e32 v66, v66, v67
	v_mul_f32_e32 v67, v60, v60
	v_mul_f32_e32 v68, v61, v61
	v_cvt_pk_bf16_f32 v60, v64, v60
	v_cvt_pk_bf16_f32 v61, v65, v61
	global_store_dwordx4 v82, v[58:61], s[98:99]
	v_lshlrev_b32_e32 v62, 16, v57
	v_and_b32_e32 v57, 0xffff0000, v57
	v_mul_f32_e32 v58, v91, v110
	v_lshlrev_b32_e32 v59, 16, v54
	v_mul_f32_e32 v58, v58, v59
	v_mul_f32_e32 v59, v91, v111
	v_and_b32_e32 v54, 0xffff0000, v54
	v_mul_f32_e32 v54, v59, v54
	v_mul_f32_e32 v59, v91, v112
	v_lshlrev_b32_e32 v60, 16, v55
	v_mul_f32_e32 v59, v59, v60
	v_mul_f32_e32 v60, v91, v113
	v_and_b32_e32 v55, 0xffff0000, v55
	v_mul_f32_e32 v55, v60, v55
	v_mul_f32_e32 v60, v91, v98
	v_lshlrev_b32_e32 v61, 16, v56
	v_mul_f32_e32 v60, v60, v61
	v_mul_f32_e32 v61, v91, v99
	v_and_b32_e32 v56, 0xffff0000, v56
	v_mul_f32_e32 v56, v61, v56
	v_mul_f32_e32 v61, v91, v100
	v_mul_f32_e32 v61, v61, v62
	v_mul_f32_e32 v62, v91, v101
	v_mul_f32_e32 v57, v62, v57
	v_mul_f32_e32 v62, v54, v54
	v_mul_f32_e32 v63, v55, v55
	v_fmac_f32_e32 v62, v58, v58
	v_fmac_f32_e32 v63, v59, v59
	v_cvt_pk_bf16_f32 v54, v58, v54
	v_cvt_pk_bf16_f32 v55, v59, v55
	v_mul_f32_e32 v58, v91, v86
	v_lshlrev_b32_e32 v59, 16, v42
	v_add_f32_e32 v62, v62, v63
	v_mul_f32_e32 v63, v56, v56
	v_mul_f32_e32 v58, v58, v59
	v_mul_f32_e32 v59, v91, v87
	v_and_b32_e32 v42, 0xffff0000, v42
	v_fmac_f32_e32 v63, v60, v60
	v_cvt_pk_bf16_f32 v56, v60, v56
	v_mul_f32_e32 v42, v59, v42
	v_mul_f32_e32 v59, v91, v88
	v_lshlrev_b32_e32 v60, 16, v43
	v_fmac_f32_e32 v67, v64, v64
	v_mul_f32_e32 v64, v57, v57
	v_mul_f32_e32 v59, v59, v60
	v_mul_f32_e32 v60, v91, v89
	v_and_b32_e32 v43, 0xffff0000, v43
	v_fmac_f32_e32 v64, v61, v61
	v_cvt_pk_bf16_f32 v57, v61, v57
	v_mul_f32_e32 v60, v60, v43
	v_mul_f32_e32 v43, v91, v78
	v_lshlrev_b32_e32 v61, 16, v44
	v_fmac_f32_e32 v103, v96, v96
	v_fmac_f32_e32 v104, v97, v97
	v_add_f32_e32 v63, v63, v64
	v_mul_f32_e32 v61, v43, v61
	v_mul_f32_e32 v43, v91, v79
	v_and_b32_e32 v44, 0xffff0000, v44
	v_add_f32_e32 v103, v103, v104
	v_add_f32_e32 v94, v94, v95
	v_fmac_f32_e32 v85, v77, v77
	v_add_f32_e32 v62, v62, v63
	v_mul_f32_e32 v44, v43, v44
	v_mul_f32_e32 v43, v91, v80
	v_lshlrev_b32_e32 v63, 16, v45
	v_add_f32_e32 v102, v102, v103
	v_add_f32_e32 v93, v93, v94
	v_add_f32_e32 v84, v84, v85
	v_fmac_f32_e32 v76, v73, v73
	v_mul_f32_e32 v63, v43, v63
	v_mul_f32_e32 v43, v91, v81
	v_and_b32_e32 v45, 0xffff0000, v45
	v_add_f32_e32 v93, v102, v93
	v_add_f32_e32 v83, v83, v84
	v_add_f32_e32 v75, v75, v76
	v_fmac_f32_e32 v72, v69, v69
	v_mul_f32_e32 v45, v43, v45
	v_mul_f32_e32 v43, v42, v42
	v_mul_f32_e32 v64, v60, v60
	v_add_f32_e32 v83, v93, v83
	v_add_f32_e32 v74, v74, v75
	v_add_f32_e32 v71, v71, v72
	v_fmac_f32_e32 v68, v65, v65
	v_fmac_f32_e32 v43, v58, v58
	v_fmac_f32_e32 v64, v59, v59
	v_add_f32_e32 v74, v83, v74
	v_add_f32_e32 v70, v70, v71
	v_add_f32_e32 v67, v67, v68
	v_add_f32_e32 v43, v43, v64
	v_mul_f32_e32 v64, v44, v44
	v_mul_f32_e32 v65, v45, v45
	v_add_f32_e32 v70, v74, v70
	v_add_f32_e32 v66, v66, v67
	v_fmac_f32_e32 v64, v61, v61
	v_fmac_f32_e32 v65, v63, v63
	v_add_f32_e32 v66, v70, v66
	v_add_f32_e32 v64, v64, v65
	v_add_f32_e32 v62, v66, v62
	v_add_f32_e32 v43, v43, v64
	s_or_b32 s4, s4, 35
	v_add_f32_e32 v43, v62, v43
	s_add_u32 s4, s5, s4
	v_mov_b32_e32 v62, v43
	s_nop 1
	v_permlane16_swap_b32_e32 v62, v43
	s_addc_u32 s5, s18, 0
	s_lshl_b64 s[4:5], s[4:5], 14
	s_add_u32 s4, s44, s4
	s_addc_u32 s5, s45, s5
	global_store_dwordx4 v92, v[54:57], s[4:5]
	s_nop 1
	v_cvt_pk_bf16_f32 v54, v58, v42
	s_waitcnt lgkmcnt(0)
	v_add_f32_e32 v42, v43, v62
	v_mov_b32_e32 v43, v42
	s_nop 1
	v_permlane32_swap_b32_e32 v43, v42
	v_cvt_pk_bf16_f32 v55, v59, v60
	v_cvt_pk_bf16_f32 v56, v61, v44
	v_cvt_pk_bf16_f32 v57, v63, v45
	global_store_dwordx4 v82, v[54:57], s[4:5]
	s_and_saveexec_b64 s[4:5], s[0:1]
	s_cbranch_execz .LBB0_448
	v_ashrrev_i32_e32 v91, 31, v90
	s_waitcnt lgkmcnt(0)
	v_add_f32_e32 v44, v42, v43
	v_lshlrev_b64 v[42:43], 6, v[90:91]
	v_lshl_add_u64 v[42:43], s[46:47], 0, v[42:43]
	v_lshl_add_u64 v[42:43], s[12:13], 2, v[42:43]
	global_store_dword v[42:43], v44, off offset:48
	s_branch .LBB0_448

; __device__ __forceinline__ unsigned cvt_pk_bf16(float lo, float hi) { unsigned r; asm volatile("v_cvt_pk_bf16_f32 %0, %1, %2" : "=v"(r) : "v"(lo), "v"(hi)); return r; }
; #define LAS __attribute__((address_space(3)))
; __device__ __forceinline__ float bf_lo(unsigned u) { return __uint_as_float(u << 16); }
; __device__ __forceinline__ float bf_hi(unsigned u) { return __uint_as_float(u & 0xffff0000u); }
; #define MFMA16(a, b, c) __builtin_amdgcn_mfma_f32_16x16x32_bf16((a), (b), (c), 0, 0, 0)
; __device__ __forceinline__ void pool_phase(LAS unsigned char* lds, const bf16_t* PROJ, const bf16_t* PW, const float* pscale, bf16_t* Y, float* SS, int bx, int G) {
;     ...
;             for (int tt = 0; tt < 16; ++tt) { const int t = t_start + tt; const unsigned x = xr[tt + 15]; const float x0 = bf_lo(x), x1 = bf_hi(x);
;                 s0 += x0; s1 += x1; const int pos = pos0 + t; const float rc = __builtin_amdgcn_rcpf((float)((pos + 1 < w) ? (pos + 1) : w));
;                 const float d0 = s0 * rc - x0, d1 = s1 * rc - x1;
;                 *(LAS unsigned*)(lds + PL_DT + t * PL_DROW + cp * 4) = cvt_pk_bf16(d0, d1);
;                 const unsigned xo = (w == 2) ? xr[tt + 14] : (w == 4) ? xr[tt + 12] : (w == 8) ? xr[tt + 8] : xr[tt]; s0 -= bf_lo(xo); s1 -= bf_hi(xo); }
;         }
;         __syncthreads();
;         f32x4 acc[2][4];
; #pragma unroll
;         for (int j = 0; j < 2; ++j)
; #pragma unroll
;             for (int m = 0; m < 4; ++m) acc[j][m] = (f32x4){0.f, 0.f, 0.f, 0.f};
;         { bf16x8 dfb[2][4];
; #pragma unroll
;           for (int m = 0; m < 4; ++m) dfb[0][m] = *(const LAS bf16x8*)(lds + PL_DT + (16 * m + fr) * PL_DROW + (8 * fq) * 2);
; #pragma unroll
;           for (int ks = 0; ks < 8; ++ks) {
;               if (ks + 1 < 8) {
; #pragma unroll
;                   for (int m = 0; m < 4; ++m) dfb[(ks + 1) & 1][m] = *(const LAS bf16x8*)(lds + PL_DT + (16 * m + fr) * PL_DROW + (32 * (ks + 1) + 8 * fq) * 2); }
; #pragma unroll
;               for (int m = 0; m < 4; ++m)
; #pragma unroll
;                   for (int j = 0; j < 2; ++j) acc[j][m] = MFMA16(wf[j][ks], dfb[ks & 1][m], acc[j][m]);
;           } }
.LBB0_619:
	v_add_u32_e32 v104, s72, v174
	v_min_i32_e32 v104, s78, v104
	v_cvt_f32_i32_e32 v104, v104
	v_sub_f32_e32 v102, v102, v139
	v_sub_f32_e32 v105, v106, v138
	v_lshlrev_b32_e32 v106, 16, v103
	v_rcp_iflag_f32_e32 v104, v104
	v_and_b32_e32 v103, 0xffff0000, v103
	v_add_f32_e32 v102, v102, v106
	v_add_f32_e32 v105, v105, v103
	v_fma_f32 v102, v104, v102, -v106
	v_fma_f32 v103, v104, v105, -v103
	v_cvt_pk_bf16_f32 v102, v102, v103
	ds_write_b32 v190, v102 offset:40960
	s_waitcnt lgkmcnt(0)
	s_barrier
	ds_read_b128 v[102:105], v191 offset:40960
	ds_read_b128 v[106:109], v191 offset:41024
	ds_read_b128 v[114:117], v191 offset:49408
	ds_read_b128 v[118:121], v191 offset:49472
	ds_read_b128 v[126:129], v191 offset:57856
	ds_read_b128 v[136:139], v191 offset:57920
	ds_read_b128 v[144:147], v192 offset:40960
	ds_read_b128 v[148:151], v192 offset:41024
	s_waitcnt lgkmcnt(7)
	v_mfma_f32_16x16x32_bf16 v[110:113], v[2:5], v[102:105], 0
	s_waitcnt vmcnt(3)
	v_lshlrev_b32_e32 v181, 16, v98
	v_and_b32_e32 v98, 0xffff0000, v98
	s_ashr_i32 s70, s86, 1
	v_mfma_f32_16x16x32_bf16 v[102:105], v[34:37], v[102:105], 0
	s_mul_hi_i32 s71, s70, 48
	s_mul_i32 s70, s70, 48
	s_add_u32 s70, s70, s80
	s_waitcnt lgkmcnt(5)
	v_mfma_f32_16x16x32_bf16 v[122:125], v[2:5], v[114:117], 0
	s_addc_u32 s71, s71, s81
	s_lshl_b64 s[70:71], s[70:71], 14
	s_add_u32 s70, s44, s70
	v_mfma_f32_16x16x32_bf16 v[114:117], v[34:37], v[114:117], 0
	s_addc_u32 s71, s45, s71
	s_lshr_b32 s72, s88, 3
	s_waitcnt lgkmcnt(3)
	v_mfma_f32_16x16x32_bf16 v[140:143], v[2:5], v[126:129], 0
	v_mfma_f32_16x16x32_bf16 v[126:129], v[34:37], v[126:129], 0
	s_waitcnt lgkmcnt(1)
	v_mfma_f32_16x16x32_bf16 v[152:155], v[2:5], v[144:147], 0
	v_mfma_f32_16x16x32_bf16 v[144:147], v[34:37], v[144:147], 0
	v_mfma_f32_16x16x32_bf16 v[110:113], v[6:9], v[106:109], v[110:113]
	v_mfma_f32_16x16x32_bf16 v[102:105], v[38:41], v[106:109], v[102:105]
	v_mfma_f32_16x16x32_bf16 v[106:109], v[6:9], v[118:121], v[122:125]
	v_mfma_f32_16x16x32_bf16 v[114:117], v[38:41], v[118:121], v[114:117]
	v_mfma_f32_16x16x32_bf16 v[118:121], v[6:9], v[136:139], v[140:143]
	v_mfma_f32_16x16x32_bf16 v[122:125], v[38:41], v[136:139], v[126:129]
	s_waitcnt lgkmcnt(0)
	v_mfma_f32_16x16x32_bf16 v[136:139], v[38:41], v[148:151], v[144:147]
	ds_read_b128 v[140:143], v191 offset:41088
	s_nop 1
	ds_read_b128 v[144:147], v191 offset:41152
	v_mfma_f32_16x16x32_bf16 v[126:129], v[6:9], v[148:151], v[152:155]
	s_waitcnt lgkmcnt(1)
	v_mfma_f32_16x16x32_bf16 v[110:113], v[10:13], v[140:143], v[110:113]
	v_mfma_f32_16x16x32_bf16 v[102:105], v[42:45], v[140:143], v[102:105]
	ds_read_b128 v[140:143], v191 offset:49536
	ds_read_b128 v[148:151], v191 offset:49600
	s_waitcnt lgkmcnt(1)
	v_mfma_f32_16x16x32_bf16 v[106:109], v[10:13], v[140:143], v[106:109]
	v_mfma_f32_16x16x32_bf16 v[114:117], v[42:45], v[140:143], v[114:117]
	ds_read_b128 v[140:143], v191 offset:57984
	ds_read_b128 v[152:155], v191 offset:58048
	s_waitcnt lgkmcnt(1)
	v_mfma_f32_16x16x32_bf16 v[118:121], v[10:13], v[140:143], v[118:121]
	v_mfma_f32_16x16x32_bf16 v[122:125], v[42:45], v[140:143], v[122:125]
	ds_read_b128 v[140:143], v192 offset:41088
	ds_read_b128 v[196:199], v192 offset:41152
	s_waitcnt lgkmcnt(1)
	v_mfma_f32_16x16x32_bf16 v[126:129], v[10:13], v[140:143], v[126:129]
	v_mfma_f32_16x16x32_bf16 v[136:139], v[42:45], v[140:143], v[136:139]
	v_mfma_f32_16x16x32_bf16 v[110:113], v[14:17], v[144:147], v[110:113]
	v_mfma_f32_16x16x32_bf16 v[102:105], v[46:49], v[144:147], v[102:105]
	ds_read_b128 v[140:143], v191 offset:41216
	ds_read_b128 v[144:147], v191 offset:41280
	v_mfma_f32_16x16x32_bf16 v[106:109], v[14:17], v[148:151], v[106:109]
	v_mfma_f32_16x16x32_bf16 v[114:117], v[46:49], v[148:151], v[114:117]
	s_waitcnt lgkmcnt(1)
	v_mfma_f32_16x16x32_bf16 v[110:113], v[18:21], v[140:143], v[110:113]
	v_mfma_f32_16x16x32_bf16 v[140:143], v[50:53], v[140:143], v[102:105]
	s_nop 2
	ds_read_b128 v[102:105], v191 offset:49664
	ds_read_b128 v[148:151], v191 offset:49728
	v_mfma_f32_16x16x32_bf16 v[118:121], v[14:17], v[152:155], v[118:121]
	v_mfma_f32_16x16x32_bf16 v[122:125], v[46:49], v[152:155], v[122:125]
	v_mfma_f32_16x16x32_bf16 v[126:129], v[14:17], v[196:199], v[126:129]
	v_mfma_f32_16x16x32_bf16 v[136:139], v[46:49], v[196:199], v[136:139]
	s_waitcnt lgkmcnt(1)
	v_mfma_f32_16x16x32_bf16 v[152:155], v[18:21], v[102:105], v[106:109]
	v_mfma_f32_16x16x32_bf16 v[114:117], v[50:53], v[102:105], v[114:117]
	ds_read_b128 v[102:105], v191 offset:58112
	ds_read_b128 v[196:199], v191 offset:58176
	global_load_dwordx4 v[106:109], v[134:135], off
	ds_read_b128 v[200:203], v192 offset:41216
	ds_read_b128 v[204:207], v192 offset:41280
	s_waitcnt lgkmcnt(3)
	v_mfma_f32_16x16x32_bf16 v[118:121], v[18:21], v[102:105], v[118:121]
	v_mfma_f32_16x16x32_bf16 v[122:125], v[50:53], v[102:105], v[122:125]
	global_load_dwordx4 v[102:105], v[134:135], off offset:16
	ds_read_b128 v[208:211], v191 offset:41344
	ds_read_b128 v[212:215], v191 offset:41408
	v_mfma_f32_16x16x32_bf16 v[110:113], v[22:25], v[144:147], v[110:113]
	s_waitcnt lgkmcnt(1)
	v_mfma_f32_16x16x32_bf16 v[110:113], v[26:29], v[208:211], v[110:113]
	v_mfma_f32_16x16x32_bf16 v[140:143], v[54:57], v[144:147], v[140:143]
	s_waitcnt lgkmcnt(0)
	v_mfma_f32_16x16x32_bf16 v[110:113], v[30:33], v[212:215], v[110:113]
	v_mfma_f32_16x16x32_bf16 v[140:143], v[58:61], v[208:211], v[140:143]
	v_mfma_f32_16x16x32_bf16 v[144:147], v[22:25], v[148:151], v[152:155]
	s_waitcnt vmcnt(1)
; __host__ __device__ __forceinline__ size_t img_off(int r, int c, int K) { return ((size_t)(r >> 7) * (size_t)(K >> 6) + (size_t)(c >> 6)) * 8192u + (size_t)(lds_byte(r & 127, c & 63) >> 1); }
; __device__ __forceinline__ unsigned cvt_pk_bf16(float lo, float hi) { unsigned r; asm volatile("v_cvt_pk_bf16_f32 %0, %1, %2" : "=v"(r) : "v"(lo), "v"(hi)); return r; }
; #define LAS __attribute__((address_space(3)))
; __device__ __forceinline__ float bf_lo(unsigned u) { return __uint_as_float(u << 16); }
; __device__ __forceinline__ float bf_hi(unsigned u) { return __uint_as_float(u & 0xffff0000u); }
; __device__ __forceinline__ void pool_phase(LAS unsigned char* lds, const bf16_t* PROJ, const bf16_t* PW, const float* pscale, bf16_t* Y, float* SS, int bx, int G) {
;     ...
;           for (int ks = 0; ks < 8; ++ks) {
;               if (ks + 1 < 8) {
; #pragma unroll
;                   for (int m = 0; m < 4; ++m) dfb[(ks + 1) & 1][m] = *(const LAS bf16x8*)(lds + PL_DT + (16 * m + fr) * PL_DROW + (32 * (ks + 1) + 8 * fq) * 2); }
; #pragma unroll
;               for (int m = 0; m < 4; ++m)
; #pragma unroll
;                   for (int j = 0; j < 2; ++j) acc[j][m] = MFMA16(wf[j][ks], dfb[ks & 1][m], acc[j][m]);
;           } }
;         const int cb = g * 256 + 32 * wid + 8 * fq; const f32x4 sc0 = *(const f32x4*)(pscale + cb), sc1 = *(const f32x4*)(pscale + cb + 4);
; #pragma unroll
;         for (int m = 0; m < 4; ++m) { const int tok = T0 + 16 * m + fr; float ssq = 0.f; const u32x4 gq = gt[m];
;             const float v0 = acc[0][m][0] * sc0[0] * bf_lo(gq.x), v1 = acc[0][m][1] * sc0[1] * bf_hi(gq.x), v2 = acc[0][m][2] * sc0[2] * bf_lo(gq.y), v3 = acc[0][m][3] * sc0[3] * bf_hi(gq.y);
;             const float v4 = acc[1][m][0] * sc1[0] * bf_lo(gq.z), v5 = acc[1][m][1] * sc1[1] * bf_hi(gq.z), v6 = acc[1][m][2] * sc1[2] * bf_lo(gq.w), v7 = acc[1][m][3] * sc1[3] * bf_hi(gq.w);
;             ssq = ((v0 * v0 + v1 * v1) + (v2 * v2 + v3 * v3)) + ((v4 * v4 + v5 * v5) + (v6 * v6 + v7 * v7));
;             u32x4 o; o.x = cvt_pk_bf16(v0, v1); o.y = cvt_pk_bf16(v2, v3); o.z = cvt_pk_bf16(v4, v5); o.w = cvt_pk_bf16(v6, v7); *(u32x4*)(Y + pg8::img_off(tok, cb, MIXW)) = o;
;             ssq += __shfl_xor(ssq, 16); ssq += __shfl_xor(ssq, 32);
;             if (fq == 0) ssw[wid * 64 + 16 * m + fr] = ssq; }
	s_nop 4
	v_mul_f32_e32 v110, v110, v106
	v_mul_f32_e32 v152, v110, v181
	v_mul_f32_e32 v110, v111, v107
	v_mfma_f32_16x16x32_bf16 v[114:117], v[54:57], v[148:151], v[114:117]
	v_mul_f32_e32 v148, v110, v98
	v_mul_f32_e32 v98, v112, v108
	v_lshlrev_b32_e32 v110, 16, v99
	v_mul_f32_e32 v149, v98, v110
	v_mul_f32_e32 v98, v113, v109
	v_mfma_f32_16x16x32_bf16 v[110:113], v[62:65], v[212:215], v[140:143]
	v_and_b32_e32 v99, 0xffff0000, v99
	v_mfma_f32_16x16x32_bf16 v[126:129], v[18:21], v[200:203], v[126:129]
	s_nop 0
	v_mul_f32_e32 v143, v98, v99
	s_waitcnt vmcnt(0)
	s_nop 2
	v_mul_f32_e32 v98, v110, v102
	v_lshlrev_b32_e32 v99, 16, v100
	v_mfma_f32_16x16x32_bf16 v[136:139], v[50:53], v[200:203], v[136:139]
	ds_read_b128 v[200:203], v191 offset:49792
	ds_read_b128 v[216:219], v191 offset:49856
	ds_read_b128 v[220:223], v191 offset:58240
	ds_read_b128 v[224:227], v191 offset:58304
	v_mul_f32_e32 v150, v98, v99
	v_mul_f32_e32 v98, v111, v103
	v_and_b32_e32 v99, 0xffff0000, v100
	v_mul_f32_e32 v151, v98, v99
	v_mul_f32_e32 v98, v112, v104
	v_lshlrev_b32_e32 v99, 16, v101
	v_mul_f32_e32 v110, v113, v105
	v_and_b32_e32 v111, 0xffff0000, v101
	ds_read_b128 v[228:231], v192 offset:41344
	ds_read_b128 v[232:235], v192 offset:41408
	v_mfma_f32_16x16x32_bf16 v[126:129], v[22:25], v[204:207], v[126:129]
	v_mul_f32_e32 v153, v98, v99
	v_cvt_pk_bf16_f32 v142, v152, v148
	v_mfma_f32_16x16x32_bf16 v[98:101], v[54:57], v[204:207], v[136:139]
	s_nop 2
	v_mul_f32_e32 v136, v110, v111
	s_waitcnt lgkmcnt(5)
	v_mfma_f32_16x16x32_bf16 v[110:113], v[26:29], v[200:203], v[144:147]
	v_mul_f32_e32 v137, v148, v148
	v_mul_f32_e32 v138, v143, v143
	v_fmac_f32_e32 v137, v152, v152
	v_fmac_f32_e32 v138, v149, v149
	v_mul_f32_e32 v139, v136, v136
	v_cvt_pk_bf16_f32 v143, v149, v143
	s_waitcnt lgkmcnt(1)
	v_mfma_f32_16x16x32_bf16 v[146:149], v[26:29], v[228:231], v[126:129]
	v_add_f32_e32 v137, v137, v138
	v_mul_f32_e32 v138, v151, v151
	v_fmac_f32_e32 v139, v153, v153
	v_mfma_f32_16x16x32_bf16 v[126:129], v[30:33], v[216:219], v[110:113]
	v_cvt_pk_bf16_f32 v144, v150, v151
	v_cvt_pk_bf16_f32 v145, v153, v136
	v_fmac_f32_e32 v138, v150, v150
	v_mfma_f32_16x16x32_bf16 v[122:125], v[54:57], v[196:199], v[122:125]
	v_add_f32_e32 v138, v138, v139
	v_and_b32_e32 v111, 64, v193
	v_xor_b32_e32 v110, 16, v193
	v_add_u32_e32 v153, 64, v111
	v_cmp_lt_i32_e32 vcc, v110, v153
	v_add_f32_e32 v137, v137, v138
	v_mfma_f32_16x16x32_bf16 v[114:117], v[58:61], v[200:203], v[114:117]
	v_cndmask_b32_e32 v110, v193, v110, vcc
	v_lshlrev_b32_e32 v136, 2, v110
	v_mov_b32_e32 v110, v137
	s_nop 1
	v_permlane16_swap_b32_e32 v110, v137
	v_mfma_f32_16x16x32_bf16 v[138:141], v[58:61], v[220:223], v[122:125]
	v_lshrrev_b32_e32 v152, 4, v182
	v_and_or_b32 v150, v182, s87, v157
	v_and_b32_e32 v111, 32, v152
	v_mfma_f32_16x16x32_bf16 v[118:121], v[22:25], v[196:199], v[118:121]
	v_and_or_b32 v122, s72, 8, v156
	v_lshlrev_b32_e32 v151, 10, v122
	v_bitop3_b32 v111, v150, v151, v111 bitop3:0xde
	v_mfma_f32_16x16x32_bf16 v[122:125], v[62:65], v[216:219], v[114:117]
	global_store_dwordx4 v111, v[142:145], s[70:71]
	v_mfma_f32_16x16x32_bf16 v[114:117], v[62:65], v[224:227], v[138:141]
	s_waitcnt lgkmcnt(0)
	s_nop 1
	v_add_f32_e32 v138, v137, v110
	v_xor_b32_e32 v137, 32, v193
	v_mfma_f32_16x16x32_bf16 v[118:121], v[26:29], v[220:223], v[118:121]
	v_cmp_lt_i32_e32 vcc, v137, v153
	v_mfma_f32_16x16x32_bf16 v[98:101], v[58:61], v[228:231], v[98:101]
	s_nop 0
	v_cndmask_b32_e32 v137, v193, v137, vcc
	v_lshlrev_b32_e32 v137, 2, v137
	v_mov_b32_e32 v139, v138
	s_nop 1
	v_permlane32_swap_b32_e32 v139, v138
	v_mfma_f32_16x16x32_bf16 v[118:121], v[30:33], v[224:227], v[118:121]
	v_mfma_f32_16x16x32_bf16 v[110:113], v[30:33], v[232:235], v[146:149]
	v_mfma_f32_16x16x32_bf16 v[98:101], v[62:65], v[232:235], v[98:101]
	s_and_saveexec_b64 s[72:73], s[16:17]
	s_cbranch_execz .LBB0_621
	s_waitcnt lgkmcnt(0)
	v_add_f32_e32 v138, v138, v139
	ds_write_b32 v158, v138
; __host__ __device__ __forceinline__ size_t img_off(int r, int c, int K) { return ((size_t)(r >> 7) * (size_t)(K >> 6) + (size_t)(c >> 6)) * 8192u + (size_t)(lds_byte(r & 127, c & 63) >> 1); }
; __device__ __forceinline__ unsigned cvt_pk_bf16(float lo, float hi) { unsigned r; asm volatile("v_cvt_pk_bf16_f32 %0, %1, %2" : "=v"(r) : "v"(lo), "v"(hi)); return r; }
; __device__ __forceinline__ float bf_lo(unsigned u) { return __uint_as_float(u << 16); }
; __device__ __forceinline__ float bf_hi(unsigned u) { return __uint_as_float(u & 0xffff0000u); }
; __device__ __forceinline__ void pool_phase(LAS unsigned char* lds, const bf16_t* PROJ, const bf16_t* PW, const float* pscale, bf16_t* Y, float* SS, int bx, int G) {
;     ...
;         for (int m = 0; m < 4; ++m) { const int tok = T0 + 16 * m + fr; float ssq = 0.f; const u32x4 gq = gt[m];
;             const float v0 = acc[0][m][0] * sc0[0] * bf_lo(gq.x), v1 = acc[0][m][1] * sc0[1] * bf_hi(gq.x), v2 = acc[0][m][2] * sc0[2] * bf_lo(gq.y), v3 = acc[0][m][3] * sc0[3] * bf_hi(gq.y);
;             const float v4 = acc[1][m][0] * sc1[0] * bf_lo(gq.z), v5 = acc[1][m][1] * sc1[1] * bf_hi(gq.z), v6 = acc[1][m][2] * sc1[2] * bf_lo(gq.w), v7 = acc[1][m][3] * sc1[3] * bf_hi(gq.w);
;             ssq = ((v0 * v0 + v1 * v1) + (v2 * v2 + v3 * v3)) + ((v4 * v4 + v5 * v5) + (v6 * v6 + v7 * v7));
;             u32x4 o; o.x = cvt_pk_bf16(v0, v1); o.y = cvt_pk_bf16(v2, v3); o.z = cvt_pk_bf16(v4, v5); o.w = cvt_pk_bf16(v6, v7); *(u32x4*)(Y + pg8::img_off(tok, cb, MIXW)) = o;
;             ssq += __shfl_xor(ssq, 16); ssq += __shfl_xor(ssq, 32);
;             if (fq == 0) ssw[wid * 64 + 16 * m + fr] = ssq; }
.LBB0_621:
	s_or_b64 exec, exec, s[72:73]
	v_lshlrev_b32_e32 v138, 16, v94
	v_mul_f32_e32 v127, v127, v107
	v_and_b32_e32 v94, 0xffff0000, v94
	v_mul_f32_e32 v94, v127, v94
	v_mul_f32_e32 v127, v128, v108
	v_lshlrev_b32_e32 v128, 16, v95
	v_mul_f32_e32 v127, v127, v128
	v_mul_f32_e32 v128, v129, v109
	v_and_b32_e32 v95, 0xffff0000, v95
	v_mul_f32_e32 v95, v128, v95
	v_mul_f32_e32 v122, v122, v102
	v_lshlrev_b32_e32 v128, 16, v96
	v_mul_f32_e32 v128, v122, v128
	v_mul_f32_e32 v122, v123, v103
	v_and_b32_e32 v96, 0xffff0000, v96
	v_mul_f32_e32 v96, v122, v96
	v_mul_f32_e32 v122, v124, v104
	v_lshlrev_b32_e32 v123, 16, v97
	v_mul_f32_e32 v126, v126, v106
	v_mul_f32_e32 v129, v122, v123
	v_mul_f32_e32 v122, v125, v105
	v_and_b32_e32 v97, 0xffff0000, v97
	v_mul_f32_e32 v126, v126, v138
	v_mul_f32_e32 v97, v122, v97
	v_mul_f32_e32 v122, v94, v94
	v_mul_f32_e32 v123, v95, v95
	v_fmac_f32_e32 v122, v126, v126
	v_fmac_f32_e32 v123, v127, v127
	v_add_f32_e32 v122, v122, v123
	v_mul_f32_e32 v123, v96, v96
	v_mul_f32_e32 v124, v97, v97
	v_fmac_f32_e32 v123, v128, v128
	v_fmac_f32_e32 v124, v129, v129
	v_add_f32_e32 v123, v123, v124
	v_add_f32_e32 v138, v122, v123
	v_cvt_pk_bf16_f32 v122, v126, v94
	ds_bpermute_b32 v94, v136, v138
	s_add_i32 s72, s88, 16
	s_lshr_b32 s72, s72, 3
	v_cvt_pk_bf16_f32 v123, v127, v95
	v_and_or_b32 v95, s72, 10, v156
	s_waitcnt lgkmcnt(0)
	v_add_f32_e32 v94, v138, v94
	v_lshlrev_b32_e32 v126, 10, v95
	v_mov_b32_e32 v95, v94
	s_nop 1
	v_permlane32_swap_b32_e32 v95, v94
	v_cvt_pk_bf16_f32 v124, v128, v96
	v_add_u32_e32 v96, 0x400, v182
	v_cvt_pk_bf16_f32 v125, v129, v97
	v_and_or_b32 v97, v96, s87, v157
	v_lshrrev_b32_e32 v96, 4, v96
	v_and_b32_e32 v96, 32, v96
	v_bitop3_b32 v96, v97, v126, v96 bitop3:0xde
	global_store_dwordx4 v96, v[122:125], s[70:71]
	s_and_saveexec_b64 s[72:73], s[16:17]
	s_cbranch_execz .LBB0_623
	s_waitcnt lgkmcnt(0)
	v_add_f32_e32 v94, v94, v95
	ds_write_b32 v158, v94 offset:64
.LBB0_623:
	s_or_b64 exec, exec, s[72:73]
	v_mul_f32_e32 v94, v118, v106
	s_waitcnt lgkmcnt(0)
	v_lshlrev_b32_e32 v95, 16, v90
	v_mul_f32_e32 v94, v94, v95
	v_mul_f32_e32 v95, v119, v107
	v_and_b32_e32 v90, 0xffff0000, v90
	v_mul_f32_e32 v90, v95, v90
	v_mul_f32_e32 v95, v120, v108
	v_lshlrev_b32_e32 v96, 16, v91
	v_mul_f32_e32 v95, v95, v96
	v_mul_f32_e32 v96, v121, v109
	v_and_b32_e32 v91, 0xffff0000, v91
	v_mul_f32_e32 v91, v96, v91
	v_mul_f32_e32 v96, v114, v102
	v_lshlrev_b32_e32 v97, 16, v92
	v_mul_f32_e32 v96, v96, v97
	v_mul_f32_e32 v97, v115, v103
	v_and_b32_e32 v92, 0xffff0000, v92
	v_mul_f32_e32 v97, v97, v92
	v_mul_f32_e32 v92, v116, v104
	v_lshlrev_b32_e32 v114, 16, v93
	v_mul_f32_e32 v114, v92, v114
	v_mul_f32_e32 v92, v117, v105
	v_and_b32_e32 v93, 0xffff0000, v93
	v_mul_f32_e32 v115, v92, v93
	v_mul_f32_e32 v92, v90, v90
	v_mul_f32_e32 v93, v91, v91
	v_fmac_f32_e32 v92, v94, v94
	v_fmac_f32_e32 v93, v95, v95
	v_add_f32_e32 v92, v92, v93
	v_mul_f32_e32 v93, v97, v97
	v_mul_f32_e32 v116, v115, v115
	v_fmac_f32_e32 v93, v96, v96
	v_fmac_f32_e32 v116, v114, v114
	v_add_f32_e32 v93, v93, v116
	v_add_f32_e32 v116, v92, v93
	v_cvt_pk_bf16_f32 v92, v94, v90
	v_mov_b32_e32 v90, v116
	s_nop 1
	v_permlane16_swap_b32_e32 v90, v116
	s_add_i32 s72, s88, 32
	s_lshr_b32 s72, s72, 3
	v_cvt_pk_bf16_f32 v93, v95, v91
	v_and_or_b32 v91, s72, 12, v156
	s_waitcnt lgkmcnt(0)
	v_add_f32_e32 v90, v116, v90
	v_cvt_pk_bf16_f32 v94, v96, v97
	v_cvt_pk_bf16_f32 v95, v114, v115
	v_lshlrev_b32_e32 v114, 10, v91
	v_mov_b32_e32 v91, v90
	s_nop 1
	v_permlane32_swap_b32_e32 v91, v90
	v_add_u32_e32 v96, 0x800, v182
	v_and_or_b32 v97, v96, s87, v157
	v_lshrrev_b32_e32 v96, 4, v96
	v_and_b32_e32 v96, 32, v96
	v_bitop3_b32 v96, v97, v114, v96 bitop3:0xde
	global_store_dwordx4 v96, v[92:95], s[70:71]
	s_and_saveexec_b64 s[72:73], s[16:17]
	s_cbranch_execz .LBB0_625
	s_waitcnt lgkmcnt(0)
	v_add_f32_e32 v90, v90, v91
	ds_write_b32 v158, v90 offset:128
.LBB0_625:
	s_or_b64 exec, exec, s[72:73]
	v_mul_f32_e32 v90, v110, v106
	s_waitcnt lgkmcnt(0)
	v_lshlrev_b32_e32 v91, 16, v86
	v_mul_f32_e32 v90, v90, v91
	v_mul_f32_e32 v91, v111, v107
	v_and_b32_e32 v86, 0xffff0000, v86
	v_mul_f32_e32 v86, v91, v86
	v_mul_f32_e32 v91, v112, v108
	v_lshlrev_b32_e32 v92, 16, v87
	v_mul_f32_e32 v91, v91, v92
	v_mul_f32_e32 v92, v113, v109
	v_and_b32_e32 v87, 0xffff0000, v87
	v_mul_f32_e32 v87, v92, v87
	v_mul_f32_e32 v92, v98, v102
	v_lshlrev_b32_e32 v93, 16, v88
	v_mul_f32_e32 v92, v92, v93
	v_mul_f32_e32 v93, v99, v103
	v_and_b32_e32 v88, 0xffff0000, v88
	v_mul_f32_e32 v93, v93, v88
	v_mul_f32_e32 v88, v100, v104
	v_lshlrev_b32_e32 v94, 16, v89
	v_mul_f32_e32 v94, v88, v94
	v_mul_f32_e32 v88, v101, v105
	v_and_b32_e32 v89, 0xffff0000, v89
	v_mul_f32_e32 v95, v88, v89
	v_mul_f32_e32 v88, v86, v86
	v_mul_f32_e32 v89, v87, v87
	v_fmac_f32_e32 v88, v90, v90
	v_fmac_f32_e32 v89, v91, v91
	v_add_f32_e32 v88, v88, v89
	v_mul_f32_e32 v89, v93, v93
	v_mul_f32_e32 v96, v95, v95
	v_fmac_f32_e32 v89, v92, v92
	v_fmac_f32_e32 v96, v94, v94
	v_add_f32_e32 v89, v89, v96
	v_add_f32_e32 v96, v88, v89
	v_cvt_pk_bf16_f32 v88, v90, v86
	ds_bpermute_b32 v86, v136, v96
	s_add_i32 s88, s88, 48
	s_lshr_b32 s72, s88, 3
	v_cvt_pk_bf16_f32 v89, v91, v87
	v_and_or_b32 v87, s72, 14, v156
	s_waitcnt lgkmcnt(0)
	v_add_f32_e32 v86, v96, v86
	v_cvt_pk_bf16_f32 v90, v92, v93
	v_cvt_pk_bf16_f32 v91, v94, v95
	v_lshlrev_b32_e32 v94, 10, v87
	v_mov_b32_e32 v87, v86
	s_nop 1
	v_permlane32_swap_b32_e32 v87, v86
	v_add_u32_e32 v92, 0xc00, v182
	v_and_or_b32 v93, v92, s87, v157
	v_lshrrev_b32_e32 v92, 4, v92
	v_and_b32_e32 v92, 32, v92
	v_bitop3_b32 v92, v93, v94, v92 bitop3:0xde
	global_store_dwordx4 v92, v[88:91], s[70:71]
	s_and_saveexec_b64 s[70:71], s[16:17]
	s_cbranch_execz .LBB0_627
	s_waitcnt lgkmcnt(0)
	v_add_f32_e32 v86, v86, v87
	ds_write_b32 v158, v86 offset:192

; __host__ __device__ __forceinline__ size_t img_off(int r, int c, int K) { return ((size_t)(r >> 7) * (size_t)(K >> 6) + (size_t)(c >> 6)) * 8192u + (size_t)(lds_byte(r & 127, c & 63) >> 1); }
; __device__ __forceinline__ unsigned cvt_pk_bf16(float lo, float hi) { unsigned r; asm volatile("v_cvt_pk_bf16_f32 %0, %1, %2" : "=v"(r) : "v"(lo), "v"(hi)); return r; }
; __device__ __forceinline__ float bf_lo(unsigned u) { return __uint_as_float(u << 16); }
; __device__ __forceinline__ float bf_hi(unsigned u) { return __uint_as_float(u & 0xffff0000u); }
; __device__ __forceinline__ void sgu_phase(LAS unsigned char* lds, const bf16_t* PROJ, const float* VST, const bf16_t* SW, const float* ln_g, const float* ln_b, const float* sgu_b,
;                                           bf16_t* Y, float* SS, int bx, int G) {
;     ...
;             const int t = 16 * j + fr, tok = T0 + t, cb = h * 128 + 32 * dp + 8 * fq; const float bs = bias[jj]; const u32x4 u4 = uu[jj], g4 = gg[jj];
;             const float v0 = (acc0[0] + bs) * bf_lo(u4.x) * bf_lo(g4.x), v1 = (acc0[1] + bs) * bf_hi(u4.x) * bf_hi(g4.x), v2 = (acc0[2] + bs) * bf_lo(u4.y) * bf_lo(g4.y), v3 = (acc0[3] + bs) * bf_hi(u4.y) * bf_hi(g4.y);
;             const float v4 = (acc1[0] + bs) * bf_lo(u4.z) * bf_lo(g4.z), v5 = (acc1[1] + bs) * bf_hi(u4.z) * bf_hi(g4.z), v6 = (acc1[2] + bs) * bf_lo(u4.w) * bf_lo(g4.w), v7 = (acc1[3] + bs) * bf_hi(u4.w) * bf_hi(g4.w);
;             float ssq = ((v0 * v0 + v1 * v1) + (v2 * v2 + v3 * v3)) + ((v4 * v4 + v5 * v5) + (v6 * v6 + v7 * v7));
;             u32x4 o; o.x = cvt_pk_bf16(v0, v1); o.y = cvt_pk_bf16(v2, v3); o.z = cvt_pk_bf16(v4, v5); o.w = cvt_pk_bf16(v6, v7); *(u32x4*)(Y + pg8::img_off(tok, 1024 + cb, MIXW)) = o;
;             ssq += __shfl_xor(ssq, 16); ssq += __shfl_xor(ssq, 32);
;             if (fq == 0) ssw[wid * 128 + t] = ssq;
.LBB0_641:
	s_nop 6
	v_add_f32_e32 v94, v109, v94
	s_waitcnt vmcnt(7)
	v_lshlrev_b32_e32 v98, 16, v54
	v_add_f32_e32 v95, v109, v95
	v_and_b32_e32 v54, 0xffff0000, v54
	v_mul_f32_e32 v94, v94, v98
	s_waitcnt vmcnt(6)
	v_lshlrev_b32_e32 v98, 16, v50
	v_mul_f32_e32 v54, v95, v54
	v_and_b32_e32 v50, 0xffff0000, v50
	v_mul_f32_e32 v50, v54, v50
	v_add_f32_e32 v54, v109, v96
	v_lshlrev_b32_e32 v95, 16, v55
	v_mul_f32_e32 v54, v54, v95
	v_lshlrev_b32_e32 v95, 16, v51
	v_mul_f32_e32 v54, v54, v95
	v_add_f32_e32 v95, v109, v97
	v_and_b32_e32 v55, 0xffff0000, v55
	v_mul_f32_e32 v55, v95, v55
	v_and_b32_e32 v51, 0xffff0000, v51
	v_mul_f32_e32 v51, v55, v51
	v_add_f32_e32 v55, v109, v90
	v_lshlrev_b32_e32 v90, 16, v56
	v_mul_f32_e32 v55, v55, v90
	v_lshlrev_b32_e32 v90, 16, v52
	v_mul_f32_e32 v55, v55, v90
	v_add_f32_e32 v90, v109, v91
	v_and_b32_e32 v56, 0xffff0000, v56
	v_mul_f32_e32 v56, v90, v56
	v_and_b32_e32 v52, 0xffff0000, v52
	v_mul_f32_e32 v56, v56, v52
	v_add_f32_e32 v52, v109, v92
	v_lshlrev_b32_e32 v90, 16, v57
	v_mul_f32_e32 v52, v52, v90
	v_lshlrev_b32_e32 v90, 16, v53
	v_mul_f32_e32 v90, v52, v90
	v_add_f32_e32 v52, v109, v93
	v_and_b32_e32 v57, 0xffff0000, v57
	v_mul_f32_e32 v52, v52, v57
	v_and_b32_e32 v53, 0xffff0000, v53
	v_mul_f32_e32 v94, v94, v98
	v_mul_f32_e32 v57, v52, v53
	v_mul_f32_e32 v52, v50, v50
	v_mul_f32_e32 v53, v51, v51
	v_fmac_f32_e32 v52, v94, v94
	v_fmac_f32_e32 v53, v54, v54
	v_add_f32_e32 v52, v52, v53
	v_mul_f32_e32 v53, v56, v56
	v_mul_f32_e32 v91, v57, v57
	v_fmac_f32_e32 v53, v55, v55
	v_fmac_f32_e32 v91, v90, v90
	v_add_f32_e32 v53, v53, v91
	v_add_f32_e32 v91, v52, v53
	v_cvt_pk_bf16_f32 v52, v94, v50
	v_mov_b32_e32 v50, v91
	s_nop 1
	v_permlane16_swap_b32_e32 v50, v91
	v_cvt_pk_bf16_f32 v53, v54, v51
	v_cvt_pk_bf16_f32 v54, v55, v56
	v_cvt_pk_bf16_f32 v55, v90, v57
	v_add_u32_e32 v90, s62, v148
	v_lshrrev_b32_e32 v56, 4, v90
	s_ashr_i32 s19, s59, 31
	v_and_or_b32 v51, v90, s67, v117
	v_and_b32_e32 v56, 32, v56
	s_waitcnt lgkmcnt(0)
	v_add_f32_e32 v50, v91, v50
	s_add_u32 s18, s59, s10
	v_bitop3_b32 v56, v51, s38, v56 bitop3:0xde
	v_mov_b32_e32 v51, v50
	s_nop 1
	v_permlane32_swap_b32_e32 v51, v50
	s_addc_u32 s19, s19, s11
	s_lshl_b64 s[18:19], s[18:19], 14
	s_add_u32 s18, s44, s18
	s_addc_u32 s19, s45, s19
	global_store_dwordx4 v56, v[52:55], s[18:19]
	s_and_saveexec_b64 s[18:19], s[8:9]
	s_cbranch_execz .LBB0_643
	s_waitcnt lgkmcnt(0)
	v_add_f32_e32 v50, v50, v51
	ds_write_b32 v138, v50

; __host__ __device__ __forceinline__ size_t img_off(int r, int c, int K) { return ((size_t)(r >> 7) * (size_t)(K >> 6) + (size_t)(c >> 6)) * 8192u + (size_t)(lds_byte(r & 127, c & 63) >> 1); }
; __device__ __forceinline__ unsigned cvt_pk_bf16(float lo, float hi) { unsigned r; asm volatile("v_cvt_pk_bf16_f32 %0, %1, %2" : "=v"(r) : "v"(lo), "v"(hi)); return r; }
; __device__ __forceinline__ float bf_lo(unsigned u) { return __uint_as_float(u << 16); }
; __device__ __forceinline__ float bf_hi(unsigned u) { return __uint_as_float(u & 0xffff0000u); }
; __device__ __forceinline__ void sgu_phase(LAS unsigned char* lds, const bf16_t* PROJ, const float* VST, const bf16_t* SW, const float* ln_g, const float* ln_b, const float* sgu_b,
;                                           bf16_t* Y, float* SS, int bx, int G) {
;     ...
;             const int t = 16 * j + fr, tok = T0 + t, cb = h * 128 + 32 * dp + 8 * fq; const float bs = bias[jj]; const u32x4 u4 = uu[jj], g4 = gg[jj];
;             const float v0 = (acc0[0] + bs) * bf_lo(u4.x) * bf_lo(g4.x), v1 = (acc0[1] + bs) * bf_hi(u4.x) * bf_hi(g4.x), v2 = (acc0[2] + bs) * bf_lo(u4.y) * bf_lo(g4.y), v3 = (acc0[3] + bs) * bf_hi(u4.y) * bf_hi(g4.y);
;             const float v4 = (acc1[0] + bs) * bf_lo(u4.z) * bf_lo(g4.z), v5 = (acc1[1] + bs) * bf_hi(u4.z) * bf_hi(g4.z), v6 = (acc1[2] + bs) * bf_lo(u4.w) * bf_lo(g4.w), v7 = (acc1[3] + bs) * bf_hi(u4.w) * bf_hi(g4.w);
;             float ssq = ((v0 * v0 + v1 * v1) + (v2 * v2 + v3 * v3)) + ((v4 * v4 + v5 * v5) + (v6 * v6 + v7 * v7));
;             u32x4 o; o.x = cvt_pk_bf16(v0, v1); o.y = cvt_pk_bf16(v2, v3); o.z = cvt_pk_bf16(v4, v5); o.w = cvt_pk_bf16(v6, v7); *(u32x4*)(Y + pg8::img_off(tok, 1024 + cb, MIXW)) = o;
;             ssq += __shfl_xor(ssq, 16); ssq += __shfl_xor(ssq, 32);
;             if (fq == 0) ssw[wid * 128 + t] = ssq;
.LBB0_647:
	s_nop 6
	v_add_f32_e32 v54, v110, v54
	s_waitcnt vmcnt(6)
	v_lshlrev_b32_e32 v93, 16, v46
	v_add_f32_e32 v55, v110, v55
	v_and_b32_e32 v46, 0xffff0000, v46
	v_mul_f32_e32 v54, v54, v93
	s_waitcnt vmcnt(5)
	v_lshlrev_b32_e32 v93, 16, v42
	v_mul_f32_e32 v46, v55, v46
	v_and_b32_e32 v42, 0xffff0000, v42
	v_mul_f32_e32 v42, v46, v42
	v_add_f32_e32 v46, v110, v56
	v_lshlrev_b32_e32 v55, 16, v47
	v_mul_f32_e32 v46, v46, v55
	v_lshlrev_b32_e32 v55, 16, v43
	v_mul_f32_e32 v46, v46, v55
	v_add_f32_e32 v55, v110, v57
	v_and_b32_e32 v47, 0xffff0000, v47
	v_mul_f32_e32 v47, v55, v47
	v_and_b32_e32 v43, 0xffff0000, v43
	v_mul_f32_e32 v43, v47, v43
	v_add_f32_e32 v47, v110, v50
	v_lshlrev_b32_e32 v50, 16, v48
	v_mul_f32_e32 v47, v47, v50
	v_lshlrev_b32_e32 v50, 16, v44
	v_mul_f32_e32 v47, v47, v50
	v_add_f32_e32 v50, v110, v51
	v_and_b32_e32 v48, 0xffff0000, v48
	v_mul_f32_e32 v48, v50, v48
	v_and_b32_e32 v44, 0xffff0000, v44
	v_mul_f32_e32 v48, v48, v44
	v_add_f32_e32 v44, v110, v52
	v_lshlrev_b32_e32 v50, 16, v49
	v_mul_f32_e32 v44, v44, v50
	v_lshlrev_b32_e32 v50, 16, v45
	v_mul_f32_e32 v50, v44, v50
	v_add_f32_e32 v44, v110, v53
	v_and_b32_e32 v49, 0xffff0000, v49
	v_mul_f32_e32 v44, v44, v49
	v_and_b32_e32 v45, 0xffff0000, v45
	v_mul_f32_e32 v54, v54, v93
	v_mul_f32_e32 v49, v44, v45
	v_mul_f32_e32 v44, v42, v42
	v_mul_f32_e32 v45, v43, v43
	v_fmac_f32_e32 v44, v54, v54
	v_fmac_f32_e32 v45, v46, v46
	v_add_f32_e32 v44, v44, v45
	v_mul_f32_e32 v45, v48, v48
	v_mul_f32_e32 v51, v49, v49
	v_add_u32_e32 v91, s58, v149
	v_fmac_f32_e32 v45, v47, v47
	v_fmac_f32_e32 v51, v50, v50
	v_add_u32_e32 v92, 16, v91
	v_add_f32_e32 v45, v45, v51
	v_add_f32_e32 v51, v44, v45
	v_cvt_pk_bf16_f32 v44, v54, v42
	v_ashrrev_i32_e32 v42, 7, v92
	v_mul_lo_u32 v42, v42, 48
	v_cvt_pk_bf16_f32 v45, v46, v43
	v_ashrrev_i32_e32 v43, 31, v42
	v_cvt_pk_bf16_f32 v46, v47, v48
	v_cvt_pk_bf16_f32 v47, v50, v49
	v_lshl_add_u64 v[48:49], v[42:43], 0, s[10:11]
	v_mov_b32_e32 v43, v51
	s_nop 1
	v_permlane16_swap_b32_e32 v43, v51
	v_add_u32_e32 v42, 0x400, v90
	v_and_or_b32 v50, v42, s67, v117
	v_lshrrev_b32_e32 v42, 4, v42
	v_and_b32_e32 v42, 32, v42
	v_bitop3_b32 v98, v50, s39, v42 bitop3:0xde
	s_waitcnt lgkmcnt(0)
	v_add_f32_e32 v42, v51, v43
	v_mov_b32_e32 v43, v42
	s_nop 1
	v_permlane32_swap_b32_e32 v43, v42
	v_lshlrev_b64 v[48:49], 14, v[48:49]
	v_lshl_add_u64 v[48:49], s[44:45], 0, v[48:49]
	v_lshl_add_u64 v[48:49], v[48:49], 0, v[98:99]
	global_store_dwordx4 v[48:49], v[44:47], off
	s_and_saveexec_b64 s[18:19], s[8:9]
	s_cbranch_execz .LBB0_649
	s_waitcnt lgkmcnt(0)
	v_add_f32_e32 v42, v42, v43
	ds_write_b32 v139, v42

; __host__ __device__ __forceinline__ size_t img_off(int r, int c, int K) { return ((size_t)(r >> 7) * (size_t)(K >> 6) + (size_t)(c >> 6)) * 8192u + (size_t)(lds_byte(r & 127, c & 63) >> 1); }
; __device__ __forceinline__ unsigned cvt_pk_bf16(float lo, float hi) { unsigned r; asm volatile("v_cvt_pk_bf16_f32 %0, %1, %2" : "=v"(r) : "v"(lo), "v"(hi)); return r; }
; __device__ __forceinline__ float bf_lo(unsigned u) { return __uint_as_float(u << 16); }
; __device__ __forceinline__ float bf_hi(unsigned u) { return __uint_as_float(u & 0xffff0000u); }
; __device__ __forceinline__ void sgu_phase(LAS unsigned char* lds, const bf16_t* PROJ, const float* VST, const bf16_t* SW, const float* ln_g, const float* ln_b, const float* sgu_b,
;                                           bf16_t* Y, float* SS, int bx, int G) {
;     ...
;             const int t = 16 * j + fr, tok = T0 + t, cb = h * 128 + 32 * dp + 8 * fq; const float bs = bias[jj]; const u32x4 u4 = uu[jj], g4 = gg[jj];
;             const float v0 = (acc0[0] + bs) * bf_lo(u4.x) * bf_lo(g4.x), v1 = (acc0[1] + bs) * bf_hi(u4.x) * bf_hi(g4.x), v2 = (acc0[2] + bs) * bf_lo(u4.y) * bf_lo(g4.y), v3 = (acc0[3] + bs) * bf_hi(u4.y) * bf_hi(g4.y);
;             const float v4 = (acc1[0] + bs) * bf_lo(u4.z) * bf_lo(g4.z), v5 = (acc1[1] + bs) * bf_hi(u4.z) * bf_hi(g4.z), v6 = (acc1[2] + bs) * bf_lo(u4.w) * bf_lo(g4.w), v7 = (acc1[3] + bs) * bf_hi(u4.w) * bf_hi(g4.w);
;             float ssq = ((v0 * v0 + v1 * v1) + (v2 * v2 + v3 * v3)) + ((v4 * v4 + v5 * v5) + (v6 * v6 + v7 * v7));
;             u32x4 o; o.x = cvt_pk_bf16(v0, v1); o.y = cvt_pk_bf16(v2, v3); o.z = cvt_pk_bf16(v4, v5); o.w = cvt_pk_bf16(v6, v7); *(u32x4*)(Y + pg8::img_off(tok, 1024 + cb, MIXW)) = o;
;             ssq += __shfl_xor(ssq, 16); ssq += __shfl_xor(ssq, 32);
;             if (fq == 0) ssw[wid * 128 + t] = ssq;
.LBB0_653:
	s_nop 6
	v_add_f32_e32 v46, v111, v46
	s_waitcnt vmcnt(5)
	v_lshlrev_b32_e32 v51, 16, v38
	v_add_f32_e32 v47, v111, v47
	v_and_b32_e32 v38, 0xffff0000, v38
	v_mul_f32_e32 v46, v46, v51
	s_waitcnt vmcnt(4)
	v_lshlrev_b32_e32 v51, 16, v34
	v_mul_f32_e32 v38, v47, v38
	v_and_b32_e32 v34, 0xffff0000, v34
	v_mul_f32_e32 v34, v38, v34
	v_add_f32_e32 v38, v111, v48
	v_lshlrev_b32_e32 v47, 16, v39
	v_mul_f32_e32 v38, v38, v47
	v_lshlrev_b32_e32 v47, 16, v35
	v_mul_f32_e32 v38, v38, v47
	v_add_f32_e32 v47, v111, v49
	v_and_b32_e32 v39, 0xffff0000, v39
	v_mul_f32_e32 v39, v47, v39
	v_and_b32_e32 v35, 0xffff0000, v35
	v_mul_f32_e32 v35, v39, v35
	v_add_f32_e32 v39, v111, v42
	v_lshlrev_b32_e32 v42, 16, v40
	v_mul_f32_e32 v39, v39, v42
	v_lshlrev_b32_e32 v42, 16, v36
	v_mul_f32_e32 v39, v39, v42
	v_add_f32_e32 v42, v111, v43
	v_and_b32_e32 v40, 0xffff0000, v40
	v_mul_f32_e32 v40, v42, v40
	v_and_b32_e32 v36, 0xffff0000, v36
	v_mul_f32_e32 v40, v40, v36
	v_add_f32_e32 v36, v111, v44
	v_lshlrev_b32_e32 v42, 16, v41
	v_mul_f32_e32 v36, v36, v42
	v_lshlrev_b32_e32 v42, 16, v37
	v_mul_f32_e32 v42, v36, v42
	v_add_f32_e32 v36, v111, v45
	v_and_b32_e32 v41, 0xffff0000, v41
	v_mul_f32_e32 v36, v36, v41
	v_and_b32_e32 v37, 0xffff0000, v37
	v_mul_f32_e32 v46, v46, v51
	v_mul_f32_e32 v41, v36, v37
	v_mul_f32_e32 v36, v34, v34
	v_mul_f32_e32 v37, v35, v35
	v_fmac_f32_e32 v36, v46, v46
	v_fmac_f32_e32 v37, v38, v38
	v_add_f32_e32 v36, v36, v37
	v_mul_f32_e32 v37, v40, v40
	v_mul_f32_e32 v43, v41, v41
	v_fmac_f32_e32 v37, v39, v39
	v_fmac_f32_e32 v43, v42, v42
	v_add_u32_e32 v50, 32, v91
	v_add_f32_e32 v37, v37, v43
	v_add_f32_e32 v43, v36, v37
	v_cvt_pk_bf16_f32 v36, v46, v34
	v_ashrrev_i32_e32 v34, 7, v50
	v_mul_lo_u32 v34, v34, 48
	v_cvt_pk_bf16_f32 v37, v38, v35
	v_ashrrev_i32_e32 v35, 31, v34
	v_cvt_pk_bf16_f32 v38, v39, v40
	v_cvt_pk_bf16_f32 v39, v42, v41
	v_lshl_add_u64 v[40:41], v[34:35], 0, s[10:11]
	v_mov_b32_e32 v35, v43
	s_nop 1
	v_permlane16_swap_b32_e32 v35, v43
	v_add_u32_e32 v34, 0x800, v90
	v_and_or_b32 v42, v34, s67, v117
	v_lshrrev_b32_e32 v34, 4, v34
	v_and_b32_e32 v34, 32, v34
	v_bitop3_b32 v98, v42, s54, v34 bitop3:0xde
	s_waitcnt lgkmcnt(0)
	v_add_f32_e32 v34, v43, v35
	v_mov_b32_e32 v35, v34
	s_nop 1
	v_permlane32_swap_b32_e32 v35, v34
	v_lshlrev_b64 v[40:41], 14, v[40:41]
	v_lshl_add_u64 v[40:41], s[44:45], 0, v[40:41]
	v_lshl_add_u64 v[40:41], v[40:41], 0, v[98:99]
	global_store_dwordx4 v[40:41], v[36:39], off
	s_and_saveexec_b64 s[18:19], s[8:9]
	s_cbranch_execz .LBB0_655
	s_waitcnt lgkmcnt(0)
	v_add_f32_e32 v34, v34, v35
	ds_write_b32 v140, v34

; __host__ __device__ __forceinline__ size_t img_off(int r, int c, int K) { return ((size_t)(r >> 7) * (size_t)(K >> 6) + (size_t)(c >> 6)) * 8192u + (size_t)(lds_byte(r & 127, c & 63) >> 1); }
; __device__ __forceinline__ unsigned cvt_pk_bf16(float lo, float hi) { unsigned r; asm volatile("v_cvt_pk_bf16_f32 %0, %1, %2" : "=v"(r) : "v"(lo), "v"(hi)); return r; }
; __device__ __forceinline__ float bf_lo(unsigned u) { return __uint_as_float(u << 16); }
; __device__ __forceinline__ float bf_hi(unsigned u) { return __uint_as_float(u & 0xffff0000u); }
; __device__ __forceinline__ void sgu_phase(LAS unsigned char* lds, const bf16_t* PROJ, const float* VST, const bf16_t* SW, const float* ln_g, const float* ln_b, const float* sgu_b,
;                                           bf16_t* Y, float* SS, int bx, int G) {
;     ...
;             const int t = 16 * j + fr, tok = T0 + t, cb = h * 128 + 32 * dp + 8 * fq; const float bs = bias[jj]; const u32x4 u4 = uu[jj], g4 = gg[jj];
;             const float v0 = (acc0[0] + bs) * bf_lo(u4.x) * bf_lo(g4.x), v1 = (acc0[1] + bs) * bf_hi(u4.x) * bf_hi(g4.x), v2 = (acc0[2] + bs) * bf_lo(u4.y) * bf_lo(g4.y), v3 = (acc0[3] + bs) * bf_hi(u4.y) * bf_hi(g4.y);
;             const float v4 = (acc1[0] + bs) * bf_lo(u4.z) * bf_lo(g4.z), v5 = (acc1[1] + bs) * bf_hi(u4.z) * bf_hi(g4.z), v6 = (acc1[2] + bs) * bf_lo(u4.w) * bf_lo(g4.w), v7 = (acc1[3] + bs) * bf_hi(u4.w) * bf_hi(g4.w);
;             float ssq = ((v0 * v0 + v1 * v1) + (v2 * v2 + v3 * v3)) + ((v4 * v4 + v5 * v5) + (v6 * v6 + v7 * v7));
;             u32x4 o; o.x = cvt_pk_bf16(v0, v1); o.y = cvt_pk_bf16(v2, v3); o.z = cvt_pk_bf16(v4, v5); o.w = cvt_pk_bf16(v6, v7); *(u32x4*)(Y + pg8::img_off(tok, 1024 + cb, MIXW)) = o;
;             ssq += __shfl_xor(ssq, 16); ssq += __shfl_xor(ssq, 32);
;             if (fq == 0) ssw[wid * 128 + t] = ssq;
.LBB0_659:
	s_nop 6
	v_add_f32_e32 v38, v112, v38
	s_waitcnt vmcnt(4)
	v_lshlrev_b32_e32 v43, 16, v30
	v_add_f32_e32 v39, v112, v39
	v_and_b32_e32 v30, 0xffff0000, v30
	v_mul_f32_e32 v38, v38, v43
	s_waitcnt vmcnt(3)
	v_lshlrev_b32_e32 v43, 16, v26
	v_mul_f32_e32 v30, v39, v30
	v_and_b32_e32 v26, 0xffff0000, v26
	v_mul_f32_e32 v26, v30, v26
	v_add_f32_e32 v30, v112, v40
	v_lshlrev_b32_e32 v39, 16, v31
	v_mul_f32_e32 v30, v30, v39
	v_lshlrev_b32_e32 v39, 16, v27
	v_mul_f32_e32 v30, v30, v39
	v_add_f32_e32 v39, v112, v41
	v_and_b32_e32 v31, 0xffff0000, v31
	v_mul_f32_e32 v31, v39, v31
	v_and_b32_e32 v27, 0xffff0000, v27
	v_mul_f32_e32 v27, v31, v27
	v_add_f32_e32 v31, v112, v34
	v_lshlrev_b32_e32 v34, 16, v32
	v_mul_f32_e32 v31, v31, v34
	v_lshlrev_b32_e32 v34, 16, v28
	v_mul_f32_e32 v31, v31, v34
	v_add_f32_e32 v34, v112, v35
	v_and_b32_e32 v32, 0xffff0000, v32
	v_mul_f32_e32 v32, v34, v32
	v_and_b32_e32 v28, 0xffff0000, v28
	v_mul_f32_e32 v32, v32, v28
	v_add_f32_e32 v28, v112, v36
	v_lshlrev_b32_e32 v34, 16, v33
	v_mul_f32_e32 v28, v28, v34
	v_lshlrev_b32_e32 v34, 16, v29
	v_mul_f32_e32 v34, v28, v34
	v_add_f32_e32 v28, v112, v37
	v_and_b32_e32 v33, 0xffff0000, v33
	v_mul_f32_e32 v28, v28, v33
	v_and_b32_e32 v29, 0xffff0000, v29
	v_mul_f32_e32 v38, v38, v43
	v_mul_f32_e32 v33, v28, v29
	v_mul_f32_e32 v28, v26, v26
	v_mul_f32_e32 v29, v27, v27
	v_fmac_f32_e32 v28, v38, v38
	v_fmac_f32_e32 v29, v30, v30
	v_add_f32_e32 v28, v28, v29
	v_mul_f32_e32 v29, v32, v32
	v_mul_f32_e32 v35, v33, v33
	v_fmac_f32_e32 v29, v31, v31
	v_fmac_f32_e32 v35, v34, v34
	v_add_u32_e32 v42, 48, v91
	v_add_f32_e32 v29, v29, v35
	v_add_f32_e32 v35, v28, v29
	v_cvt_pk_bf16_f32 v28, v38, v26
	v_ashrrev_i32_e32 v26, 7, v42
	v_mul_lo_u32 v26, v26, 48
	v_cvt_pk_bf16_f32 v29, v30, v27
	v_ashrrev_i32_e32 v27, 31, v26
	v_cvt_pk_bf16_f32 v30, v31, v32
	v_cvt_pk_bf16_f32 v31, v34, v33
	v_lshl_add_u64 v[32:33], v[26:27], 0, s[10:11]
	ds_bpermute_b32 v27, v119, v35
	v_add_u32_e32 v26, 0xc00, v90
	v_and_or_b32 v34, v26, s67, v117
	v_lshrrev_b32_e32 v26, 4, v26
	v_and_b32_e32 v26, 32, v26
	v_bitop3_b32 v98, v34, s55, v26 bitop3:0xde
	s_waitcnt lgkmcnt(0)
	v_add_f32_e32 v26, v35, v27
	v_mov_b32_e32 v27, v26
	s_nop 1
	v_permlane32_swap_b32_e32 v27, v26
	v_lshlrev_b64 v[32:33], 14, v[32:33]
	v_lshl_add_u64 v[32:33], s[44:45], 0, v[32:33]
	v_lshl_add_u64 v[32:33], v[32:33], 0, v[98:99]
	global_store_dwordx4 v[32:33], v[28:31], off
	s_and_saveexec_b64 s[6:7], s[8:9]
	s_cbranch_execz .LBB0_661
	s_waitcnt lgkmcnt(0)
	v_add_f32_e32 v26, v26, v27
	ds_write_b32 v141, v26

; __device__ __forceinline__ unsigned cvt_pk_bf16(float lo, float hi) { unsigned r; asm volatile("v_cvt_pk_bf16_f32 %0, %1, %2" : "=v"(r) : "v"(lo), "v"(hi)); return r; }
;     __device__ __forceinline__ void operator()(const f32x4 (&acc)[2][2][4][2], const pg8::Unit& u, int wr, int wc, int fr, int fq, const LAS float* tab) const {
;     ...
;                 const int row = row0 + ai * 128 + m * 16;
;                 bf16_t* rowp = (mode == 0) ? base + (size_t)(row >> 4) * 4096 + (size_t)(wc * 512 + (row & 15) * 32 + 8 * fq) : base + (size_t)row * ldc + col0;
;                 const int bjstep = (mode == 0) ? 4 * 512 : 128;
;                 float s1 = 0.f, s2 = 0.f;
;                 const float f2 = (kind == 4) ? tab[512 + ai * 128 + wr * 64 + m * 16 + fr] : 1.0f;
; #pragma unroll
;                 for (int bj = 0; bj < 2; ++bj) {
;                     f32x4 v0 = acc[ai][bj][m][0], v1 = acc[ai][bj][m][1];
;                     if (kind == 1) {
; #pragma unroll
;                         for (int e = 0; e < 4; ++e) { v0[e] = silu_f(v0[e]); v1[e] = silu_f(v1[e]); }
;                     } else if (kind == 2) { v0 = v0 * QSCALE; v1 = v1 * QSCALE; }
;                     else if (kind == 3) {
; #pragma unroll
;                         for (int e = 0; e < 4; ++e) { s1 += v0[e] + v1[e]; s2 += v0[e] * v0[e] + v1[e] * v1[e]; }
;                     } else if (kind == 4) {
;                         v0 = v0 * f2; v1 = v1 * f2;
; #pragma unroll
;                         for (int e = 0; e < 4; ++e) s2 += v0[e] * v0[e] + v1[e] * v1[e];
;                     }
;                     u32x4 w; w.x = cvt_pk_bf16(v0[0], v0[1]); w.y = cvt_pk_bf16(v0[2], v0[3]); w.z = cvt_pk_bf16(v1[0], v1[1]); w.w = cvt_pk_bf16(v1[2], v1[3]);
;                     *(u32x4*)(rowp + bj * bjstep) = w;
;                 }
;                 if (kind == 3) {
;                     s1 += __shfl_xor(s1, 16); s1 += __shfl_xor(s1, 32); s2 += __shfl_xor(s2, 16); s2 += __shfl_xor(s2, 32);
;                     if (fq == 0) { float* p = aux + (size_t)row * 32 + ((pn - 12) * 4 + wc) * 2; p[0] = s1; p[1] = s2; }
;                 } else if (kind == 4) {
;                     s2 += __shfl_xor(s2, 16); s2 += __shfl_xor(s2, 32);
;                     if (fq == 0) aux[(size_t)row * 32 + pn * 4 + wc] = s2;
.LBB0_761:
	ds_read_b32 v148, v158 offset:2048
	v_lshl_or_b32 v146, s14, 8, v153
	v_lshl_add_u32 v4, s70, 8, v1
	v_ashrrev_i32_e32 v147, 31, v146
	v_ashrrev_i32_e32 v5, 31, v4
	s_waitcnt lgkmcnt(0)
	v_pk_mul_f32 v[162:163], v[128:129], v[148:149] op_sel_hi:[1,0]
	v_pk_mul_f32 v[128:129], v[126:127], v[148:149] op_sel_hi:[1,0]
	v_pk_mul_f32 v[130:131], v[130:131], v[148:149] op_sel_hi:[1,0]
	v_mul_f32_e32 v3, v128, v128
	v_mul_f32_e32 v126, v129, v129
	v_fmac_f32_e32 v3, v130, v130
	v_fmac_f32_e32 v126, v131, v131
	v_pk_mul_f32 v[132:133], v[132:133], v[148:149] op_sel_hi:[1,0]
	v_add_f32_e32 v3, v3, v126
	v_mul_f32_e32 v126, v162, v162
	v_fmac_f32_e32 v126, v132, v132
	v_add_f32_e32 v3, v126, v3
	v_mul_f32_e32 v126, v163, v163
	v_fmac_f32_e32 v126, v133, v133
	v_add_f32_e32 v3, v126, v3
	v_cvt_pk_bf16_f32 v126, v130, v131
	v_cvt_pk_bf16_f32 v127, v132, v133
	v_pk_mul_f32 v[132:133], v[118:119], v[148:149] op_sel_hi:[1,0]
	v_pk_mul_f32 v[122:123], v[122:123], v[148:149] op_sel_hi:[1,0]
	v_mul_f32_e32 v118, v132, v132
	v_fmac_f32_e32 v118, v122, v122
	v_add_f32_e32 v3, v118, v3
	v_mul_f32_e32 v118, v133, v133
	v_pk_mul_f32 v[130:131], v[120:121], v[148:149] op_sel_hi:[1,0]
	v_fmac_f32_e32 v118, v123, v123
	v_pk_mul_f32 v[124:125], v[124:125], v[148:149] op_sel_hi:[1,0]
	v_add_f32_e32 v3, v118, v3
	v_mul_f32_e32 v118, v130, v130
	v_fmac_f32_e32 v118, v124, v124
	v_add_f32_e32 v3, v118, v3
	v_mul_f32_e32 v118, v131, v131
	v_fmac_f32_e32 v118, v125, v125
	v_and_b32_e32 v119, 64, v157
	v_add_f32_e32 v118, v118, v3
	v_xor_b32_e32 v3, 16, v157
	v_add_u32_e32 v119, 64, v119
	v_cmp_lt_i32_e32 vcc, v3, v119
	v_lshl_add_u64 v[146:147], v[146:147], 1, s[30:31]
	s_lshl_b32 s6, s14, 2
	v_cndmask_b32_e32 v3, v157, v3, vcc
	v_lshlrev_b32_e32 v3, 2, v3
	v_mov_b32_e32 v120, v118
	s_nop 1
	v_permlane16_swap_b32_e32 v120, v118
	v_lshlrev_b64 v[160:161], 12, v[4:5]
	s_ashr_i32 s7, s6, 31
	v_lshl_add_u64 v[160:161], v[146:147], 0, v[160:161]
	v_cvt_pk_bf16_f32 v128, v128, v129
	s_waitcnt lgkmcnt(0)
	v_add_f32_e32 v118, v118, v120
	v_xor_b32_e32 v120, 32, v157
	v_cmp_lt_i32_e32 vcc, v120, v119
	v_cvt_pk_bf16_f32 v129, v162, v163
	global_store_dwordx4 v[160:161], v[126:129], off
	v_cvt_pk_bf16_f32 v122, v122, v123
	v_cvt_pk_bf16_f32 v123, v124, v125
	v_cvt_pk_bf16_f32 v124, v132, v133
	s_nop 0
	v_cndmask_b32_e32 v119, v157, v120, vcc
	v_lshlrev_b32_e32 v120, 2, v119
	v_mov_b32_e32 v119, v118
	s_nop 1
	v_permlane32_swap_b32_e32 v119, v118
	v_cvt_pk_bf16_f32 v125, v130, v131
	global_store_dwordx4 v[160:161], v[122:125], off offset:256
	s_and_saveexec_b64 s[10:11], s[8:9]
	s_cbranch_execz .LBB0_763
	v_lshlrev_b64 v[122:123], 7, v[4:5]
	v_lshl_add_u64 v[122:123], s[12:13], 0, v[122:123]
	v_lshl_add_u64 v[122:123], s[6:7], 2, v[122:123]
	s_lshl_b32 s14, s59, 2
	v_lshl_add_u64 v[122:123], v[122:123], 0, s[14:15]
	s_waitcnt lgkmcnt(0)
	v_add_f32_e32 v5, v118, v119
	global_store_dword v[122:123], v5, off
.LBB0_763:
	s_or_b64 exec, exec, s[10:11]
	ds_read_b32 v122, v158 offset:2112
	v_or_b32_e32 v118, 16, v4
	s_waitcnt lgkmcnt(0)
	v_ashrrev_i32_e32 v119, 31, v118
	v_lshlrev_b64 v[124:125], 12, v[118:119]
	v_lshl_add_u64 v[124:125], v[146:147], 0, v[124:125]
	v_pk_mul_f32 v[126:127], v[112:113], v[122:123] op_sel_hi:[1,0]
	v_pk_mul_f32 v[112:113], v[110:111], v[122:123] op_sel_hi:[1,0]
	v_pk_mul_f32 v[114:115], v[114:115], v[122:123] op_sel_hi:[1,0]
	v_mul_f32_e32 v5, v112, v112
	v_mul_f32_e32 v110, v113, v113
	v_fmac_f32_e32 v5, v114, v114
	v_fmac_f32_e32 v110, v115, v115
	v_pk_mul_f32 v[116:117], v[116:117], v[122:123] op_sel_hi:[1,0]
	v_add_f32_e32 v5, v5, v110
	v_mul_f32_e32 v110, v126, v126
	v_fmac_f32_e32 v110, v116, v116
	v_add_f32_e32 v5, v110, v5
	v_mul_f32_e32 v110, v127, v127
	v_fmac_f32_e32 v110, v117, v117
	v_add_f32_e32 v5, v110, v5
	v_cvt_pk_bf16_f32 v110, v114, v115
	v_cvt_pk_bf16_f32 v111, v116, v117
	v_pk_mul_f32 v[116:117], v[102:103], v[122:123] op_sel_hi:[1,0]
	v_pk_mul_f32 v[106:107], v[106:107], v[122:123] op_sel_hi:[1,0]
	v_mul_f32_e32 v102, v116, v116
	v_fmac_f32_e32 v102, v106, v106
	v_add_f32_e32 v5, v102, v5
	v_mul_f32_e32 v102, v117, v117
	v_pk_mul_f32 v[114:115], v[104:105], v[122:123] op_sel_hi:[1,0]
	v_fmac_f32_e32 v102, v107, v107
	v_pk_mul_f32 v[108:109], v[108:109], v[122:123] op_sel_hi:[1,0]
	v_add_f32_e32 v5, v102, v5
	v_mul_f32_e32 v102, v114, v114
	v_fmac_f32_e32 v102, v108, v108
	v_add_f32_e32 v5, v102, v5
	v_mul_f32_e32 v102, v115, v115
	v_fmac_f32_e32 v102, v109, v109
	v_add_f32_e32 v5, v102, v5
	v_mov_b32_e32 v102, v5
	s_nop 1
	v_permlane16_swap_b32_e32 v102, v5
	v_cvt_pk_bf16_f32 v112, v112, v113
	v_cvt_pk_bf16_f32 v113, v126, v127
	global_store_dwordx4 v[124:125], v[110:113], off
	v_cvt_pk_bf16_f32 v104, v106, v107
	s_waitcnt lgkmcnt(0)
	v_add_f32_e32 v5, v5, v102
	v_mov_b32_e32 v102, v5
	s_nop 1
	v_permlane32_swap_b32_e32 v102, v5
	v_cvt_pk_bf16_f32 v105, v108, v109
	v_cvt_pk_bf16_f32 v106, v116, v117
	v_cvt_pk_bf16_f32 v107, v114, v115
	global_store_dwordx4 v[124:125], v[104:107], off offset:256
	s_and_saveexec_b64 s[10:11], s[8:9]
	s_cbranch_execz .LBB0_765
	v_lshlrev_b64 v[104:105], 7, v[118:119]
	v_lshl_add_u64 v[104:105], s[12:13], 0, v[104:105]
	v_lshl_add_u64 v[104:105], s[6:7], 2, v[104:105]
	s_lshl_b32 s14, s59, 2
	v_lshl_add_u64 v[104:105], v[104:105], 0, s[14:15]
	s_waitcnt lgkmcnt(0)
	v_add_f32_e32 v5, v5, v102
	global_store_dword v[104:105], v5, off
; __device__ __forceinline__ unsigned cvt_pk_bf16(float lo, float hi) { unsigned r; asm volatile("v_cvt_pk_bf16_f32 %0, %1, %2" : "=v"(r) : "v"(lo), "v"(hi)); return r; }
;     __device__ __forceinline__ void operator()(const f32x4 (&acc)[2][2][4][2], const pg8::Unit& u, int wr, int wc, int fr, int fq, const LAS float* tab) const {
;     ...
;                 const int row = row0 + ai * 128 + m * 16;
;                 bf16_t* rowp = (mode == 0) ? base + (size_t)(row >> 4) * 4096 + (size_t)(wc * 512 + (row & 15) * 32 + 8 * fq) : base + (size_t)row * ldc + col0;
;                 const int bjstep = (mode == 0) ? 4 * 512 : 128;
;                 float s1 = 0.f, s2 = 0.f;
;                 const float f2 = (kind == 4) ? tab[512 + ai * 128 + wr * 64 + m * 16 + fr] : 1.0f;
; #pragma unroll
;                 for (int bj = 0; bj < 2; ++bj) {
;                     f32x4 v0 = acc[ai][bj][m][0], v1 = acc[ai][bj][m][1];
;                     if (kind == 1) {
; #pragma unroll
;                         for (int e = 0; e < 4; ++e) { v0[e] = silu_f(v0[e]); v1[e] = silu_f(v1[e]); }
;                     } else if (kind == 2) { v0 = v0 * QSCALE; v1 = v1 * QSCALE; }
;                     else if (kind == 3) {
; #pragma unroll
;                         for (int e = 0; e < 4; ++e) { s1 += v0[e] + v1[e]; s2 += v0[e] * v0[e] + v1[e] * v1[e]; }
;                     } else if (kind == 4) {
;                         v0 = v0 * f2; v1 = v1 * f2;
; #pragma unroll
;                         for (int e = 0; e < 4; ++e) s2 += v0[e] * v0[e] + v1[e] * v1[e];
;                     }
;                     u32x4 w; w.x = cvt_pk_bf16(v0[0], v0[1]); w.y = cvt_pk_bf16(v0[2], v0[3]); w.z = cvt_pk_bf16(v1[0], v1[1]); w.w = cvt_pk_bf16(v1[2], v1[3]);
;                     *(u32x4*)(rowp + bj * bjstep) = w;
;                 }
;                 if (kind == 3) {
;                     s1 += __shfl_xor(s1, 16); s1 += __shfl_xor(s1, 32); s2 += __shfl_xor(s2, 16); s2 += __shfl_xor(s2, 32);
;                     if (fq == 0) { float* p = aux + (size_t)row * 32 + ((pn - 12) * 4 + wc) * 2; p[0] = s1; p[1] = s2; }
;                 } else if (kind == 4) {
;                     s2 += __shfl_xor(s2, 16); s2 += __shfl_xor(s2, 32);
;                     if (fq == 0) aux[(size_t)row * 32 + pn * 4 + wc] = s2;
.LBB0_765:
	s_or_b64 exec, exec, s[10:11]
	ds_read_b32 v104, v158 offset:2176
	s_waitcnt lgkmcnt(0)
	v_or_b32_e32 v102, 32, v4
	v_ashrrev_i32_e32 v103, 31, v102
	v_lshlrev_b64 v[106:107], 12, v[102:103]
	v_lshl_add_u64 v[106:107], v[146:147], 0, v[106:107]
	v_pk_mul_f32 v[108:109], v[96:97], v[104:105] op_sel_hi:[1,0]
	v_pk_mul_f32 v[96:97], v[94:95], v[104:105] op_sel_hi:[1,0]
	v_pk_mul_f32 v[98:99], v[98:99], v[104:105] op_sel_hi:[1,0]
	v_mul_f32_e32 v5, v96, v96
	v_mul_f32_e32 v94, v97, v97
	v_fmac_f32_e32 v5, v98, v98
	v_fmac_f32_e32 v94, v99, v99
	v_pk_mul_f32 v[100:101], v[100:101], v[104:105] op_sel_hi:[1,0]
	v_add_f32_e32 v5, v5, v94
	v_mul_f32_e32 v94, v108, v108
	v_fmac_f32_e32 v94, v100, v100
	v_add_f32_e32 v5, v94, v5
	v_mul_f32_e32 v94, v109, v109
	v_fmac_f32_e32 v94, v101, v101
	v_add_f32_e32 v5, v94, v5
	v_cvt_pk_bf16_f32 v94, v98, v99
	v_cvt_pk_bf16_f32 v95, v100, v101
	v_pk_mul_f32 v[100:101], v[86:87], v[104:105] op_sel_hi:[1,0]
	v_pk_mul_f32 v[90:91], v[90:91], v[104:105] op_sel_hi:[1,0]
	v_mul_f32_e32 v86, v100, v100
	v_fmac_f32_e32 v86, v90, v90
	v_add_f32_e32 v5, v86, v5
	v_mul_f32_e32 v86, v101, v101
	v_pk_mul_f32 v[98:99], v[88:89], v[104:105] op_sel_hi:[1,0]
	v_fmac_f32_e32 v86, v91, v91
	v_pk_mul_f32 v[92:93], v[92:93], v[104:105] op_sel_hi:[1,0]
	v_add_f32_e32 v5, v86, v5
	v_mul_f32_e32 v86, v98, v98
	v_fmac_f32_e32 v86, v92, v92
	v_add_f32_e32 v5, v86, v5
	v_mul_f32_e32 v86, v99, v99
	v_fmac_f32_e32 v86, v93, v93
	v_add_f32_e32 v5, v86, v5
	v_mov_b32_e32 v86, v5
	s_nop 1
	v_permlane16_swap_b32_e32 v86, v5
	v_cvt_pk_bf16_f32 v96, v96, v97
	v_cvt_pk_bf16_f32 v97, v108, v109
	global_store_dwordx4 v[106:107], v[94:97], off
	v_cvt_pk_bf16_f32 v88, v90, v91
	s_waitcnt lgkmcnt(0)
	v_add_f32_e32 v5, v5, v86
	v_mov_b32_e32 v86, v5
	s_nop 1
	v_permlane32_swap_b32_e32 v86, v5
	v_cvt_pk_bf16_f32 v89, v92, v93
	v_cvt_pk_bf16_f32 v90, v100, v101
	v_cvt_pk_bf16_f32 v91, v98, v99
	global_store_dwordx4 v[106:107], v[88:91], off offset:256
	s_and_saveexec_b64 s[10:11], s[8:9]
	s_cbranch_execz .LBB0_767
	v_lshlrev_b64 v[88:89], 7, v[102:103]
	v_lshl_add_u64 v[88:89], s[12:13], 0, v[88:89]
	v_lshl_add_u64 v[88:89], s[6:7], 2, v[88:89]
	s_lshl_b32 s14, s59, 2
	v_lshl_add_u64 v[88:89], v[88:89], 0, s[14:15]
	s_waitcnt lgkmcnt(0)
	v_add_f32_e32 v5, v5, v86
	global_store_dword v[88:89], v5, off
.LBB0_767:
	s_or_b64 exec, exec, s[10:11]
	ds_read_b32 v88, v158 offset:2240
	s_waitcnt lgkmcnt(0)
	v_or_b32_e32 v86, 48, v4
	v_ashrrev_i32_e32 v87, 31, v86
	v_lshlrev_b64 v[90:91], 12, v[86:87]
	v_lshl_add_u64 v[90:91], v[146:147], 0, v[90:91]
	v_pk_mul_f32 v[92:93], v[80:81], v[88:89] op_sel_hi:[1,0]
	v_pk_mul_f32 v[80:81], v[78:79], v[88:89] op_sel_hi:[1,0]
	v_pk_mul_f32 v[82:83], v[82:83], v[88:89] op_sel_hi:[1,0]
	v_mul_f32_e32 v5, v80, v80
	v_mul_f32_e32 v78, v81, v81
	v_fmac_f32_e32 v5, v82, v82
	v_fmac_f32_e32 v78, v83, v83
	v_pk_mul_f32 v[84:85], v[84:85], v[88:89] op_sel_hi:[1,0]
	v_add_f32_e32 v5, v5, v78
	v_mul_f32_e32 v78, v92, v92
	v_fmac_f32_e32 v78, v84, v84
	v_add_f32_e32 v5, v78, v5
	v_mul_f32_e32 v78, v93, v93
	v_fmac_f32_e32 v78, v85, v85
	v_add_f32_e32 v5, v78, v5
	v_cvt_pk_bf16_f32 v78, v82, v83
	v_cvt_pk_bf16_f32 v79, v84, v85
	v_pk_mul_f32 v[84:85], v[70:71], v[88:89] op_sel_hi:[1,0]
	v_pk_mul_f32 v[74:75], v[74:75], v[88:89] op_sel_hi:[1,0]
	v_mul_f32_e32 v70, v84, v84
	v_fmac_f32_e32 v70, v74, v74
	v_add_f32_e32 v5, v70, v5
	v_mul_f32_e32 v70, v85, v85
	v_pk_mul_f32 v[82:83], v[72:73], v[88:89] op_sel_hi:[1,0]
	v_fmac_f32_e32 v70, v75, v75
	v_pk_mul_f32 v[76:77], v[76:77], v[88:89] op_sel_hi:[1,0]
	v_add_f32_e32 v5, v70, v5
	v_mul_f32_e32 v70, v82, v82
	v_fmac_f32_e32 v70, v76, v76
	v_add_f32_e32 v5, v70, v5
	v_mul_f32_e32 v70, v83, v83
	v_fmac_f32_e32 v70, v77, v77
	v_add_f32_e32 v5, v70, v5
	v_mov_b32_e32 v70, v5
	s_nop 1
	v_permlane16_swap_b32_e32 v70, v5
	v_cvt_pk_bf16_f32 v80, v80, v81
	v_cvt_pk_bf16_f32 v81, v92, v93
	global_store_dwordx4 v[90:91], v[78:81], off
	v_cvt_pk_bf16_f32 v72, v74, v75
	s_waitcnt lgkmcnt(0)
	v_add_f32_e32 v5, v5, v70
	v_mov_b32_e32 v70, v5
	s_nop 1
	v_permlane32_swap_b32_e32 v70, v5
	v_cvt_pk_bf16_f32 v73, v76, v77
	v_cvt_pk_bf16_f32 v74, v84, v85
	v_cvt_pk_bf16_f32 v75, v82, v83
	global_store_dwordx4 v[90:91], v[72:75], off offset:256
	s_and_saveexec_b64 s[10:11], s[8:9]
	s_cbranch_execz .LBB0_769
	v_lshlrev_b64 v[72:73], 7, v[86:87]
	v_lshl_add_u64 v[72:73], s[12:13], 0, v[72:73]
	v_lshl_add_u64 v[72:73], s[6:7], 2, v[72:73]
	s_lshl_b32 s14, s59, 2
	v_lshl_add_u64 v[72:73], v[72:73], 0, s[14:15]
	s_waitcnt lgkmcnt(0)
	v_add_f32_e32 v5, v5, v70
	global_store_dword v[72:73], v5, off
; __device__ __forceinline__ unsigned cvt_pk_bf16(float lo, float hi) { unsigned r; asm volatile("v_cvt_pk_bf16_f32 %0, %1, %2" : "=v"(r) : "v"(lo), "v"(hi)); return r; }
;     __device__ __forceinline__ void operator()(const f32x4 (&acc)[2][2][4][2], const pg8::Unit& u, int wr, int wc, int fr, int fq, const LAS float* tab) const {
;     ...
;                 const int row = row0 + ai * 128 + m * 16;
;                 bf16_t* rowp = (mode == 0) ? base + (size_t)(row >> 4) * 4096 + (size_t)(wc * 512 + (row & 15) * 32 + 8 * fq) : base + (size_t)row * ldc + col0;
;                 const int bjstep = (mode == 0) ? 4 * 512 : 128;
;                 float s1 = 0.f, s2 = 0.f;
;                 const float f2 = (kind == 4) ? tab[512 + ai * 128 + wr * 64 + m * 16 + fr] : 1.0f;
; #pragma unroll
;                 for (int bj = 0; bj < 2; ++bj) {
;                     f32x4 v0 = acc[ai][bj][m][0], v1 = acc[ai][bj][m][1];
;                     if (kind == 1) {
; #pragma unroll
;                         for (int e = 0; e < 4; ++e) { v0[e] = silu_f(v0[e]); v1[e] = silu_f(v1[e]); }
;                     } else if (kind == 2) { v0 = v0 * QSCALE; v1 = v1 * QSCALE; }
;                     else if (kind == 3) {
; #pragma unroll
;                         for (int e = 0; e < 4; ++e) { s1 += v0[e] + v1[e]; s2 += v0[e] * v0[e] + v1[e] * v1[e]; }
;                     } else if (kind == 4) {
;                         v0 = v0 * f2; v1 = v1 * f2;
; #pragma unroll
;                         for (int e = 0; e < 4; ++e) s2 += v0[e] * v0[e] + v1[e] * v1[e];
;                     }
;                     u32x4 w; w.x = cvt_pk_bf16(v0[0], v0[1]); w.y = cvt_pk_bf16(v0[2], v0[3]); w.z = cvt_pk_bf16(v1[0], v1[1]); w.w = cvt_pk_bf16(v1[2], v1[3]);
;                     *(u32x4*)(rowp + bj * bjstep) = w;
;                 }
;                 if (kind == 3) {
;                     s1 += __shfl_xor(s1, 16); s1 += __shfl_xor(s1, 32); s2 += __shfl_xor(s2, 16); s2 += __shfl_xor(s2, 32);
;                     if (fq == 0) { float* p = aux + (size_t)row * 32 + ((pn - 12) * 4 + wc) * 2; p[0] = s1; p[1] = s2; }
;                 } else if (kind == 4) {
;                     s2 += __shfl_xor(s2, 16); s2 += __shfl_xor(s2, 32);
;                     if (fq == 0) aux[(size_t)row * 32 + pn * 4 + wc] = s2;
.LBB0_769:
	s_or_b64 exec, exec, s[10:11]
	ds_read_b32 v72, v158 offset:2560
	s_waitcnt lgkmcnt(0)
	v_add_u32_e32 v70, 0x80, v4
	v_ashrrev_i32_e32 v71, 31, v70
	v_lshlrev_b64 v[74:75], 12, v[70:71]
	v_lshl_add_u64 v[74:75], v[146:147], 0, v[74:75]
	v_pk_mul_f32 v[76:77], v[64:65], v[72:73] op_sel_hi:[1,0]
	v_pk_mul_f32 v[64:65], v[62:63], v[72:73] op_sel_hi:[1,0]
	v_pk_mul_f32 v[66:67], v[66:67], v[72:73] op_sel_hi:[1,0]
	v_mul_f32_e32 v5, v64, v64
	v_mul_f32_e32 v62, v65, v65
	v_fmac_f32_e32 v5, v66, v66
	v_fmac_f32_e32 v62, v67, v67
	v_pk_mul_f32 v[68:69], v[68:69], v[72:73] op_sel_hi:[1,0]
	v_add_f32_e32 v5, v5, v62
	v_mul_f32_e32 v62, v76, v76
	v_fmac_f32_e32 v62, v68, v68
	v_add_f32_e32 v5, v62, v5
	v_mul_f32_e32 v62, v77, v77
	v_fmac_f32_e32 v62, v69, v69
	v_add_f32_e32 v5, v62, v5
	v_cvt_pk_bf16_f32 v62, v66, v67
	v_cvt_pk_bf16_f32 v63, v68, v69
	v_pk_mul_f32 v[68:69], v[54:55], v[72:73] op_sel_hi:[1,0]
	v_pk_mul_f32 v[58:59], v[58:59], v[72:73] op_sel_hi:[1,0]
	v_mul_f32_e32 v54, v68, v68
	v_fmac_f32_e32 v54, v58, v58
	v_add_f32_e32 v5, v54, v5
	v_mul_f32_e32 v54, v69, v69
	v_pk_mul_f32 v[66:67], v[56:57], v[72:73] op_sel_hi:[1,0]
	v_fmac_f32_e32 v54, v59, v59
	v_pk_mul_f32 v[60:61], v[60:61], v[72:73] op_sel_hi:[1,0]
	v_add_f32_e32 v5, v54, v5
	v_mul_f32_e32 v54, v66, v66
	v_fmac_f32_e32 v54, v60, v60
	v_add_f32_e32 v5, v54, v5
	v_mul_f32_e32 v54, v67, v67
	v_fmac_f32_e32 v54, v61, v61
	v_add_f32_e32 v5, v54, v5
	v_mov_b32_e32 v54, v5
	s_nop 1
	v_permlane16_swap_b32_e32 v54, v5
	v_cvt_pk_bf16_f32 v64, v64, v65
	v_cvt_pk_bf16_f32 v65, v76, v77
	global_store_dwordx4 v[74:75], v[62:65], off
	v_cvt_pk_bf16_f32 v56, v58, v59
	s_waitcnt lgkmcnt(0)
	v_add_f32_e32 v5, v5, v54
	v_mov_b32_e32 v54, v5
	s_nop 1
	v_permlane32_swap_b32_e32 v54, v5
	v_cvt_pk_bf16_f32 v57, v60, v61
	v_cvt_pk_bf16_f32 v58, v68, v69
	v_cvt_pk_bf16_f32 v59, v66, v67
	global_store_dwordx4 v[74:75], v[56:59], off offset:256
	s_and_saveexec_b64 s[10:11], s[8:9]
	s_cbranch_execz .LBB0_771
	v_lshlrev_b64 v[56:57], 7, v[70:71]
	v_lshl_add_u64 v[56:57], s[12:13], 0, v[56:57]
	v_lshl_add_u64 v[56:57], s[6:7], 2, v[56:57]
	s_lshl_b32 s14, s59, 2
	v_lshl_add_u64 v[56:57], v[56:57], 0, s[14:15]
	s_waitcnt lgkmcnt(0)
	v_add_f32_e32 v5, v5, v54
	global_store_dword v[56:57], v5, off
.LBB0_771:
	s_or_b64 exec, exec, s[10:11]
	ds_read_b32 v56, v158 offset:2624
	s_waitcnt lgkmcnt(0)
	v_add_u32_e32 v54, 0x90, v4
	v_ashrrev_i32_e32 v55, 31, v54
	v_lshlrev_b64 v[58:59], 12, v[54:55]
	v_lshl_add_u64 v[58:59], v[146:147], 0, v[58:59]
	v_pk_mul_f32 v[60:61], v[48:49], v[56:57] op_sel_hi:[1,0]
	v_pk_mul_f32 v[48:49], v[46:47], v[56:57] op_sel_hi:[1,0]
	v_pk_mul_f32 v[50:51], v[50:51], v[56:57] op_sel_hi:[1,0]
	v_mul_f32_e32 v5, v48, v48
	v_mul_f32_e32 v46, v49, v49
	v_fmac_f32_e32 v5, v50, v50
	v_fmac_f32_e32 v46, v51, v51
	v_pk_mul_f32 v[52:53], v[52:53], v[56:57] op_sel_hi:[1,0]
	v_add_f32_e32 v5, v5, v46
	v_mul_f32_e32 v46, v60, v60
	v_fmac_f32_e32 v46, v52, v52
	v_add_f32_e32 v5, v46, v5
	v_mul_f32_e32 v46, v61, v61
	v_fmac_f32_e32 v46, v53, v53
	v_add_f32_e32 v5, v46, v5
	v_cvt_pk_bf16_f32 v46, v50, v51
	v_cvt_pk_bf16_f32 v47, v52, v53
	v_pk_mul_f32 v[52:53], v[38:39], v[56:57] op_sel_hi:[1,0]
	v_pk_mul_f32 v[42:43], v[42:43], v[56:57] op_sel_hi:[1,0]
	v_mul_f32_e32 v38, v52, v52
	v_fmac_f32_e32 v38, v42, v42
	v_add_f32_e32 v5, v38, v5
	v_mul_f32_e32 v38, v53, v53
	v_pk_mul_f32 v[50:51], v[40:41], v[56:57] op_sel_hi:[1,0]
	v_fmac_f32_e32 v38, v43, v43
	v_pk_mul_f32 v[44:45], v[44:45], v[56:57] op_sel_hi:[1,0]
	v_add_f32_e32 v5, v38, v5
	v_mul_f32_e32 v38, v50, v50
	v_fmac_f32_e32 v38, v44, v44
	v_add_f32_e32 v5, v38, v5
	v_mul_f32_e32 v38, v51, v51
	v_fmac_f32_e32 v38, v45, v45
	v_add_f32_e32 v5, v38, v5
	v_mov_b32_e32 v38, v5
	s_nop 1
	v_permlane16_swap_b32_e32 v38, v5
	v_cvt_pk_bf16_f32 v48, v48, v49
	v_cvt_pk_bf16_f32 v49, v60, v61
	global_store_dwordx4 v[58:59], v[46:49], off
	v_cvt_pk_bf16_f32 v40, v42, v43
	s_waitcnt lgkmcnt(0)
	v_add_f32_e32 v5, v5, v38
	v_mov_b32_e32 v38, v5
	s_nop 1
	v_permlane32_swap_b32_e32 v38, v5
	v_cvt_pk_bf16_f32 v41, v44, v45
	v_cvt_pk_bf16_f32 v42, v52, v53
	v_cvt_pk_bf16_f32 v43, v50, v51
	global_store_dwordx4 v[58:59], v[40:43], off offset:256
	s_and_saveexec_b64 s[10:11], s[8:9]
	s_cbranch_execz .LBB0_773
	v_lshlrev_b64 v[40:41], 7, v[54:55]
	v_lshl_add_u64 v[40:41], s[12:13], 0, v[40:41]
	v_lshl_add_u64 v[40:41], s[6:7], 2, v[40:41]
	s_lshl_b32 s14, s59, 2
	v_lshl_add_u64 v[40:41], v[40:41], 0, s[14:15]
	s_waitcnt lgkmcnt(0)
	v_add_f32_e32 v5, v5, v38
	global_store_dword v[40:41], v5, off
; __device__ __forceinline__ unsigned cvt_pk_bf16(float lo, float hi) { unsigned r; asm volatile("v_cvt_pk_bf16_f32 %0, %1, %2" : "=v"(r) : "v"(lo), "v"(hi)); return r; }
;     __device__ __forceinline__ void operator()(const f32x4 (&acc)[2][2][4][2], const pg8::Unit& u, int wr, int wc, int fr, int fq, const LAS float* tab) const {
;     ...
;                 const int row = row0 + ai * 128 + m * 16;
;                 bf16_t* rowp = (mode == 0) ? base + (size_t)(row >> 4) * 4096 + (size_t)(wc * 512 + (row & 15) * 32 + 8 * fq) : base + (size_t)row * ldc + col0;
;                 const int bjstep = (mode == 0) ? 4 * 512 : 128;
;                 float s1 = 0.f, s2 = 0.f;
;                 const float f2 = (kind == 4) ? tab[512 + ai * 128 + wr * 64 + m * 16 + fr] : 1.0f;
; #pragma unroll
;                 for (int bj = 0; bj < 2; ++bj) {
;                     f32x4 v0 = acc[ai][bj][m][0], v1 = acc[ai][bj][m][1];
;                     if (kind == 1) {
; #pragma unroll
;                         for (int e = 0; e < 4; ++e) { v0[e] = silu_f(v0[e]); v1[e] = silu_f(v1[e]); }
;                     } else if (kind == 2) { v0 = v0 * QSCALE; v1 = v1 * QSCALE; }
;                     else if (kind == 3) {
; #pragma unroll
;                         for (int e = 0; e < 4; ++e) { s1 += v0[e] + v1[e]; s2 += v0[e] * v0[e] + v1[e] * v1[e]; }
;                     } else if (kind == 4) {
;                         v0 = v0 * f2; v1 = v1 * f2;
; #pragma unroll
;                         for (int e = 0; e < 4; ++e) s2 += v0[e] * v0[e] + v1[e] * v1[e];
;                     }
;                     u32x4 w; w.x = cvt_pk_bf16(v0[0], v0[1]); w.y = cvt_pk_bf16(v0[2], v0[3]); w.z = cvt_pk_bf16(v1[0], v1[1]); w.w = cvt_pk_bf16(v1[2], v1[3]);
;                     *(u32x4*)(rowp + bj * bjstep) = w;
;                 }
;                 if (kind == 3) {
;                     s1 += __shfl_xor(s1, 16); s1 += __shfl_xor(s1, 32); s2 += __shfl_xor(s2, 16); s2 += __shfl_xor(s2, 32);
;                     if (fq == 0) { float* p = aux + (size_t)row * 32 + ((pn - 12) * 4 + wc) * 2; p[0] = s1; p[1] = s2; }
;                 } else if (kind == 4) {
;                     s2 += __shfl_xor(s2, 16); s2 += __shfl_xor(s2, 32);
;                     if (fq == 0) aux[(size_t)row * 32 + pn * 4 + wc] = s2;
.LBB0_773:
	s_or_b64 exec, exec, s[10:11]
	ds_read_b32 v40, v158 offset:2688
	s_waitcnt lgkmcnt(0)
	v_add_u32_e32 v38, 0xa0, v4
	v_ashrrev_i32_e32 v39, 31, v38
	v_lshlrev_b64 v[42:43], 12, v[38:39]
	v_lshl_add_u64 v[42:43], v[146:147], 0, v[42:43]
	v_pk_mul_f32 v[44:45], v[32:33], v[40:41] op_sel_hi:[1,0]
	v_pk_mul_f32 v[32:33], v[30:31], v[40:41] op_sel_hi:[1,0]
	v_pk_mul_f32 v[34:35], v[34:35], v[40:41] op_sel_hi:[1,0]
	v_mul_f32_e32 v5, v32, v32
	v_mul_f32_e32 v30, v33, v33
	v_fmac_f32_e32 v5, v34, v34
	v_fmac_f32_e32 v30, v35, v35
	v_pk_mul_f32 v[36:37], v[36:37], v[40:41] op_sel_hi:[1,0]
	v_add_f32_e32 v5, v5, v30
	v_mul_f32_e32 v30, v44, v44
	v_fmac_f32_e32 v30, v36, v36
	v_add_f32_e32 v5, v30, v5
	v_mul_f32_e32 v30, v45, v45
	v_fmac_f32_e32 v30, v37, v37
	v_add_f32_e32 v5, v30, v5
	v_cvt_pk_bf16_f32 v30, v34, v35
	v_cvt_pk_bf16_f32 v31, v36, v37
	v_pk_mul_f32 v[36:37], v[22:23], v[40:41] op_sel_hi:[1,0]
	v_pk_mul_f32 v[26:27], v[26:27], v[40:41] op_sel_hi:[1,0]
	v_mul_f32_e32 v22, v36, v36
	v_fmac_f32_e32 v22, v26, v26
	v_add_f32_e32 v5, v22, v5
	v_mul_f32_e32 v22, v37, v37
	v_pk_mul_f32 v[34:35], v[24:25], v[40:41] op_sel_hi:[1,0]
	v_fmac_f32_e32 v22, v27, v27
	v_pk_mul_f32 v[28:29], v[28:29], v[40:41] op_sel_hi:[1,0]
	v_add_f32_e32 v5, v22, v5
	v_mul_f32_e32 v22, v34, v34
	v_fmac_f32_e32 v22, v28, v28
	v_add_f32_e32 v5, v22, v5
	v_mul_f32_e32 v22, v35, v35
	v_fmac_f32_e32 v22, v29, v29
	v_add_f32_e32 v5, v22, v5
	v_mov_b32_e32 v22, v5
	s_nop 1
	v_permlane16_swap_b32_e32 v22, v5
	v_cvt_pk_bf16_f32 v32, v32, v33
	v_cvt_pk_bf16_f32 v33, v44, v45
	global_store_dwordx4 v[42:43], v[30:33], off
	v_cvt_pk_bf16_f32 v24, v26, v27
	s_waitcnt lgkmcnt(0)
	v_add_f32_e32 v5, v5, v22
	v_mov_b32_e32 v22, v5
	s_nop 1
	v_permlane32_swap_b32_e32 v22, v5
	v_cvt_pk_bf16_f32 v25, v28, v29
	v_cvt_pk_bf16_f32 v26, v36, v37
	v_cvt_pk_bf16_f32 v27, v34, v35
	global_store_dwordx4 v[42:43], v[24:27], off offset:256
	s_and_saveexec_b64 s[10:11], s[8:9]
	s_cbranch_execz .LBB0_775
	v_lshlrev_b64 v[24:25], 7, v[38:39]
	v_lshl_add_u64 v[24:25], s[12:13], 0, v[24:25]
	v_lshl_add_u64 v[24:25], s[6:7], 2, v[24:25]
	s_lshl_b32 s14, s59, 2
	v_lshl_add_u64 v[24:25], v[24:25], 0, s[14:15]
	s_waitcnt lgkmcnt(0)
	v_add_f32_e32 v5, v5, v22
	global_store_dword v[24:25], v5, off
.LBB0_775:
	s_or_b64 exec, exec, s[10:11]
	s_waitcnt lgkmcnt(0)
	ds_read_b32 v22, v158 offset:2752
	v_add_u32_e32 v4, 0xb0, v4
	v_ashrrev_i32_e32 v5, 31, v4
	v_lshlrev_b64 v[24:25], 12, v[4:5]
	v_lshl_add_u64 v[24:25], v[146:147], 0, v[24:25]
	s_waitcnt lgkmcnt(0)
	v_pk_mul_f32 v[26:27], v[16:17], v[22:23] op_sel_hi:[1,0]
	v_pk_mul_f32 v[16:17], v[14:15], v[22:23] op_sel_hi:[1,0]
	v_pk_mul_f32 v[18:19], v[18:19], v[22:23] op_sel_hi:[1,0]
	v_mul_f32_e32 v14, v16, v16
	v_mul_f32_e32 v15, v17, v17
	v_fmac_f32_e32 v14, v18, v18
	v_fmac_f32_e32 v15, v19, v19
	v_pk_mul_f32 v[20:21], v[20:21], v[22:23] op_sel_hi:[1,0]
	v_add_f32_e32 v14, v14, v15
	v_mul_f32_e32 v15, v26, v26
	v_fmac_f32_e32 v15, v20, v20
	v_add_f32_e32 v14, v15, v14
	v_mul_f32_e32 v15, v27, v27
	v_fmac_f32_e32 v15, v21, v21
	v_add_f32_e32 v23, v15, v14
	v_cvt_pk_bf16_f32 v14, v18, v19
	v_cvt_pk_bf16_f32 v15, v20, v21
	v_pk_mul_f32 v[20:21], v[6:7], v[22:23] op_sel_hi:[1,0]
	v_pk_mul_f32 v[10:11], v[10:11], v[22:23] op_sel_hi:[1,0]
	v_mul_f32_e32 v6, v20, v20
	v_fmac_f32_e32 v6, v10, v10
	v_mul_f32_e32 v7, v21, v21
	v_pk_mul_f32 v[18:19], v[8:9], v[22:23] op_sel_hi:[1,0]
	v_add_f32_e32 v6, v6, v23
	v_fmac_f32_e32 v7, v11, v11
	v_pk_mul_f32 v[12:13], v[12:13], v[22:23] op_sel_hi:[1,0]
	v_add_f32_e32 v6, v7, v6
	v_mul_f32_e32 v7, v18, v18
	v_fmac_f32_e32 v7, v12, v12
	v_add_f32_e32 v6, v7, v6
	v_mul_f32_e32 v7, v19, v19
	v_fmac_f32_e32 v7, v13, v13
	v_add_f32_e32 v6, v7, v6
	ds_bpermute_b32 v3, v3, v6
	v_cvt_pk_bf16_f32 v16, v16, v17
	v_cvt_pk_bf16_f32 v17, v26, v27
	global_store_dwordx4 v[24:25], v[14:17], off
	v_cvt_pk_bf16_f32 v8, v10, v11
	s_waitcnt lgkmcnt(0)
	v_add_f32_e32 v3, v6, v3
	v_mov_b32_e32 v6, v3
	s_nop 1
	v_permlane32_swap_b32_e32 v6, v3
	v_cvt_pk_bf16_f32 v9, v12, v13
	v_cvt_pk_bf16_f32 v10, v20, v21
	v_cvt_pk_bf16_f32 v11, v18, v19
	global_store_dwordx4 v[24:25], v[8:11], off offset:256
	s_and_saveexec_b64 s[10:11], s[8:9]
	s_cbranch_execz .LBB0_777
	v_lshlrev_b64 v[4:5], 7, v[4:5]
	v_lshl_add_u64 v[4:5], s[12:13], 0, v[4:5]
	v_lshl_add_u64 v[4:5], s[6:7], 2, v[4:5]
	s_lshl_b32 s14, s59, 2
	v_lshl_add_u64 v[4:5], v[4:5], 0, s[14:15]
	s_waitcnt lgkmcnt(0)
	v_add_f32_e32 v3, v3, v6
	global_store_dword v[4:5], v3, off

; __device__ __forceinline__ float bf_lo(unsigned u) { return __uint_as_float(u << 16); }
; __device__ __forceinline__ float bf_hi(unsigned u) { return __uint_as_float(u & 0xffff0000u); }
; __device__ __forceinline__ float wave_sum(float v) {
; #pragma unroll
;     for (int o = 1; o < 64; o <<= 1) v += __shfl_xor(v, o);
;     return v;
; __global__ void __launch_bounds__(NTHR, 2) mk_fwd(Args a) {
;     ...
;             for (int r = 0; r < 2; ++r) { const int m = m0 + r * NGW; const bool ok = m < NTOK; const int mm = ok ? m : m0;
;                 part[r] = (lane < 32) ? OSS[(size_t)mm * 32 + lane] : 0.f;
;                 const f32x4* xr = (const f32x4*)(x + (size_t)mm * DMODEL) + lane; const u32x2* ob = (const u32x2*)(OutB + (size_t)mm * DMODEL) + lane;
; #pragma unroll
;                 for (int j = 0; j < 8; ++j) { xv[r][j] = __builtin_nontemporal_load(xr + 64 * j); ov[r][j] = __builtin_nontemporal_load(ob + 64 * j); } }
; #pragma unroll
;             for (int r = 0; r < 2; ++r) { const int m = m0 + r * NGW;
;                 const float rs = 1.0f / sqrtf(wave_sum(part[r]) * (1.0f / DMODEL) + EPS);
;                 if (m < NTOK) { f32x4* orow = (f32x4*)(a.out + (size_t)m * DMODEL) + lane;
; #pragma unroll
;                     for (int j = 0; j < 8; ++j) { const f32x4 xx = xv[r][j], g4 = gv[j]; const u32x2 o = ov[r][j];
;                         f32x4 res; res[0] = xx[0] + bf_lo(o.x) * rs * g4[0]; res[1] = xx[1] + bf_hi(o.x) * rs * g4[1]; res[2] = xx[2] + bf_lo(o.y) * rs * g4[2]; res[3] = xx[3] + bf_hi(o.y) * rs * g4[3];
;                         __builtin_nontemporal_store(res, orow + 64 * j); } } }
.LBB0_844:
	s_or_b64 exec, exec, s[12:13]
	s_waitcnt vmcnt(16)
	ds_bpermute_b32 v33, v136, v32
	s_lshl_b64 s[12:13], s[2:3], 13
	s_lshl_b64 s[2:3], s[2:3], 12
	v_lshl_add_u64 v[104:105], v[98:99], 0, s[2:3]
	s_waitcnt vmcnt(11)
	v_and_b32_e32 v151, 0xffff0000, v134
	s_waitcnt lgkmcnt(0)
	v_add_f32_e32 v32, v32, v33
	ds_bpermute_b32 v33, v137, v32
	s_waitcnt lgkmcnt(0)
	v_add_f32_e32 v34, v32, v33
	ds_bpermute_b32 v35, v138, v34
	v_lshl_add_u64 v[32:33], v[96:97], 0, s[12:13]
	global_load_dwordx4 v[64:67], v[32:33], off nt
	global_load_dwordx4 v[56:59], v[32:33], off offset:1024 nt
	global_load_dwordx4 v[52:55], v[32:33], off offset:2048 nt
	global_load_dwordx4 v[44:47], v[32:33], off offset:3072 nt
	v_add_co_u32_e32 v32, vcc, 0x1000, v32
	s_waitcnt lgkmcnt(0)
	v_add_f32_e32 v34, v34, v35
	ds_bpermute_b32 v35, v139, v34
	v_addc_co_u32_e32 v33, vcc, 0, v33, vcc
	global_load_dwordx2 v[120:121], v[104:105], off nt
	global_load_dwordx2 v[116:117], v[104:105], off offset:512 nt
	global_load_dwordx2 v[114:115], v[104:105], off offset:1024 nt
	global_load_dwordx2 v[110:111], v[104:105], off offset:1536 nt
	s_waitcnt lgkmcnt(0)
	v_add_f32_e32 v34, v34, v35
	v_mov_b32_e32 v35, v34
	s_nop 1
	v_permlane16_swap_b32_e32 v35, v34
	s_waitcnt lgkmcnt(0)
	v_add_f32_e32 v34, v34, v35
	v_mov_b32_e32 v35, v34
	s_nop 1
	v_permlane32_swap_b32_e32 v35, v34
	s_waitcnt lgkmcnt(0)
	v_add_f32_e32 v34, v34, v35
	v_fmamk_f32 v34, v34, 0x3a000000, v142
	v_mul_f32_e32 v35, 0x4f800000, v34
	v_cmp_gt_f32_e32 vcc, s17, v34
	s_nop 1
	v_cndmask_b32_e32 v106, v34, v35, vcc
	v_sqrt_f32_e32 v107, v106
	global_load_dwordx4 v[48:51], v[32:33], off nt
	global_load_dwordx4 v[40:43], v[32:33], off offset:1024 nt
	global_load_dwordx4 v[36:39], v[32:33], off offset:2048 nt
	s_nop 0
	global_load_dwordx4 v[32:35], v[32:33], off offset:3072 nt
	v_add_u32_e32 v108, -1, v107
	v_add_u32_e32 v109, 1, v107
	v_fma_f32 v112, -v108, v107, v106
	v_fma_f32 v113, -v109, v107, v106
	v_cmp_ge_f32_e64 s[2:3], 0, v112
	s_nop 1
	v_cndmask_b32_e64 v107, v107, v108, s[2:3]
	v_cmp_lt_f32_e64 s[2:3], 0, v113
	s_nop 1
	v_cndmask_b32_e64 v107, v107, v109, s[2:3]
	v_mul_f32_e32 v108, 0x37800000, v107
	v_cndmask_b32_e32 v107, v107, v108, vcc
	v_cmp_class_f32_e32 vcc, v106, v143
	s_nop 1
	v_cndmask_b32_e32 v145, v107, v106, vcc
	global_load_dwordx2 v[112:113], v[104:105], off offset:2048 nt
	global_load_dwordx2 v[108:109], v[104:105], off offset:2560 nt
	global_load_dwordx2 v[106:107], v[104:105], off offset:3072 nt
	s_nop 0
	global_load_dwordx2 v[104:105], v[104:105], off offset:3584 nt
	v_div_scale_f32 v146, s[2:3], v145, v145, 1.0
	v_rcp_f32_e32 v147, v146
	s_nop 0
	v_fma_f32 v148, -v146, v147, 1.0
	v_fmac_f32_e32 v147, v148, v147
	v_div_scale_f32 v148, vcc, 1.0, v145, 1.0
	v_mul_f32_e32 v149, v148, v147
	v_fma_f32 v150, -v146, v149, v148
	v_fmac_f32_e32 v149, v150, v147
	v_fma_f32 v146, -v146, v149, v148
	v_div_fmas_f32 v146, v146, v147, v149
	v_div_fixup_f32 v146, v146, v145, 1.0
	v_lshlrev_b32_e32 v150, 16, v134
	v_lshlrev_b32_e32 v134, 16, v135
	v_and_b32_e32 v135, 0xffff0000, v135
	v_pk_mul_f32 v[150:151], v[146:147], v[150:151] op_sel_hi:[0,1]
	v_pk_mul_f32 v[134:135], v[146:147], v[134:135] op_sel_hi:[0,1]
	v_lshl_add_u64 v[148:149], v[102:103], 0, s[10:11]
	v_pk_fma_f32 v[92:93], v[28:29], v[150:151], v[92:93]
	v_pk_fma_f32 v[94:95], v[30:31], v[134:135], v[94:95]
	global_store_dwordx4 v[148:149], v[92:95], off nt
	s_waitcnt vmcnt(27)
	s_nop 0
	v_lshlrev_b32_e32 v92, 16, v132
	v_and_b32_e32 v93, 0xffff0000, v132
	v_pk_mul_f32 v[92:93], v[146:147], v[92:93] op_sel_hi:[0,1]
	v_pk_fma_f32 v[88:89], v[24:25], v[92:93], v[88:89]
	v_lshlrev_b32_e32 v92, 16, v133
	v_and_b32_e32 v93, 0xffff0000, v133
	v_pk_mul_f32 v[92:93], v[146:147], v[92:93] op_sel_hi:[0,1]
	v_pk_fma_f32 v[90:91], v[26:27], v[92:93], v[90:91]
	global_store_dwordx4 v[148:149], v[88:91], off offset:1024 nt
	s_waitcnt vmcnt(27)
	s_nop 0
	v_lshlrev_b32_e32 v88, 16, v130
	v_and_b32_e32 v89, 0xffff0000, v130
	v_pk_mul_f32 v[88:89], v[146:147], v[88:89] op_sel_hi:[0,1]
	v_pk_fma_f32 v[84:85], v[20:21], v[88:89], v[84:85]
	v_lshlrev_b32_e32 v88, 16, v131
	v_and_b32_e32 v89, 0xffff0000, v131
	v_pk_mul_f32 v[88:89], v[146:147], v[88:89] op_sel_hi:[0,1]
	v_pk_fma_f32 v[86:87], v[22:23], v[88:89], v[86:87]
	global_store_dwordx4 v[148:149], v[84:87], off offset:2048 nt
	s_waitcnt vmcnt(27)
	s_nop 0
	v_lshlrev_b32_e32 v84, 16, v128
	v_and_b32_e32 v85, 0xffff0000, v128
	v_pk_mul_f32 v[84:85], v[146:147], v[84:85] op_sel_hi:[0,1]
	v_pk_fma_f32 v[80:81], v[16:17], v[84:85], v[80:81]
	v_lshlrev_b32_e32 v84, 16, v129
	v_and_b32_e32 v85, 0xffff0000, v129
	v_pk_mul_f32 v[84:85], v[146:147], v[84:85] op_sel_hi:[0,1]
	v_pk_fma_f32 v[82:83], v[18:19], v[84:85], v[82:83]
	global_store_dwordx4 v[148:149], v[80:83], off offset:3072 nt
	s_waitcnt vmcnt(23)
	s_nop 0
	v_lshlrev_b32_e32 v80, 16, v126
	v_and_b32_e32 v81, 0xffff0000, v126
	v_pk_mul_f32 v[80:81], v[146:147], v[80:81] op_sel_hi:[0,1]
	v_pk_fma_f32 v[76:77], v[12:13], v[80:81], v[76:77]
	v_lshlrev_b32_e32 v80, 16, v127
	v_and_b32_e32 v81, 0xffff0000, v127
	v_pk_mul_f32 v[80:81], v[146:147], v[80:81] op_sel_hi:[0,1]
	v_pk_fma_f32 v[78:79], v[14:15], v[80:81], v[78:79]
	v_add_co_u32_e32 v80, vcc, s15, v148
	s_nop 1
	v_addc_co_u32_e32 v81, vcc, 0, v149, vcc
	global_store_dwordx4 v[80:81], v[76:79], off nt
	s_waitcnt vmcnt(21)
	ds_bpermute_b32 v78, v136, v144
	s_andn2_b64 vcc, exec, s[8:9]
	v_lshlrev_b32_e32 v76, 16, v124
	v_and_b32_e32 v77, 0xffff0000, v124
	v_pk_mul_f32 v[76:77], v[146:147], v[76:77] op_sel_hi:[0,1]
	v_pk_fma_f32 v[72:73], v[8:9], v[76:77], v[72:73]
	v_lshlrev_b32_e32 v76, 16, v125
	v_and_b32_e32 v77, 0xffff0000, v125
	v_pk_mul_f32 v[76:77], v[146:147], v[76:77] op_sel_hi:[0,1]
	v_pk_fma_f32 v[74:75], v[10:11], v[76:77], v[74:75]
	global_store_dwordx4 v[80:81], v[72:75], off offset:1024 nt
	s_waitcnt lgkmcnt(0)
; __device__ __forceinline__ float bf_lo(unsigned u) { return __uint_as_float(u << 16); }
; __device__ __forceinline__ float bf_hi(unsigned u) { return __uint_as_float(u & 0xffff0000u); }
; __global__ void __launch_bounds__(NTHR, 2) mk_fwd(Args a) {
;     ...
;             for (int r = 0; r < 2; ++r) { const int m = m0 + r * NGW; const bool ok = m < NTOK; const int mm = ok ? m : m0;
;                 part[r] = (lane < 32) ? OSS[(size_t)mm * 32 + lane] : 0.f;
;                 const f32x4* xr = (const f32x4*)(x + (size_t)mm * DMODEL) + lane; const u32x2* ob = (const u32x2*)(OutB + (size_t)mm * DMODEL) + lane;
; #pragma unroll
;                 for (int j = 0; j < 8; ++j) { xv[r][j] = __builtin_nontemporal_load(xr + 64 * j); ov[r][j] = __builtin_nontemporal_load(ob + 64 * j); } }
; #pragma unroll
;             for (int r = 0; r < 2; ++r) { const int m = m0 + r * NGW;
;                 const float rs = 1.0f / sqrtf(wave_sum(part[r]) * (1.0f / DMODEL) + EPS);
;                 if (m < NTOK) { f32x4* orow = (f32x4*)(a.out + (size_t)m * DMODEL) + lane;
; #pragma unroll
;                     for (int j = 0; j < 8; ++j) { const f32x4 xx = xv[r][j], g4 = gv[j]; const u32x2 o = ov[r][j];
;                         f32x4 res; res[0] = xx[0] + bf_lo(o.x) * rs * g4[0]; res[1] = xx[1] + bf_hi(o.x) * rs * g4[1]; res[2] = xx[2] + bf_lo(o.y) * rs * g4[2]; res[3] = xx[3] + bf_hi(o.y) * rs * g4[3];
;                         __builtin_nontemporal_store(res, orow + 64 * j); } } }
	s_nop 0
	v_add_f32_e32 v74, v144, v78
	ds_bpermute_b32 v75, v137, v74
	v_lshlrev_b32_e32 v72, 16, v122
	v_and_b32_e32 v73, 0xffff0000, v122
	v_pk_mul_f32 v[72:73], v[146:147], v[72:73] op_sel_hi:[0,1]
	v_pk_fma_f32 v[68:69], v[4:5], v[72:73], v[68:69]
	s_waitcnt lgkmcnt(0)
	v_add_f32_e32 v74, v74, v75
	ds_bpermute_b32 v75, v138, v74
	v_lshlrev_b32_e32 v72, 16, v123
	v_and_b32_e32 v73, 0xffff0000, v123
	v_pk_mul_f32 v[72:73], v[146:147], v[72:73] op_sel_hi:[0,1]
	v_pk_fma_f32 v[70:71], v[6:7], v[72:73], v[70:71]
	global_store_dwordx4 v[80:81], v[68:71], off offset:2048 nt
	s_waitcnt lgkmcnt(0)
	s_nop 0
	v_add_f32_e32 v70, v74, v75
	ds_bpermute_b32 v71, v139, v70
	v_lshlrev_b32_e32 v68, 16, v118
	v_and_b32_e32 v69, 0xffff0000, v118
	v_pk_mul_f32 v[68:69], v[146:147], v[68:69] op_sel_hi:[0,1]
	v_pk_fma_f32 v[68:69], v[0:1], v[68:69], v[60:61]
	s_waitcnt lgkmcnt(0)
	v_add_f32_e32 v72, v70, v71
	ds_bpermute_b32 v73, v140, v72
	v_lshlrev_b32_e32 v60, 16, v119
	v_and_b32_e32 v61, 0xffff0000, v119
	v_pk_mul_f32 v[60:61], v[146:147], v[60:61] op_sel_hi:[0,1]
	v_pk_fma_f32 v[70:71], v[2:3], v[60:61], v[62:63]
	s_waitcnt lgkmcnt(0)
	v_add_f32_e32 v60, v72, v73
	ds_bpermute_b32 v61, v141, v60
	global_store_dwordx4 v[80:81], v[68:71], off offset:3072 nt
	s_cbranch_vccnz .LBB0_839
	s_waitcnt lgkmcnt(0)
	v_add_f32_e32 v60, v60, v61
	v_fmamk_f32 v60, v60, 0x3a000000, v142
	v_mul_f32_e32 v61, 0x4f800000, v60
	v_cmp_gt_f32_e32 vcc, s17, v60
	s_ashr_i32 s7, s6, 31
	s_nop 0
	v_cndmask_b32_e32 v60, v60, v61, vcc
	v_sqrt_f32_e32 v61, v60
	s_nop 0
	v_add_u32_e32 v62, -1, v61
	v_fma_f32 v68, -v62, v61, v60
	v_add_u32_e32 v63, 1, v61
	v_cmp_ge_f32_e64 s[2:3], 0, v68
	s_nop 1
	v_cndmask_b32_e64 v62, v61, v62, s[2:3]
	v_fma_f32 v61, -v63, v61, v60
	v_cmp_lt_f32_e64 s[2:3], 0, v61
	s_nop 1
	v_cndmask_b32_e64 v61, v62, v63, s[2:3]
	v_mul_f32_e32 v62, 0x37800000, v61
	v_cndmask_b32_e32 v61, v61, v62, vcc
	v_cmp_class_f32_e32 vcc, v60, v143
	s_nop 1
	v_cndmask_b32_e32 v60, v61, v60, vcc
	v_div_scale_f32 v61, s[2:3], v60, v60, 1.0
	v_rcp_f32_e32 v62, v61
	s_lshl_b64 s[2:3], s[6:7], 13
	v_lshl_add_u64 v[70:71], v[102:103], 0, s[2:3]
	v_fma_f32 v63, -v61, v62, 1.0
	v_fmac_f32_e32 v62, v63, v62
	v_div_scale_f32 v63, vcc, 1.0, v60, 1.0
	v_mul_f32_e32 v68, v63, v62
	v_fma_f32 v69, -v61, v68, v63
	v_fmac_f32_e32 v68, v69, v62
	v_fma_f32 v61, -v61, v68, v63
	v_div_fmas_f32 v61, v61, v62, v68
	v_div_fixup_f32 v68, v61, v60, 1.0
	s_waitcnt vmcnt(19)
	v_lshlrev_b32_e32 v60, 16, v120
	v_and_b32_e32 v61, 0xffff0000, v120
	v_lshlrev_b32_e32 v62, 16, v121
	v_and_b32_e32 v63, 0xffff0000, v121
	v_pk_mul_f32 v[60:61], v[68:69], v[60:61] op_sel_hi:[0,1]
	v_pk_mul_f32 v[62:63], v[68:69], v[62:63] op_sel_hi:[0,1]
	v_pk_fma_f32 v[60:61], v[28:29], v[60:61], v[64:65]
	v_pk_fma_f32 v[62:63], v[30:31], v[62:63], v[66:67]
	global_store_dwordx4 v[70:71], v[60:63], off nt
	s_waitcnt vmcnt(19)
	s_nop 0
	v_lshlrev_b32_e32 v60, 16, v116
	v_and_b32_e32 v61, 0xffff0000, v116
	v_pk_mul_f32 v[60:61], v[68:69], v[60:61] op_sel_hi:[0,1]
	v_pk_fma_f32 v[56:57], v[24:25], v[60:61], v[56:57]
	v_lshlrev_b32_e32 v60, 16, v117
	v_and_b32_e32 v61, 0xffff0000, v117
	v_pk_mul_f32 v[60:61], v[68:69], v[60:61] op_sel_hi:[0,1]
	v_pk_fma_f32 v[58:59], v[26:27], v[60:61], v[58:59]
	global_store_dwordx4 v[70:71], v[56:59], off offset:1024 nt
	s_waitcnt vmcnt(19)
	s_nop 0
	v_lshlrev_b32_e32 v56, 16, v114
	v_and_b32_e32 v57, 0xffff0000, v114
	v_pk_mul_f32 v[56:57], v[68:69], v[56:57] op_sel_hi:[0,1]
	v_pk_fma_f32 v[52:53], v[20:21], v[56:57], v[52:53]
	v_lshlrev_b32_e32 v56, 16, v115
	v_and_b32_e32 v57, 0xffff0000, v115
	v_pk_mul_f32 v[56:57], v[68:69], v[56:57] op_sel_hi:[0,1]
	v_pk_fma_f32 v[54:55], v[22:23], v[56:57], v[54:55]
	global_store_dwordx4 v[70:71], v[52:55], off offset:2048 nt
	s_waitcnt vmcnt(19)
	s_nop 0
	v_lshlrev_b32_e32 v52, 16, v110
	v_and_b32_e32 v53, 0xffff0000, v110
	v_pk_mul_f32 v[52:53], v[68:69], v[52:53] op_sel_hi:[0,1]
	v_pk_fma_f32 v[44:45], v[16:17], v[52:53], v[44:45]
	v_lshlrev_b32_e32 v52, 16, v111
	v_and_b32_e32 v53, 0xffff0000, v111
	v_pk_mul_f32 v[52:53], v[68:69], v[52:53] op_sel_hi:[0,1]
	v_pk_fma_f32 v[46:47], v[18:19], v[52:53], v[46:47]
	global_store_dwordx4 v[70:71], v[44:47], off offset:3072 nt
	s_waitcnt vmcnt(15)
	s_nop 0
	v_lshlrev_b32_e32 v44, 16, v112
	v_and_b32_e32 v45, 0xffff0000, v112
	v_pk_mul_f32 v[44:45], v[68:69], v[44:45] op_sel_hi:[0,1]
	v_lshlrev_b32_e32 v46, 16, v113
	v_and_b32_e32 v47, 0xffff0000, v113
	v_pk_fma_f32 v[44:45], v[12:13], v[44:45], v[48:49]
	v_pk_mul_f32 v[46:47], v[68:69], v[46:47] op_sel_hi:[0,1]
	v_add_co_u32_e32 v48, vcc, s15, v70
	v_pk_fma_f32 v[46:47], v[14:15], v[46:47], v[50:51]
	s_nop 0
	v_addc_co_u32_e32 v49, vcc, 0, v71, vcc
	global_store_dwordx4 v[48:49], v[44:47], off nt
	s_waitcnt vmcnt(15)
	s_nop 0
	v_lshlrev_b32_e32 v44, 16, v108
	v_and_b32_e32 v45, 0xffff0000, v108
	v_pk_mul_f32 v[44:45], v[68:69], v[44:45] op_sel_hi:[0,1]
	v_pk_fma_f32 v[40:41], v[8:9], v[44:45], v[40:41]
	v_lshlrev_b32_e32 v44, 16, v109
	v_and_b32_e32 v45, 0xffff0000, v109
	v_pk_mul_f32 v[44:45], v[68:69], v[44:45] op_sel_hi:[0,1]
	v_pk_fma_f32 v[42:43], v[10:11], v[44:45], v[42:43]
	global_store_dwordx4 v[48:49], v[40:43], off offset:1024 nt
	s_waitcnt vmcnt(15)
	s_nop 0
	v_lshlrev_b32_e32 v40, 16, v106
	v_and_b32_e32 v41, 0xffff0000, v106
	v_pk_mul_f32 v[40:41], v[68:69], v[40:41] op_sel_hi:[0,1]
	v_pk_fma_f32 v[36:37], v[4:5], v[40:41], v[36:37]
	v_lshlrev_b32_e32 v40, 16, v107
	v_and_b32_e32 v41, 0xffff0000, v107
	v_pk_mul_f32 v[40:41], v[68:69], v[40:41] op_sel_hi:[0,1]
	v_pk_fma_f32 v[38:39], v[6:7], v[40:41], v[38:39]
	global_store_dwordx4 v[48:49], v[36:39], off offset:2048 nt
	s_waitcnt vmcnt(15)
	s_nop 0
	v_lshlrev_b32_e32 v36, 16, v104
	v_and_b32_e32 v37, 0xffff0000, v104
	v_pk_mul_f32 v[36:37], v[68:69], v[36:37] op_sel_hi:[0,1]
	v_pk_fma_f32 v[32:33], v[0:1], v[36:37], v[32:33]
	v_lshlrev_b32_e32 v36, 16, v105
	v_and_b32_e32 v37, 0xffff0000, v105
	v_pk_mul_f32 v[36:37], v[68:69], v[36:37] op_sel_hi:[0,1]
	v_pk_fma_f32 v[34:35], v[2:3], v[36:37], v[34:35]
	global_store_dwordx4 v[48:49], v[32:35], off offset:3072 nt
	s_branch .LBB0_839
